# v91 + redundant s_waitcnt lgkmcnt(0) after each pre-MFMA barrier removed (MFMA block now starts directly after the barrier)
# speedup vs baseline: 1.0060x; 1.0005x over previous
; #define PG8_STAGE(bufoff, gbase, voff) do { _Pragma("unroll") for (int _i = 0; _i < 2; ++_i) \
;         __builtin_amdgcn_global_load_lds((const unsigned*)((const char*)(gbase) + (voff)[_i]), (PG8_LAS unsigned*)(lds + (bufoff) + ldsw + _i * 8192), 16, 0, 0); } while (0)
; #define PG8_LDA(dst, b, h) do { _Pragma("unroll") for (int m = 0; m < 4; ++m) _Pragma("unroll") for (int k = 0; k < 2; ++k) dst[m][k] = *(const PG8_LAS bf16x8*)(lds + PG8_SA(b, h) + aoff + m * 2048 + k * 1024); } while (0)
; #define PG8_LDB(dst, b, h) do { _Pragma("unroll") for (int n = 0; n < 2; ++n) _Pragma("unroll") for (int k = 0; k < 2; ++k) dst[n][k] = *(const PG8_LAS bf16x8*)(lds + PG8_SB(b, h) + boff + n * 2048 + k * 1024); } while (0)
; #define PG8_MMA(ai, bj, At, Bt) do { __builtin_amdgcn_s_setprio(1); _Pragma("unroll") for (int m = 0; m < 4; ++m) _Pragma("unroll") for (int n = 0; n < 2; ++n) _Pragma("unroll") for (int k = 0; k < 2; ++k) \
;         acc[ai][bj][m][n] = mma16<Epi::I8>(Bt[n][k], At[m][k], acc[ai][bj][m][n]); __builtin_amdgcn_s_setprio(0); } while (0)
; #define PG8_WAIT_V(n) asm volatile("s_waitcnt vmcnt(" #n ")" ::: "memory")
; #define PG8_WAIT_L(n) asm volatile("s_waitcnt lgkmcnt(" #n ")" ::: "memory")
; #define PG8_BAR __builtin_amdgcn_s_barrier()
; template <class Epi, class Sched, bool ALIGN_EPI = false, bool SP2 = false>
; __device__ __forceinline__ void gemm_phase(PG8_LAS unsigned char* lds, const Gemm g, const Sched& S, const Epi& E) {
;     ...
;             const bool last = (t == nt - 2);
;             const char* a1 = cA + (size_t)(t + 1) * kstep;
;             const char* a2 = last ? nA : cA + (size_t)(t + 2) * kstep; const char* b2 = last ? nB : cB + (size_t)(t + 2) * kstep;
;             const char* a3 = a2 + kstep; const char* b3 = b2 + kstep;
;             if (last && has_next) S.a_ready(nxt);
;             if constexpr (SP2) {
;             PG8_LDB(B0, 0, 0); PG8_LDB(B1, 0, 1); PG8_SCHED; PG8_LDA(At, 0, 0); PG8_STAGE(PG8_SA(1, 1), a1 + hstep, voffA);
;             PG8_WAIT_V(8); PG8_WAIT_L(0); PG8_BAR; PG8_MMA(0, 0, At, B0); PG8_MMA(0, 1, At, B1); PG8_BAR; PG8_SCHED;
;             PG8_LDA(At, 0, 1); PG8_STAGE(PG8_SB(0, 0), b2, voffB); PG8_STAGE(PG8_SB(0, 1), b2 + hstep, voffB); PG8_STAGE(PG8_SA(0, 0), a2, voffA);
;             PG8_WAIT_V(8); PG8_WAIT_L(0); PG8_BAR; PG8_MMA(1, 0, At, B0); PG8_MMA(1, 1, At, B1); PG8_BAR; PG8_SCHED;
.Lpeel80:
	s_add_u32 s8, s0, 0x100
	s_addc_u32 s9, s1, 0
	s_add_i32 vcc_hi, 0, 0x10000
	s_cmp_eq_u32 vcc_lo, 12
	s_cselect_b32 s13, s66, s9
	s_cselect_b32 s12, s67, s8
	s_cselect_b32 s7, s82, s97
	s_cselect_b32 s6, s83, s96
	s_add_i32 s4, 0, 0x14000
	v_add_u32_e32 v38, vcc_hi, v242
	v_add_u32_e32 v158, s4, v242
	ds_read_b128 v[18:21], v38
	ds_read_b128 v[22:25], v38 offset:1024
	ds_read_b128 v[34:37], v38 offset:2048
	ds_read_b128 v[38:41], v38 offset:3072
	ds_read_b128 v[130:133], v158
	ds_read_b128 v[134:137], v158 offset:1024
	ds_read_b128 v[154:157], v158 offset:2048
	ds_read_b128 v[158:161], v158 offset:3072
	s_add_i32 m0, s11, 0xc000
	ds_read_b128 v[162:165], v243
	ds_read_b128 v[166:169], v243 offset:1024
	ds_read_b128 v[170:173], v243 offset:2048
	ds_read_b128 v[174:177], v243 offset:3072
	ds_read_b128 v[178:181], v243 offset:4096
	ds_read_b128 v[182:185], v243 offset:5120
	ds_read_b128 v[186:189], v243 offset:6144
	ds_read_b128 v[190:193], v243 offset:7168
	global_load_lds_dwordx4 v216, s[0:1]
	s_add_i32 m0, s11, 0xe000
	s_nop 0
	global_load_lds_dwordx4 v218, s[0:1]
	s_waitcnt vmcnt(8)
	s_waitcnt lgkmcnt(0)
	s_barrier
	v_mfma_i32_16x16x64_i8 v[150:153], v[18:21], v[162:165], 0
	v_mfma_i32_16x16x64_i8 v[150:153], v[22:25], v[166:169], v[150:153]
	v_mfma_i32_16x16x64_i8 v[146:149], v[38:41], v[166:169], 0
	v_mfma_i32_16x16x64_i8 v[146:149], v[34:37], v[162:165], v[146:149]
	v_mfma_i32_16x16x64_i8 v[110:113], v[34:37], v[170:173], 0
	v_mfma_i32_16x16x64_i8 v[110:113], v[38:41], v[174:177], v[110:113]
	v_mfma_i32_16x16x64_i8 v[118:121], v[22:25], v[174:177], 0
	v_mfma_i32_16x16x64_i8 v[118:121], v[18:21], v[170:173], v[118:121]
	v_mfma_i32_16x16x64_i8 v[54:57], v[18:21], v[178:181], 0
	v_mfma_i32_16x16x64_i8 v[54:57], v[22:25], v[182:185], v[54:57]
	v_mfma_i32_16x16x64_i8 v[30:33], v[38:41], v[182:185], 0
	v_mfma_i32_16x16x64_i8 v[30:33], v[34:37], v[178:181], v[30:33]
	v_mfma_i32_16x16x64_i8 v[58:61], v[34:37], v[186:189], 0
	v_mfma_i32_16x16x64_i8 v[58:61], v[38:41], v[190:193], v[58:61]
	v_mfma_i32_16x16x64_i8 v[94:97], v[22:25], v[190:193], 0
	v_mfma_i32_16x16x64_i8 v[94:97], v[18:21], v[186:189], v[94:97]
	v_mfma_i32_16x16x64_i8 v[62:65], v[154:157], v[186:189], 0
	v_mfma_i32_16x16x64_i8 v[62:65], v[158:161], v[190:193], v[62:65]
	v_mfma_i32_16x16x64_i8 v[138:141], v[158:161], v[166:169], 0
	v_mfma_i32_16x16x64_i8 v[138:141], v[154:157], v[162:165], v[138:141]
	v_mfma_i32_16x16x64_i8 v[142:145], v[130:133], v[162:165], 0
	v_mfma_i32_16x16x64_i8 v[142:145], v[134:137], v[166:169], v[142:145]
	v_mfma_i32_16x16x64_i8 v[102:105], v[134:137], v[174:177], 0
	v_mfma_i32_16x16x64_i8 v[102:105], v[130:133], v[170:173], v[102:105]
	v_mfma_i32_16x16x64_i8 v[98:101], v[154:157], v[170:173], 0
	v_mfma_i32_16x16x64_i8 v[98:101], v[158:161], v[174:177], v[98:101]
	v_mfma_i32_16x16x64_i8 v[26:29], v[158:161], v[182:185], 0
	v_mfma_i32_16x16x64_i8 v[26:29], v[154:157], v[178:181], v[26:29]
	v_mfma_i32_16x16x64_i8 v[42:45], v[130:133], v[178:181], 0
	v_mfma_i32_16x16x64_i8 v[42:45], v[134:137], v[182:185], v[42:45]
	v_mfma_i32_16x16x64_i8 v[78:81], v[134:137], v[190:193], 0
	v_mfma_i32_16x16x64_i8 v[78:81], v[130:133], v[186:189], v[78:81]
	s_barrier
	s_add_i32 s0, vcc_hi, s69
	v_lshl_add_u64 v[198:199], s[6:7], 0, v[0:1]
	s_mov_b32 m0, s0
	ds_read_b128 v[162:165], v243 offset:16384
	ds_read_b128 v[166:169], v243 offset:17408
	ds_read_b128 v[170:173], v243 offset:18432
	ds_read_b128 v[174:177], v243 offset:19456
	ds_read_b128 v[178:181], v243 offset:20480
	ds_read_b128 v[182:185], v243 offset:21504
	ds_read_b128 v[186:189], v243 offset:22528
	ds_read_b128 v[190:193], v243 offset:23552
	global_load_lds_dwordx4 v[198:199], off
	s_add_i32 m0, s0, 0x2000
	s_add_u32 s0, s6, 0x40000
	v_lshl_add_u64 v[200:201], s[6:7], 0, v[214:215]
	s_addc_u32 s1, s7, 0
	s_add_i32 s4, s4, s69
	global_load_lds_dwordx4 v[200:201], off
	s_mov_b32 m0, s4
	v_lshl_add_u64 v[206:207], s[12:13], 0, v[210:211]
	global_load_lds_dwordx4 v0, s[0:1]
	s_add_i32 m0, s4, 0x2000
	v_lshl_add_u64 v[220:221], s[12:13], 0, v[212:213]
	global_load_lds_dwordx4 v214, s[0:1]
	s_mov_b32 m0, s11
	s_nop 0
	global_load_lds_dwordx4 v[206:207], off
	s_mov_b32 m0, s71
	s_nop 0
	global_load_lds_dwordx4 v[220:221], off
	s_waitcnt vmcnt(8)
	s_waitcnt lgkmcnt(0)
	s_barrier
	v_mfma_i32_16x16x64_i8 v[106:109], v[18:21], v[162:165], 0
	v_mfma_i32_16x16x64_i8 v[106:109], v[22:25], v[166:169], v[106:109]
	v_mfma_i32_16x16x64_i8 v[46:49], v[34:37], v[162:165], 0
	v_mfma_i32_16x16x64_i8 v[46:49], v[38:41], v[166:169], v[46:49]
	v_mfma_i32_16x16x64_i8 v[6:9], v[34:37], v[170:173], 0
	v_mfma_i32_16x16x64_i8 v[6:9], v[38:41], v[174:177], v[6:9]
	v_mfma_i32_16x16x64_i8 v[14:17], v[18:21], v[170:173], 0
	v_mfma_i32_16x16x64_i8 v[14:17], v[22:25], v[174:177], v[14:17]
	v_mfma_i32_16x16x64_i8 v[90:93], v[18:21], v[178:181], 0
	v_mfma_i32_16x16x64_i8 v[90:93], v[22:25], v[182:185], v[90:93]
	v_mfma_i32_16x16x64_i8 v[86:89], v[34:37], v[178:181], 0
	v_mfma_i32_16x16x64_i8 v[86:89], v[38:41], v[182:185], v[86:89]
	v_mfma_i32_16x16x64_i8 v[18:21], v[18:21], v[186:189], 0
	v_mfma_i32_16x16x64_i8 v[18:21], v[22:25], v[190:193], v[18:21]
	v_mfma_i32_16x16x64_i8 v[22:25], v[34:37], v[186:189], 0
	v_mfma_i32_16x16x64_i8 v[22:25], v[38:41], v[190:193], v[22:25]
	v_mfma_i32_16x16x64_i8 v[38:41], v[154:157], v[162:165], 0
	v_mfma_i32_16x16x64_i8 v[38:41], v[158:161], v[166:169], v[38:41]
	v_mfma_i32_16x16x64_i8 v[2:5], v[154:157], v[170:173], 0
	v_mfma_i32_16x16x64_i8 v[2:5], v[158:161], v[174:177], v[2:5]
	v_mfma_i32_16x16x64_i8 v[10:13], v[130:133], v[170:173], 0
	v_mfma_i32_16x16x64_i8 v[10:13], v[134:137], v[174:177], v[10:13]
	v_mfma_i32_16x16x64_i8 v[50:53], v[130:133], v[178:181], 0
	v_mfma_i32_16x16x64_i8 v[82:85], v[134:137], v[182:185], v[50:53]
	v_mfma_i32_16x16x64_i8 v[34:37], v[130:133], v[162:165], 0
	v_mfma_i32_16x16x64_i8 v[34:37], v[134:137], v[166:169], v[34:37]
	v_mfma_i32_16x16x64_i8 v[50:53], v[154:157], v[178:181], 0
	v_mfma_i32_16x16x64_i8 v[74:77], v[158:161], v[182:185], v[50:53]
	v_mfma_i32_16x16x64_i8 v[50:53], v[130:133], v[186:189], 0
	v_mfma_i32_16x16x64_i8 v[122:125], v[134:137], v[190:193], v[50:53]
	v_mfma_i32_16x16x64_i8 v[50:53], v[154:157], v[186:189], 0
	v_mfma_i32_16x16x64_i8 v[70:73], v[158:161], v[190:193], v[50:53]
	s_barrier
; #define PG8_STAGE(bufoff, gbase, voff) do { _Pragma("unroll") for (int _i = 0; _i < 2; ++_i) \
;         __builtin_amdgcn_global_load_lds((const unsigned*)((const char*)(gbase) + (voff)[_i]), (PG8_LAS unsigned*)(lds + (bufoff) + ldsw + _i * 8192), 16, 0, 0); } while (0)
; #define PG8_LDA(dst, b, h) do { _Pragma("unroll") for (int m = 0; m < 4; ++m) _Pragma("unroll") for (int k = 0; k < 2; ++k) dst[m][k] = *(const PG8_LAS bf16x8*)(lds + PG8_SA(b, h) + aoff + m * 2048 + k * 1024); } while (0)
; #define PG8_LDB(dst, b, h) do { _Pragma("unroll") for (int n = 0; n < 2; ++n) _Pragma("unroll") for (int k = 0; k < 2; ++k) dst[n][k] = *(const PG8_LAS bf16x8*)(lds + PG8_SB(b, h) + boff + n * 2048 + k * 1024); } while (0)
; #define PG8_MMA(ai, bj, At, Bt) do { __builtin_amdgcn_s_setprio(1); _Pragma("unroll") for (int m = 0; m < 4; ++m) _Pragma("unroll") for (int n = 0; n < 2; ++n) _Pragma("unroll") for (int k = 0; k < 2; ++k) \
;         acc[ai][bj][m][n] = mma16<Epi::I8>(Bt[n][k], At[m][k], acc[ai][bj][m][n]); __builtin_amdgcn_s_setprio(0); } while (0)
; #define PG8_WAIT_V(n) asm volatile("s_waitcnt vmcnt(" #n ")" ::: "memory")
; #define PG8_WAIT_L(n) asm volatile("s_waitcnt lgkmcnt(" #n ")" ::: "memory")
; #define PG8_BAR __builtin_amdgcn_s_barrier()
; #define PG8_SCHED __builtin_amdgcn_sched_barrier(0)
; template <class Epi, class Sched, bool ALIGN_EPI = false, bool SP2 = false>
; __device__ __forceinline__ void gemm_phase(PG8_LAS unsigned char* lds, const Gemm g, const Sched& S, const Epi& E) {
;     ...
;             PG8_LDB(B0, 1, 0); PG8_LDB(B1, 1, 1); PG8_SCHED; PG8_LDA(At, 1, 0); PG8_STAGE(PG8_SA(0, 1), a2 + hstep, voffA);
;             PG8_WAIT_V(8); PG8_WAIT_L(0); PG8_BAR; PG8_MMA(0, 0, At, B0); PG8_MMA(0, 1, At, B1); PG8_BAR; PG8_SCHED;
;             PG8_LDA(At, 1, 1); PG8_STAGE(PG8_SB(1, 0), b3, voffB); PG8_STAGE(PG8_SB(1, 1), b3 + hstep, voffB); PG8_STAGE(PG8_SA(1, 0), a3, voffA);
;             PG8_WAIT_V(8); PG8_WAIT_L(0); PG8_BAR; PG8_MMA(1, 0, At, B0); PG8_MMA(1, 1, At, B1); PG8_BAR; PG8_SCHED;
	s_add_i32 s4, 0, 0x18000
	v_add_u32_e32 v126, s4, v242
	s_add_i32 s5, 0, 0x1c000
	ds_read_b128 v[50:53], v126
	ds_read_b128 v[66:69], v126 offset:1024
	ds_read_b128 v[114:117], v126 offset:2048
	ds_read_b128 v[130:133], v126 offset:3072
	v_add_u32_e32 v126, s5, v242
	ds_read_b128 v[134:137], v126
	ds_read_b128 v[154:157], v126 offset:1024
	ds_read_b128 v[158:161], v126 offset:2048
	ds_read_b128 v[162:165], v126 offset:3072
	s_add_u32 s0, s12, 0x40000
	s_addc_u32 s1, s13, 0
	s_mov_b32 m0, s80
	ds_read_b128 v[126:129], v243 offset:32768
	ds_read_b128 v[166:169], v243 offset:33792
	ds_read_b128 v[170:173], v243 offset:34816
	ds_read_b128 v[174:177], v243 offset:35840
	ds_read_b128 v[178:181], v243 offset:36864
	ds_read_b128 v[182:185], v243 offset:37888
	ds_read_b128 v[186:189], v243 offset:38912
	ds_read_b128 v[190:193], v243 offset:39936
	global_load_lds_dwordx4 v210, s[0:1]
	s_mov_b32 m0, s81
	s_nop 0
	global_load_lds_dwordx4 v212, s[0:1]
	s_waitcnt vmcnt(8)
	s_waitcnt lgkmcnt(0)
	s_barrier
	v_mfma_i32_16x16x64_i8 v[150:153], v[50:53], v[126:129], v[150:153]
	v_mfma_i32_16x16x64_i8 v[150:153], v[66:69], v[166:169], v[150:153]
	v_mfma_i32_16x16x64_i8 v[146:149], v[114:117], v[126:129], v[146:149]
	v_mfma_i32_16x16x64_i8 v[146:149], v[130:133], v[166:169], v[146:149]
	v_mfma_i32_16x16x64_i8 v[110:113], v[114:117], v[170:173], v[110:113]
	v_mfma_i32_16x16x64_i8 v[110:113], v[130:133], v[174:177], v[110:113]
	v_mfma_i32_16x16x64_i8 v[118:121], v[50:53], v[170:173], v[118:121]
	v_mfma_i32_16x16x64_i8 v[118:121], v[66:69], v[174:177], v[118:121]
	v_mfma_i32_16x16x64_i8 v[54:57], v[50:53], v[178:181], v[54:57]
	v_mfma_i32_16x16x64_i8 v[54:57], v[66:69], v[182:185], v[54:57]
	v_mfma_i32_16x16x64_i8 v[30:33], v[114:117], v[178:181], v[30:33]
	v_mfma_i32_16x16x64_i8 v[30:33], v[130:133], v[182:185], v[30:33]
	v_mfma_i32_16x16x64_i8 v[58:61], v[114:117], v[186:189], v[58:61]
	v_mfma_i32_16x16x64_i8 v[58:61], v[130:133], v[190:193], v[58:61]
	v_mfma_i32_16x16x64_i8 v[94:97], v[50:53], v[186:189], v[94:97]
	v_mfma_i32_16x16x64_i8 v[94:97], v[66:69], v[190:193], v[94:97]
	v_mfma_i32_16x16x64_i8 v[142:145], v[134:137], v[126:129], v[142:145]
	v_mfma_i32_16x16x64_i8 v[142:145], v[154:157], v[166:169], v[142:145]
	v_mfma_i32_16x16x64_i8 v[126:129], v[158:161], v[126:129], v[138:141]
	v_mfma_i32_16x16x64_i8 v[138:141], v[162:165], v[166:169], v[126:129]
	v_mfma_i32_16x16x64_i8 v[98:101], v[158:161], v[170:173], v[98:101]
	v_mfma_i32_16x16x64_i8 v[98:101], v[162:165], v[174:177], v[98:101]
	v_mfma_i32_16x16x64_i8 v[102:105], v[134:137], v[170:173], v[102:105]
	v_mfma_i32_16x16x64_i8 v[102:105], v[154:157], v[174:177], v[102:105]
	v_mfma_i32_16x16x64_i8 v[42:45], v[134:137], v[178:181], v[42:45]
	v_mfma_i32_16x16x64_i8 v[42:45], v[154:157], v[182:185], v[42:45]
	v_mfma_i32_16x16x64_i8 v[26:29], v[158:161], v[178:181], v[26:29]
	v_mfma_i32_16x16x64_i8 v[26:29], v[162:165], v[182:185], v[26:29]
	v_mfma_i32_16x16x64_i8 v[62:65], v[158:161], v[186:189], v[62:65]
	v_mfma_i32_16x16x64_i8 v[62:65], v[162:165], v[190:193], v[62:65]
	v_mfma_i32_16x16x64_i8 v[78:81], v[134:137], v[186:189], v[78:81]
	v_mfma_i32_16x16x64_i8 v[78:81], v[154:157], v[190:193], v[78:81]
	s_barrier
	s_add_i32 s0, s4, s69
	v_lshl_add_u64 v[126:127], v[198:199], 0, s[92:93]
	s_mov_b32 m0, s0
	ds_read_b128 v[166:169], v243 offset:49152
	ds_read_b128 v[170:173], v243 offset:50176
	ds_read_b128 v[174:177], v243 offset:51200
	ds_read_b128 v[178:181], v243 offset:52224
	ds_read_b128 v[182:185], v243 offset:53248
	ds_read_b128 v[186:189], v243 offset:54272
	ds_read_b128 v[190:193], v243 offset:55296
	ds_read_b128 v[194:197], v243 offset:56320
	global_load_lds_dwordx4 v[126:127], off
	s_add_i32 m0, s0, 0x2000
	s_add_u32 s0, s6, 0x40080
	v_lshl_add_u64 v[126:127], v[200:201], 0, s[92:93]
	s_addc_u32 s1, s7, 0
	s_add_i32 s4, s5, s69
	global_load_lds_dwordx4 v[126:127], off
	s_mov_b32 m0, s4
	s_nop 0
	global_load_lds_dwordx4 v0, s[0:1]
	s_add_i32 m0, s4, 0x2000
	s_nop 0
	global_load_lds_dwordx4 v214, s[0:1]
	v_lshl_add_u64 v[126:127], v[206:207], 0, s[92:93]
	s_mov_b32 m0, s84
	s_nop 0
	global_load_lds_dwordx4 v[126:127], off
	v_lshl_add_u64 v[126:127], v[220:221], 0, s[92:93]
	s_mov_b32 m0, s85
	s_nop 0
	global_load_lds_dwordx4 v[126:127], off
	s_waitcnt vmcnt(8)
	s_waitcnt lgkmcnt(0)
	s_barrier
	v_mfma_i32_16x16x64_i8 v[18:21], v[50:53], v[190:193], v[18:21]
	v_mfma_i32_16x16x64_i8 v[126:129], v[66:69], v[194:197], v[18:21]
	v_mfma_i32_16x16x64_i8 v[106:109], v[50:53], v[166:169], v[106:109]
	v_mfma_i32_16x16x64_i8 v[106:109], v[66:69], v[170:173], v[106:109]
	v_mfma_i32_16x16x64_i8 v[46:49], v[114:117], v[166:169], v[46:49]
	v_mfma_i32_16x16x64_i8 v[46:49], v[130:133], v[170:173], v[46:49]
	v_mfma_i32_16x16x64_i8 v[6:9], v[114:117], v[174:177], v[6:9]
	v_mfma_i32_16x16x64_i8 v[6:9], v[130:133], v[178:181], v[6:9]
	v_mfma_i32_16x16x64_i8 v[14:17], v[50:53], v[174:177], v[14:17]
	v_mfma_i32_16x16x64_i8 v[14:17], v[66:69], v[178:181], v[14:17]
	v_mfma_i32_16x16x64_i8 v[90:93], v[50:53], v[182:185], v[90:93]
	v_mfma_i32_16x16x64_i8 v[90:93], v[66:69], v[186:189], v[90:93]
	v_mfma_i32_16x16x64_i8 v[86:89], v[114:117], v[182:185], v[86:89]
	v_mfma_i32_16x16x64_i8 v[86:89], v[130:133], v[186:189], v[86:89]
	v_mfma_i32_16x16x64_i8 v[18:21], v[114:117], v[190:193], v[22:25]
	v_mfma_i32_16x16x64_i8 v[66:69], v[130:133], v[194:197], v[18:21]
	v_mfma_i32_16x16x64_i8 v[18:21], v[134:137], v[166:169], v[34:37]
	v_mfma_i32_16x16x64_i8 v[114:117], v[154:157], v[170:173], v[18:21]
	v_mfma_i32_16x16x64_i8 v[10:13], v[134:137], v[174:177], v[10:13]
	v_mfma_i32_16x16x64_i8 v[10:13], v[154:157], v[178:181], v[10:13]
	v_mfma_i32_16x16x64_i8 v[2:5], v[158:161], v[174:177], v[2:5]
	v_mfma_i32_16x16x64_i8 v[2:5], v[162:165], v[178:181], v[2:5]
	v_mfma_i32_16x16x64_i8 v[18:21], v[158:161], v[166:169], v[38:41]
	v_mfma_i32_16x16x64_i8 v[50:53], v[162:165], v[170:173], v[18:21]
	v_mfma_i32_16x16x64_i8 v[18:21], v[134:137], v[182:185], v[82:85]
	v_mfma_i32_16x16x64_i8 v[82:85], v[154:157], v[186:189], v[18:21]
	v_mfma_i32_16x16x64_i8 v[18:21], v[158:161], v[182:185], v[74:77]
	v_mfma_i32_16x16x64_i8 v[74:77], v[162:165], v[186:189], v[18:21]
	v_mfma_i32_16x16x64_i8 v[18:21], v[134:137], v[190:193], v[122:125]
	v_mfma_i32_16x16x64_i8 v[122:125], v[154:157], v[194:197], v[18:21]
	v_mfma_i32_16x16x64_i8 v[18:21], v[158:161], v[190:193], v[70:73]
	v_mfma_i32_16x16x64_i8 v[70:73], v[162:165], v[194:197], v[18:21]
	s_barrier
	s_add_i32 vcc_lo, vcc_lo, 2
	s_add_u32 s96, s96, 0x100
	s_addc_u32 s97, s97, 0
	s_cmp_gt_u32 vcc_lo, 13
	s_mov_b64 s[0:1], s[8:9]
	s_cbranch_scc0 .LBB0_80
	s_branch .Lpeelx80
; #define PG8_STAGE(bufoff, gbase, voff) do { _Pragma("unroll") for (int _i = 0; _i < 2; ++_i) \
;         __builtin_amdgcn_global_load_lds((const unsigned*)((const char*)(gbase) + (voff)[_i]), (PG8_LAS unsigned*)(lds + (bufoff) + ldsw + _i * 8192), 16, 0, 0); } while (0)
; #define PG8_LDA(dst, b, h) do { _Pragma("unroll") for (int m = 0; m < 4; ++m) _Pragma("unroll") for (int k = 0; k < 2; ++k) dst[m][k] = *(const PG8_LAS bf16x8*)(lds + PG8_SA(b, h) + aoff + m * 2048 + k * 1024); } while (0)
; #define PG8_LDB(dst, b, h) do { _Pragma("unroll") for (int n = 0; n < 2; ++n) _Pragma("unroll") for (int k = 0; k < 2; ++k) dst[n][k] = *(const PG8_LAS bf16x8*)(lds + PG8_SB(b, h) + boff + n * 2048 + k * 1024); } while (0)
; #define PG8_MMA(ai, bj, At, Bt) do { __builtin_amdgcn_s_setprio(1); _Pragma("unroll") for (int m = 0; m < 4; ++m) _Pragma("unroll") for (int n = 0; n < 2; ++n) _Pragma("unroll") for (int k = 0; k < 2; ++k) \
;         acc[ai][bj][m][n] = mma16<Epi::I8>(Bt[n][k], At[m][k], acc[ai][bj][m][n]); __builtin_amdgcn_s_setprio(0); } while (0)
; #define PG8_WAIT_V(n) asm volatile("s_waitcnt vmcnt(" #n ")" ::: "memory")
; #define PG8_WAIT_L(n) asm volatile("s_waitcnt lgkmcnt(" #n ")" ::: "memory")
; #define PG8_BAR __builtin_amdgcn_s_barrier()
; template <class Epi, class Sched, bool ALIGN_EPI = false, bool SP2 = false>
; __device__ __forceinline__ void gemm_phase(PG8_LAS unsigned char* lds, const Gemm g, const Sched& S, const Epi& E) {
;     ...
;             const bool last = (t == nt - 2);
;             const char* a1 = cA + (size_t)(t + 1) * kstep;
;             const char* a2 = last ? nA : cA + (size_t)(t + 2) * kstep; const char* b2 = last ? nB : cB + (size_t)(t + 2) * kstep;
;             const char* a3 = a2 + kstep; const char* b3 = b2 + kstep;
;             if (last && has_next) S.a_ready(nxt);
;             if constexpr (SP2) {
;             PG8_LDB(B0, 0, 0); PG8_LDB(B1, 0, 1); PG8_SCHED; PG8_LDA(At, 0, 0); PG8_STAGE(PG8_SA(1, 1), a1 + hstep, voffA);
;             PG8_WAIT_V(8); PG8_WAIT_L(0); PG8_BAR; PG8_MMA(0, 0, At, B0); PG8_MMA(0, 1, At, B1); PG8_BAR; PG8_SCHED;
;             PG8_LDA(At, 0, 1); PG8_STAGE(PG8_SB(0, 0), b2, voffB); PG8_STAGE(PG8_SB(0, 1), b2 + hstep, voffB); PG8_STAGE(PG8_SA(0, 0), a2, voffA);
;             PG8_WAIT_V(8); PG8_WAIT_L(0); PG8_BAR; PG8_MMA(1, 0, At, B0); PG8_MMA(1, 1, At, B1); PG8_BAR; PG8_SCHED;
.LBB0_80:
	s_add_u32 s8, s0, 0x100
	s_addc_u32 s9, s1, 0
	s_add_i32 vcc_hi, 0, 0x10000
	s_cmp_eq_u32 vcc_lo, 12
	s_cselect_b32 s13, s66, s9
	s_cselect_b32 s12, s67, s8
	s_cselect_b32 s7, s82, s97
	s_cselect_b32 s6, s83, s96
	s_add_i32 s4, 0, 0x14000
	v_add_u32_e32 v38, vcc_hi, v242
	v_add_u32_e32 v158, s4, v242
	ds_read_b128 v[18:21], v38
	ds_read_b128 v[22:25], v38 offset:1024
	ds_read_b128 v[34:37], v38 offset:2048
	ds_read_b128 v[38:41], v38 offset:3072
	ds_read_b128 v[130:133], v158
	ds_read_b128 v[134:137], v158 offset:1024
	ds_read_b128 v[154:157], v158 offset:2048
	ds_read_b128 v[158:161], v158 offset:3072
	s_add_i32 m0, s11, 0xc000
	ds_read_b128 v[162:165], v243
	ds_read_b128 v[166:169], v243 offset:1024
	ds_read_b128 v[170:173], v243 offset:2048
	ds_read_b128 v[174:177], v243 offset:3072
	ds_read_b128 v[178:181], v243 offset:4096
	ds_read_b128 v[182:185], v243 offset:5120
	ds_read_b128 v[186:189], v243 offset:6144
	ds_read_b128 v[190:193], v243 offset:7168
	global_load_lds_dwordx4 v216, s[0:1]
	s_add_i32 m0, s11, 0xe000
	s_nop 0
	global_load_lds_dwordx4 v218, s[0:1]
	s_waitcnt vmcnt(8)
	s_waitcnt lgkmcnt(0)
	s_barrier
	v_mfma_i32_16x16x64_i8 v[150:153], v[18:21], v[162:165], v[150:153]
	v_mfma_i32_16x16x64_i8 v[150:153], v[22:25], v[166:169], v[150:153]
	v_mfma_i32_16x16x64_i8 v[146:149], v[38:41], v[166:169], v[146:149]
	v_mfma_i32_16x16x64_i8 v[146:149], v[34:37], v[162:165], v[146:149]
	v_mfma_i32_16x16x64_i8 v[110:113], v[34:37], v[170:173], v[110:113]
	v_mfma_i32_16x16x64_i8 v[110:113], v[38:41], v[174:177], v[110:113]
	v_mfma_i32_16x16x64_i8 v[118:121], v[22:25], v[174:177], v[118:121]
	v_mfma_i32_16x16x64_i8 v[118:121], v[18:21], v[170:173], v[118:121]
	v_mfma_i32_16x16x64_i8 v[54:57], v[18:21], v[178:181], v[54:57]
	v_mfma_i32_16x16x64_i8 v[54:57], v[22:25], v[182:185], v[54:57]
	v_mfma_i32_16x16x64_i8 v[30:33], v[38:41], v[182:185], v[30:33]
	v_mfma_i32_16x16x64_i8 v[30:33], v[34:37], v[178:181], v[30:33]
	v_mfma_i32_16x16x64_i8 v[58:61], v[34:37], v[186:189], v[58:61]
	v_mfma_i32_16x16x64_i8 v[58:61], v[38:41], v[190:193], v[58:61]
	v_mfma_i32_16x16x64_i8 v[94:97], v[22:25], v[190:193], v[94:97]
	v_mfma_i32_16x16x64_i8 v[94:97], v[18:21], v[186:189], v[94:97]
	v_mfma_i32_16x16x64_i8 v[62:65], v[154:157], v[186:189], v[62:65]
	v_mfma_i32_16x16x64_i8 v[62:65], v[158:161], v[190:193], v[62:65]
	v_mfma_i32_16x16x64_i8 v[138:141], v[158:161], v[166:169], v[138:141]
	v_mfma_i32_16x16x64_i8 v[138:141], v[154:157], v[162:165], v[138:141]
	v_mfma_i32_16x16x64_i8 v[142:145], v[130:133], v[162:165], v[142:145]
	v_mfma_i32_16x16x64_i8 v[142:145], v[134:137], v[166:169], v[142:145]
	v_mfma_i32_16x16x64_i8 v[102:105], v[134:137], v[174:177], v[102:105]
	v_mfma_i32_16x16x64_i8 v[102:105], v[130:133], v[170:173], v[102:105]
	v_mfma_i32_16x16x64_i8 v[98:101], v[154:157], v[170:173], v[98:101]
	v_mfma_i32_16x16x64_i8 v[98:101], v[158:161], v[174:177], v[98:101]
	v_mfma_i32_16x16x64_i8 v[26:29], v[158:161], v[182:185], v[26:29]
	v_mfma_i32_16x16x64_i8 v[26:29], v[154:157], v[178:181], v[26:29]
	v_mfma_i32_16x16x64_i8 v[42:45], v[130:133], v[178:181], v[42:45]
	v_mfma_i32_16x16x64_i8 v[42:45], v[134:137], v[182:185], v[42:45]
	v_mfma_i32_16x16x64_i8 v[78:81], v[134:137], v[190:193], v[78:81]
	v_mfma_i32_16x16x64_i8 v[78:81], v[130:133], v[186:189], v[78:81]
	s_barrier
	s_add_i32 s0, vcc_hi, s69
	v_lshl_add_u64 v[198:199], s[6:7], 0, v[0:1]
	s_mov_b32 m0, s0
	ds_read_b128 v[162:165], v243 offset:16384
	ds_read_b128 v[166:169], v243 offset:17408
	ds_read_b128 v[170:173], v243 offset:18432
	ds_read_b128 v[174:177], v243 offset:19456
	ds_read_b128 v[178:181], v243 offset:20480
	ds_read_b128 v[182:185], v243 offset:21504
	ds_read_b128 v[186:189], v243 offset:22528
	ds_read_b128 v[190:193], v243 offset:23552
	global_load_lds_dwordx4 v[198:199], off
	s_add_i32 m0, s0, 0x2000
	s_add_u32 s0, s6, 0x40000
	v_lshl_add_u64 v[200:201], s[6:7], 0, v[214:215]
	s_addc_u32 s1, s7, 0
	s_add_i32 s4, s4, s69
	global_load_lds_dwordx4 v[200:201], off
	s_mov_b32 m0, s4
	v_lshl_add_u64 v[206:207], s[12:13], 0, v[210:211]
	global_load_lds_dwordx4 v0, s[0:1]
	s_add_i32 m0, s4, 0x2000
	v_lshl_add_u64 v[220:221], s[12:13], 0, v[212:213]
	global_load_lds_dwordx4 v214, s[0:1]
	s_mov_b32 m0, s11
	s_nop 0
	global_load_lds_dwordx4 v[206:207], off
	s_mov_b32 m0, s71
	s_nop 0
	global_load_lds_dwordx4 v[220:221], off
	s_waitcnt vmcnt(8)
	s_waitcnt lgkmcnt(0)
	s_barrier
	v_mfma_i32_16x16x64_i8 v[106:109], v[18:21], v[162:165], v[106:109]
	v_mfma_i32_16x16x64_i8 v[106:109], v[22:25], v[166:169], v[106:109]
	v_mfma_i32_16x16x64_i8 v[46:49], v[34:37], v[162:165], v[46:49]
	v_mfma_i32_16x16x64_i8 v[46:49], v[38:41], v[166:169], v[46:49]
	v_mfma_i32_16x16x64_i8 v[6:9], v[34:37], v[170:173], v[6:9]
	v_mfma_i32_16x16x64_i8 v[6:9], v[38:41], v[174:177], v[6:9]
	v_mfma_i32_16x16x64_i8 v[14:17], v[18:21], v[170:173], v[14:17]
	v_mfma_i32_16x16x64_i8 v[14:17], v[22:25], v[174:177], v[14:17]
	v_mfma_i32_16x16x64_i8 v[90:93], v[18:21], v[178:181], v[90:93]
	v_mfma_i32_16x16x64_i8 v[90:93], v[22:25], v[182:185], v[90:93]
	v_mfma_i32_16x16x64_i8 v[86:89], v[34:37], v[178:181], v[86:89]
	v_mfma_i32_16x16x64_i8 v[86:89], v[38:41], v[182:185], v[86:89]
	v_mfma_i32_16x16x64_i8 v[18:21], v[18:21], v[186:189], v[126:129]
	v_mfma_i32_16x16x64_i8 v[18:21], v[22:25], v[190:193], v[18:21]
	v_mfma_i32_16x16x64_i8 v[22:25], v[34:37], v[186:189], v[66:69]
	v_mfma_i32_16x16x64_i8 v[22:25], v[38:41], v[190:193], v[22:25]
	v_mfma_i32_16x16x64_i8 v[38:41], v[154:157], v[162:165], v[50:53]
	v_mfma_i32_16x16x64_i8 v[38:41], v[158:161], v[166:169], v[38:41]
	v_mfma_i32_16x16x64_i8 v[2:5], v[154:157], v[170:173], v[2:5]
	v_mfma_i32_16x16x64_i8 v[2:5], v[158:161], v[174:177], v[2:5]
	v_mfma_i32_16x16x64_i8 v[10:13], v[130:133], v[170:173], v[10:13]
	v_mfma_i32_16x16x64_i8 v[10:13], v[134:137], v[174:177], v[10:13]
	v_mfma_i32_16x16x64_i8 v[50:53], v[130:133], v[178:181], v[82:85]
	v_mfma_i32_16x16x64_i8 v[82:85], v[134:137], v[182:185], v[50:53]
	v_mfma_i32_16x16x64_i8 v[34:37], v[130:133], v[162:165], v[114:117]
	v_mfma_i32_16x16x64_i8 v[34:37], v[134:137], v[166:169], v[34:37]
	v_mfma_i32_16x16x64_i8 v[50:53], v[154:157], v[178:181], v[74:77]
	v_mfma_i32_16x16x64_i8 v[74:77], v[158:161], v[182:185], v[50:53]
	v_mfma_i32_16x16x64_i8 v[50:53], v[130:133], v[186:189], v[122:125]
	v_mfma_i32_16x16x64_i8 v[122:125], v[134:137], v[190:193], v[50:53]
	v_mfma_i32_16x16x64_i8 v[50:53], v[154:157], v[186:189], v[70:73]
	v_mfma_i32_16x16x64_i8 v[70:73], v[158:161], v[190:193], v[50:53]
	s_barrier
; #define PG8_STAGE(bufoff, gbase, voff) do { _Pragma("unroll") for (int _i = 0; _i < 2; ++_i) \
;         __builtin_amdgcn_global_load_lds((const unsigned*)((const char*)(gbase) + (voff)[_i]), (PG8_LAS unsigned*)(lds + (bufoff) + ldsw + _i * 8192), 16, 0, 0); } while (0)
; #define PG8_LDA(dst, b, h) do { _Pragma("unroll") for (int m = 0; m < 4; ++m) _Pragma("unroll") for (int k = 0; k < 2; ++k) dst[m][k] = *(const PG8_LAS bf16x8*)(lds + PG8_SA(b, h) + aoff + m * 2048 + k * 1024); } while (0)
; #define PG8_LDB(dst, b, h) do { _Pragma("unroll") for (int n = 0; n < 2; ++n) _Pragma("unroll") for (int k = 0; k < 2; ++k) dst[n][k] = *(const PG8_LAS bf16x8*)(lds + PG8_SB(b, h) + boff + n * 2048 + k * 1024); } while (0)
; #define PG8_MMA(ai, bj, At, Bt) do { __builtin_amdgcn_s_setprio(1); _Pragma("unroll") for (int m = 0; m < 4; ++m) _Pragma("unroll") for (int n = 0; n < 2; ++n) _Pragma("unroll") for (int k = 0; k < 2; ++k) \
;         acc[ai][bj][m][n] = mma16<Epi::I8>(Bt[n][k], At[m][k], acc[ai][bj][m][n]); __builtin_amdgcn_s_setprio(0); } while (0)
; #define PG8_WAIT_V(n) asm volatile("s_waitcnt vmcnt(" #n ")" ::: "memory")
; #define PG8_WAIT_L(n) asm volatile("s_waitcnt lgkmcnt(" #n ")" ::: "memory")
; #define PG8_BAR __builtin_amdgcn_s_barrier()
; #define PG8_SCHED __builtin_amdgcn_sched_barrier(0)
; template <class Epi, class Sched, bool ALIGN_EPI = false, bool SP2 = false>
; __device__ __forceinline__ void gemm_phase(PG8_LAS unsigned char* lds, const Gemm g, const Sched& S, const Epi& E) {
;     ...
;             PG8_LDB(B0, 1, 0); PG8_LDB(B1, 1, 1); PG8_SCHED; PG8_LDA(At, 1, 0); PG8_STAGE(PG8_SA(0, 1), a2 + hstep, voffA);
;             PG8_WAIT_V(8); PG8_WAIT_L(0); PG8_BAR; PG8_MMA(0, 0, At, B0); PG8_MMA(0, 1, At, B1); PG8_BAR; PG8_SCHED;
;             PG8_LDA(At, 1, 1); PG8_STAGE(PG8_SB(1, 0), b3, voffB); PG8_STAGE(PG8_SB(1, 1), b3 + hstep, voffB); PG8_STAGE(PG8_SA(1, 0), a3, voffA);
;             PG8_WAIT_V(8); PG8_WAIT_L(0); PG8_BAR; PG8_MMA(1, 0, At, B0); PG8_MMA(1, 1, At, B1); PG8_BAR; PG8_SCHED;
	s_add_i32 s4, 0, 0x18000
	v_add_u32_e32 v126, s4, v242
	s_add_i32 s5, 0, 0x1c000
	ds_read_b128 v[50:53], v126
	ds_read_b128 v[66:69], v126 offset:1024
	ds_read_b128 v[114:117], v126 offset:2048
	ds_read_b128 v[130:133], v126 offset:3072
	v_add_u32_e32 v126, s5, v242
	ds_read_b128 v[134:137], v126
	ds_read_b128 v[154:157], v126 offset:1024
	ds_read_b128 v[158:161], v126 offset:2048
	ds_read_b128 v[162:165], v126 offset:3072
	s_add_u32 s0, s12, 0x40000
	s_addc_u32 s1, s13, 0
	s_mov_b32 m0, s80
	ds_read_b128 v[126:129], v243 offset:32768
	ds_read_b128 v[166:169], v243 offset:33792
	ds_read_b128 v[170:173], v243 offset:34816
	ds_read_b128 v[174:177], v243 offset:35840
	ds_read_b128 v[178:181], v243 offset:36864
	ds_read_b128 v[182:185], v243 offset:37888
	ds_read_b128 v[186:189], v243 offset:38912
	ds_read_b128 v[190:193], v243 offset:39936
	global_load_lds_dwordx4 v210, s[0:1]
	s_mov_b32 m0, s81
	s_nop 0
	global_load_lds_dwordx4 v212, s[0:1]
	s_waitcnt vmcnt(8)
	s_waitcnt lgkmcnt(0)
	s_barrier
	v_mfma_i32_16x16x64_i8 v[150:153], v[50:53], v[126:129], v[150:153]
	v_mfma_i32_16x16x64_i8 v[150:153], v[66:69], v[166:169], v[150:153]
	v_mfma_i32_16x16x64_i8 v[146:149], v[114:117], v[126:129], v[146:149]
	v_mfma_i32_16x16x64_i8 v[146:149], v[130:133], v[166:169], v[146:149]
	v_mfma_i32_16x16x64_i8 v[110:113], v[114:117], v[170:173], v[110:113]
	v_mfma_i32_16x16x64_i8 v[110:113], v[130:133], v[174:177], v[110:113]
	v_mfma_i32_16x16x64_i8 v[118:121], v[50:53], v[170:173], v[118:121]
	v_mfma_i32_16x16x64_i8 v[118:121], v[66:69], v[174:177], v[118:121]
	v_mfma_i32_16x16x64_i8 v[54:57], v[50:53], v[178:181], v[54:57]
	v_mfma_i32_16x16x64_i8 v[54:57], v[66:69], v[182:185], v[54:57]
	v_mfma_i32_16x16x64_i8 v[30:33], v[114:117], v[178:181], v[30:33]
	v_mfma_i32_16x16x64_i8 v[30:33], v[130:133], v[182:185], v[30:33]
	v_mfma_i32_16x16x64_i8 v[58:61], v[114:117], v[186:189], v[58:61]
	v_mfma_i32_16x16x64_i8 v[58:61], v[130:133], v[190:193], v[58:61]
	v_mfma_i32_16x16x64_i8 v[94:97], v[50:53], v[186:189], v[94:97]
	v_mfma_i32_16x16x64_i8 v[94:97], v[66:69], v[190:193], v[94:97]
	v_mfma_i32_16x16x64_i8 v[142:145], v[134:137], v[126:129], v[142:145]
	v_mfma_i32_16x16x64_i8 v[142:145], v[154:157], v[166:169], v[142:145]
	v_mfma_i32_16x16x64_i8 v[126:129], v[158:161], v[126:129], v[138:141]
	v_mfma_i32_16x16x64_i8 v[138:141], v[162:165], v[166:169], v[126:129]
	v_mfma_i32_16x16x64_i8 v[98:101], v[158:161], v[170:173], v[98:101]
	v_mfma_i32_16x16x64_i8 v[98:101], v[162:165], v[174:177], v[98:101]
	v_mfma_i32_16x16x64_i8 v[102:105], v[134:137], v[170:173], v[102:105]
	v_mfma_i32_16x16x64_i8 v[102:105], v[154:157], v[174:177], v[102:105]
	v_mfma_i32_16x16x64_i8 v[42:45], v[134:137], v[178:181], v[42:45]
	v_mfma_i32_16x16x64_i8 v[42:45], v[154:157], v[182:185], v[42:45]
	v_mfma_i32_16x16x64_i8 v[26:29], v[158:161], v[178:181], v[26:29]
	v_mfma_i32_16x16x64_i8 v[26:29], v[162:165], v[182:185], v[26:29]
	v_mfma_i32_16x16x64_i8 v[62:65], v[158:161], v[186:189], v[62:65]
	v_mfma_i32_16x16x64_i8 v[62:65], v[162:165], v[190:193], v[62:65]
	v_mfma_i32_16x16x64_i8 v[78:81], v[134:137], v[186:189], v[78:81]
	v_mfma_i32_16x16x64_i8 v[78:81], v[154:157], v[190:193], v[78:81]
	s_barrier
	s_add_i32 s0, s4, s69
	v_lshl_add_u64 v[126:127], v[198:199], 0, s[92:93]
	s_mov_b32 m0, s0
	ds_read_b128 v[166:169], v243 offset:49152
	ds_read_b128 v[170:173], v243 offset:50176
	ds_read_b128 v[174:177], v243 offset:51200
	ds_read_b128 v[178:181], v243 offset:52224
	ds_read_b128 v[182:185], v243 offset:53248
	ds_read_b128 v[186:189], v243 offset:54272
	ds_read_b128 v[190:193], v243 offset:55296
	ds_read_b128 v[194:197], v243 offset:56320
	global_load_lds_dwordx4 v[126:127], off
	s_add_i32 m0, s0, 0x2000
	s_add_u32 s0, s6, 0x40080
	v_lshl_add_u64 v[126:127], v[200:201], 0, s[92:93]
	s_addc_u32 s1, s7, 0
	s_add_i32 s4, s5, s69
	global_load_lds_dwordx4 v[126:127], off
	s_mov_b32 m0, s4
	s_nop 0
	global_load_lds_dwordx4 v0, s[0:1]
	s_add_i32 m0, s4, 0x2000
	s_nop 0
	global_load_lds_dwordx4 v214, s[0:1]
	v_lshl_add_u64 v[126:127], v[206:207], 0, s[92:93]
	s_mov_b32 m0, s84
	s_nop 0
	global_load_lds_dwordx4 v[126:127], off
	v_lshl_add_u64 v[126:127], v[220:221], 0, s[92:93]
	s_mov_b32 m0, s85
	s_nop 0
	global_load_lds_dwordx4 v[126:127], off
	s_waitcnt vmcnt(8)
	s_waitcnt lgkmcnt(0)
	s_barrier
	v_mfma_i32_16x16x64_i8 v[18:21], v[50:53], v[190:193], v[18:21]
	v_mfma_i32_16x16x64_i8 v[126:129], v[66:69], v[194:197], v[18:21]
	v_mfma_i32_16x16x64_i8 v[106:109], v[50:53], v[166:169], v[106:109]
	v_mfma_i32_16x16x64_i8 v[106:109], v[66:69], v[170:173], v[106:109]
	v_mfma_i32_16x16x64_i8 v[46:49], v[114:117], v[166:169], v[46:49]
	v_mfma_i32_16x16x64_i8 v[46:49], v[130:133], v[170:173], v[46:49]
	v_mfma_i32_16x16x64_i8 v[6:9], v[114:117], v[174:177], v[6:9]
	v_mfma_i32_16x16x64_i8 v[6:9], v[130:133], v[178:181], v[6:9]
	v_mfma_i32_16x16x64_i8 v[14:17], v[50:53], v[174:177], v[14:17]
	v_mfma_i32_16x16x64_i8 v[14:17], v[66:69], v[178:181], v[14:17]
	v_mfma_i32_16x16x64_i8 v[90:93], v[50:53], v[182:185], v[90:93]
	v_mfma_i32_16x16x64_i8 v[90:93], v[66:69], v[186:189], v[90:93]
	v_mfma_i32_16x16x64_i8 v[86:89], v[114:117], v[182:185], v[86:89]
	v_mfma_i32_16x16x64_i8 v[86:89], v[130:133], v[186:189], v[86:89]
	v_mfma_i32_16x16x64_i8 v[18:21], v[114:117], v[190:193], v[22:25]
	v_mfma_i32_16x16x64_i8 v[66:69], v[130:133], v[194:197], v[18:21]
	v_mfma_i32_16x16x64_i8 v[18:21], v[134:137], v[166:169], v[34:37]
	v_mfma_i32_16x16x64_i8 v[114:117], v[154:157], v[170:173], v[18:21]
	v_mfma_i32_16x16x64_i8 v[10:13], v[134:137], v[174:177], v[10:13]
	v_mfma_i32_16x16x64_i8 v[10:13], v[154:157], v[178:181], v[10:13]
	v_mfma_i32_16x16x64_i8 v[2:5], v[158:161], v[174:177], v[2:5]
	v_mfma_i32_16x16x64_i8 v[2:5], v[162:165], v[178:181], v[2:5]
	v_mfma_i32_16x16x64_i8 v[18:21], v[158:161], v[166:169], v[38:41]
	v_mfma_i32_16x16x64_i8 v[50:53], v[162:165], v[170:173], v[18:21]
	v_mfma_i32_16x16x64_i8 v[18:21], v[134:137], v[182:185], v[82:85]
	v_mfma_i32_16x16x64_i8 v[82:85], v[154:157], v[186:189], v[18:21]
	v_mfma_i32_16x16x64_i8 v[18:21], v[158:161], v[182:185], v[74:77]
	v_mfma_i32_16x16x64_i8 v[74:77], v[162:165], v[186:189], v[18:21]
	v_mfma_i32_16x16x64_i8 v[18:21], v[134:137], v[190:193], v[122:125]
	v_mfma_i32_16x16x64_i8 v[122:125], v[154:157], v[194:197], v[18:21]
	v_mfma_i32_16x16x64_i8 v[18:21], v[158:161], v[190:193], v[70:73]
	v_mfma_i32_16x16x64_i8 v[70:73], v[162:165], v[194:197], v[18:21]
	s_barrier
	s_add_i32 vcc_lo, vcc_lo, 2
	s_add_u32 s96, s96, 0x100
	s_addc_u32 s97, s97, 0
	s_cmp_gt_u32 vcc_lo, 13
	s_mov_b64 s[0:1], s[8:9]
	s_cbranch_scc0 .LBB0_80

; #define PG8_STAGE(bufoff, gbase, voff) do { _Pragma("unroll") for (int _i = 0; _i < 2; ++_i) \
;         __builtin_amdgcn_global_load_lds((const unsigned*)((const char*)(gbase) + (voff)[_i]), (PG8_LAS unsigned*)(lds + (bufoff) + ldsw + _i * 8192), 16, 0, 0); } while (0)
; #define PG8_LDA(dst, b, h) do { _Pragma("unroll") for (int m = 0; m < 4; ++m) _Pragma("unroll") for (int k = 0; k < 2; ++k) dst[m][k] = *(const PG8_LAS bf16x8*)(lds + PG8_SA(b, h) + aoff + m * 2048 + k * 1024); } while (0)
; #define PG8_LDB(dst, b, h) do { _Pragma("unroll") for (int n = 0; n < 2; ++n) _Pragma("unroll") for (int k = 0; k < 2; ++k) dst[n][k] = *(const PG8_LAS bf16x8*)(lds + PG8_SB(b, h) + boff + n * 2048 + k * 1024); } while (0)
; #define PG8_MMA(ai, bj, At, Bt) do { __builtin_amdgcn_s_setprio(1); _Pragma("unroll") for (int m = 0; m < 4; ++m) _Pragma("unroll") for (int n = 0; n < 2; ++n) _Pragma("unroll") for (int k = 0; k < 2; ++k) \
;         acc[ai][bj][m][n] = mma16<Epi::I8>(Bt[n][k], At[m][k], acc[ai][bj][m][n]); __builtin_amdgcn_s_setprio(0); } while (0)
; #define PG8_WAIT_V(n) asm volatile("s_waitcnt vmcnt(" #n ")" ::: "memory")
; #define PG8_WAIT_L(n) asm volatile("s_waitcnt lgkmcnt(" #n ")" ::: "memory")
; #define PG8_BAR __builtin_amdgcn_s_barrier()
; template <class Epi, class Sched, bool ALIGN_EPI = false, bool SP2 = false>
; __device__ __forceinline__ void gemm_phase(PG8_LAS unsigned char* lds, const Gemm g, const Sched& S, const Epi& E) {
;     ...
;             const bool last = (t == nt - 2);
;             const char* a1 = cA + (size_t)(t + 1) * kstep;
;             const char* a2 = last ? nA : cA + (size_t)(t + 2) * kstep; const char* b2 = last ? nB : cB + (size_t)(t + 2) * kstep;
;             const char* a3 = a2 + kstep; const char* b3 = b2 + kstep;
;             if (last && has_next) S.a_ready(nxt);
;             if constexpr (SP2) {
;             PG8_LDB(B0, 0, 0); PG8_LDB(B1, 0, 1); PG8_SCHED; PG8_LDA(At, 0, 0); PG8_STAGE(PG8_SA(1, 1), a1 + hstep, voffA);
;             PG8_WAIT_V(8); PG8_WAIT_L(0); PG8_BAR; PG8_MMA(0, 0, At, B0); PG8_MMA(0, 1, At, B1); PG8_BAR; PG8_SCHED;
;             PG8_LDA(At, 0, 1); PG8_STAGE(PG8_SB(0, 0), b2, voffB); PG8_STAGE(PG8_SB(0, 1), b2 + hstep, voffB); PG8_STAGE(PG8_SA(0, 0), a2, voffA);
;             PG8_WAIT_V(8); PG8_WAIT_L(0); PG8_BAR; PG8_MMA(1, 0, At, B0); PG8_MMA(1, 1, At, B1); PG8_BAR; PG8_SCHED;
.Lpeel175:
	s_add_i32 vcc_lo, s8, 2
	s_add_u32 s4, s6, s98
	s_addc_u32 s5, s7, 0
	s_add_i32 vcc_hi, 0, 0x10000
	s_cmp_eq_u32 s13, s8
	s_cselect_b32 s9, s1, s5
	s_cselect_b32 s8, s0, s4
	s_cselect_b32 s5, s97, s85
	s_cselect_b32 s4, s96, s67
	s_add_i32 s84, 0, 0x14000
	v_add_u32_e32 v122, vcc_hi, v248
	v_add_u32_e32 v154, s84, v248
	ds_read_b128 v[98:101], v122
	ds_read_b128 v[102:105], v122 offset:1024
	ds_read_b128 v[114:117], v122 offset:2048
	ds_read_b128 v[122:125], v122 offset:3072
	ds_read_b128 v[130:133], v154
	ds_read_b128 v[138:141], v154 offset:1024
	ds_read_b128 v[146:149], v154 offset:2048
	ds_read_b128 v[154:157], v154 offset:3072
	v_lshl_add_u64 v[206:207], s[6:7], 0, v[200:201]
	s_add_i32 m0, s81, 0xc000
	ds_read_b128 v[162:165], v249
	ds_read_b128 v[166:169], v249 offset:1024
	ds_read_b128 v[170:173], v249 offset:2048
	ds_read_b128 v[174:177], v249 offset:3072
	ds_read_b128 v[178:181], v249 offset:4096
	ds_read_b128 v[182:185], v249 offset:5120
	ds_read_b128 v[186:189], v249 offset:6144
	ds_read_b128 v[190:193], v249 offset:7168
	global_load_lds_dwordx4 v[206:207], off
	v_lshl_add_u64 v[206:207], s[6:7], 0, v[210:211]
	s_add_i32 m0, s81, 0xe000
	s_nop 0
	global_load_lds_dwordx4 v[206:207], off
	s_waitcnt vmcnt(8)
	s_waitcnt lgkmcnt(0)
	s_barrier
	v_mfma_f32_16x16x32_bf16 v[158:161], v[98:101], v[162:165], 0
	v_mfma_f32_16x16x32_bf16 v[158:161], v[102:105], v[166:169], v[158:161]
	v_mfma_f32_16x16x32_bf16 v[150:153], v[114:117], v[162:165], 0
	v_mfma_f32_16x16x32_bf16 v[150:153], v[122:125], v[166:169], v[150:153]
	v_mfma_f32_16x16x32_bf16 v[118:121], v[114:117], v[170:173], 0
	v_mfma_f32_16x16x32_bf16 v[118:121], v[122:125], v[174:177], v[118:121]
	v_mfma_f32_16x16x32_bf16 v[126:129], v[98:101], v[170:173], 0
	v_mfma_f32_16x16x32_bf16 v[126:129], v[102:105], v[174:177], v[126:129]
	v_mfma_f32_16x16x32_bf16 v[94:97], v[98:101], v[178:181], 0
	v_mfma_f32_16x16x32_bf16 v[94:97], v[102:105], v[182:185], v[94:97]
	v_mfma_f32_16x16x32_bf16 v[90:93], v[114:117], v[178:181], 0
	v_mfma_f32_16x16x32_bf16 v[90:93], v[122:125], v[182:185], v[90:93]
	v_mfma_f32_16x16x32_bf16 v[74:77], v[114:117], v[186:189], 0
	v_mfma_f32_16x16x32_bf16 v[74:77], v[122:125], v[190:193], v[74:77]
	v_mfma_f32_16x16x32_bf16 v[78:81], v[98:101], v[186:189], 0
	v_mfma_f32_16x16x32_bf16 v[78:81], v[102:105], v[190:193], v[78:81]
	v_mfma_f32_16x16x32_bf16 v[142:145], v[130:133], v[162:165], 0
	v_mfma_f32_16x16x32_bf16 v[142:145], v[138:141], v[166:169], v[142:145]
	v_mfma_f32_16x16x32_bf16 v[134:137], v[146:149], v[162:165], 0
	v_mfma_f32_16x16x32_bf16 v[134:137], v[154:157], v[166:169], v[134:137]
	v_mfma_f32_16x16x32_bf16 v[106:109], v[146:149], v[170:173], 0
	v_mfma_f32_16x16x32_bf16 v[106:109], v[154:157], v[174:177], v[106:109]
	v_mfma_f32_16x16x32_bf16 v[110:113], v[130:133], v[170:173], 0
	v_mfma_f32_16x16x32_bf16 v[110:113], v[138:141], v[174:177], v[110:113]
	v_mfma_f32_16x16x32_bf16 v[86:89], v[130:133], v[178:181], 0
	v_mfma_f32_16x16x32_bf16 v[86:89], v[138:141], v[182:185], v[86:89]
	v_mfma_f32_16x16x32_bf16 v[82:85], v[146:149], v[178:181], 0
	v_mfma_f32_16x16x32_bf16 v[82:85], v[154:157], v[182:185], v[82:85]
	v_mfma_f32_16x16x32_bf16 v[66:69], v[146:149], v[186:189], 0
	v_mfma_f32_16x16x32_bf16 v[66:69], v[154:157], v[190:193], v[66:69]
	v_mfma_f32_16x16x32_bf16 v[70:73], v[130:133], v[186:189], 0
	v_mfma_f32_16x16x32_bf16 v[70:73], v[138:141], v[190:193], v[70:73]
	s_barrier
	s_add_i32 vcc_hi, vcc_hi, s80
	v_lshl_add_u64 v[206:207], s[4:5], 0, v[0:1]
	s_mov_b32 m0, vcc_hi
	ds_read_b128 v[162:165], v249 offset:16384
	ds_read_b128 v[166:169], v249 offset:17408
	ds_read_b128 v[170:173], v249 offset:18432
	ds_read_b128 v[174:177], v249 offset:19456
	ds_read_b128 v[178:181], v249 offset:20480
	ds_read_b128 v[182:185], v249 offset:21504
	ds_read_b128 v[186:189], v249 offset:22528
	ds_read_b128 v[190:193], v249 offset:23552
	global_load_lds_dwordx4 v[206:207], off
	s_add_i32 m0, vcc_hi, 0x2000
	v_lshl_add_u64 v[212:213], s[4:5], 0, v[198:199]
	s_add_u32 s4, s4, s100
	s_addc_u32 s5, s5, 0
	s_add_i32 s84, s84, s80
	global_load_lds_dwordx4 v[212:213], off
	v_lshl_add_u64 v[214:215], s[4:5], 0, v[0:1]
	s_mov_b32 m0, s84
	v_lshl_add_u64 v[216:217], s[4:5], 0, v[198:199]
	global_load_lds_dwordx4 v[214:215], off
	s_add_i32 m0, s84, 0x2000
	v_lshl_add_u64 v[218:219], s[8:9], 0, v[194:195]
	global_load_lds_dwordx4 v[216:217], off
	s_mov_b32 m0, s81
	v_lshl_add_u64 v[220:221], s[8:9], 0, v[196:197]
	global_load_lds_dwordx4 v[218:219], off
	s_mov_b32 m0, s70
	s_nop 0
	global_load_lds_dwordx4 v[220:221], off
	s_waitcnt vmcnt(8)
	s_waitcnt lgkmcnt(0)
	s_barrier
; #define PG8_STAGE(bufoff, gbase, voff) do { _Pragma("unroll") for (int _i = 0; _i < 2; ++_i) \
;         __builtin_amdgcn_global_load_lds((const unsigned*)((const char*)(gbase) + (voff)[_i]), (PG8_LAS unsigned*)(lds + (bufoff) + ldsw + _i * 8192), 16, 0, 0); } while (0)
; #define PG8_LDA(dst, b, h) do { _Pragma("unroll") for (int m = 0; m < 4; ++m) _Pragma("unroll") for (int k = 0; k < 2; ++k) dst[m][k] = *(const PG8_LAS bf16x8*)(lds + PG8_SA(b, h) + aoff + m * 2048 + k * 1024); } while (0)
; #define PG8_LDB(dst, b, h) do { _Pragma("unroll") for (int n = 0; n < 2; ++n) _Pragma("unroll") for (int k = 0; k < 2; ++k) dst[n][k] = *(const PG8_LAS bf16x8*)(lds + PG8_SB(b, h) + boff + n * 2048 + k * 1024); } while (0)
; #define PG8_MMA(ai, bj, At, Bt) do { __builtin_amdgcn_s_setprio(1); _Pragma("unroll") for (int m = 0; m < 4; ++m) _Pragma("unroll") for (int n = 0; n < 2; ++n) _Pragma("unroll") for (int k = 0; k < 2; ++k) \
;         acc[ai][bj][m][n] = mma16<Epi::I8>(Bt[n][k], At[m][k], acc[ai][bj][m][n]); __builtin_amdgcn_s_setprio(0); } while (0)
; #define PG8_WAIT_V(n) asm volatile("s_waitcnt vmcnt(" #n ")" ::: "memory")
; #define PG8_WAIT_L(n) asm volatile("s_waitcnt lgkmcnt(" #n ")" ::: "memory")
; #define PG8_BAR __builtin_amdgcn_s_barrier()
; #define PG8_SCHED __builtin_amdgcn_sched_barrier(0)
; template <class Epi, class Sched, bool ALIGN_EPI = false, bool SP2 = false>
; __device__ __forceinline__ void gemm_phase(PG8_LAS unsigned char* lds, const Gemm g, const Sched& S, const Epi& E) {
;     ...
;             PG8_WAIT_V(8); PG8_WAIT_L(0); PG8_BAR; PG8_MMA(0, 0, At, B0); PG8_MMA(0, 1, At, B1); PG8_BAR; PG8_SCHED;
;             PG8_LDA(At, 0, 1); PG8_STAGE(PG8_SB(0, 0), b2, voffB); PG8_STAGE(PG8_SB(0, 1), b2 + hstep, voffB); PG8_STAGE(PG8_SA(0, 0), a2, voffA);
;             PG8_WAIT_V(8); PG8_WAIT_L(0); PG8_BAR; PG8_MMA(1, 0, At, B0); PG8_MMA(1, 1, At, B1); PG8_BAR; PG8_SCHED;
;             PG8_LDB(B0, 1, 0); PG8_LDB(B1, 1, 1); PG8_SCHED; PG8_LDA(At, 1, 0); PG8_STAGE(PG8_SA(0, 1), a2 + hstep, voffA);
;             PG8_WAIT_V(8); PG8_WAIT_L(0); PG8_BAR; PG8_MMA(0, 0, At, B0); PG8_MMA(0, 1, At, B1); PG8_BAR; PG8_SCHED;
	v_mfma_f32_16x16x32_bf16 v[62:65], v[98:101], v[162:165], 0
	v_mfma_f32_16x16x32_bf16 v[62:65], v[102:105], v[166:169], v[62:65]
	v_mfma_f32_16x16x32_bf16 v[58:61], v[114:117], v[162:165], 0
	v_mfma_f32_16x16x32_bf16 v[58:61], v[122:125], v[166:169], v[58:61]
	v_mfma_f32_16x16x32_bf16 v[42:45], v[114:117], v[170:173], 0
	v_mfma_f32_16x16x32_bf16 v[42:45], v[122:125], v[174:177], v[42:45]
	v_mfma_f32_16x16x32_bf16 v[46:49], v[98:101], v[170:173], 0
	v_mfma_f32_16x16x32_bf16 v[46:49], v[102:105], v[174:177], v[46:49]
	v_mfma_f32_16x16x32_bf16 v[30:33], v[98:101], v[178:181], 0
	v_mfma_f32_16x16x32_bf16 v[30:33], v[102:105], v[182:185], v[30:33]
	v_mfma_f32_16x16x32_bf16 v[26:29], v[114:117], v[178:181], 0
	v_mfma_f32_16x16x32_bf16 v[26:29], v[122:125], v[182:185], v[26:29]
	v_mfma_f32_16x16x32_bf16 v[10:13], v[114:117], v[186:189], 0
	v_mfma_f32_16x16x32_bf16 v[10:13], v[122:125], v[190:193], v[10:13]
	v_mfma_f32_16x16x32_bf16 v[14:17], v[98:101], v[186:189], 0
	v_mfma_f32_16x16x32_bf16 v[14:17], v[102:105], v[190:193], v[14:17]
	v_mfma_f32_16x16x32_bf16 v[54:57], v[130:133], v[162:165], 0
	v_mfma_f32_16x16x32_bf16 v[54:57], v[138:141], v[166:169], v[54:57]
	v_mfma_f32_16x16x32_bf16 v[50:53], v[146:149], v[162:165], 0
	v_mfma_f32_16x16x32_bf16 v[50:53], v[154:157], v[166:169], v[50:53]
	v_mfma_f32_16x16x32_bf16 v[34:37], v[146:149], v[170:173], 0
	v_mfma_f32_16x16x32_bf16 v[34:37], v[154:157], v[174:177], v[34:37]
	v_mfma_f32_16x16x32_bf16 v[38:41], v[130:133], v[170:173], 0
	v_mfma_f32_16x16x32_bf16 v[38:41], v[138:141], v[174:177], v[38:41]
	v_mfma_f32_16x16x32_bf16 v[22:25], v[130:133], v[178:181], 0
	v_mfma_f32_16x16x32_bf16 v[22:25], v[138:141], v[182:185], v[22:25]
	v_mfma_f32_16x16x32_bf16 v[18:21], v[146:149], v[178:181], 0
	v_mfma_f32_16x16x32_bf16 v[18:21], v[154:157], v[182:185], v[18:21]
	v_mfma_f32_16x16x32_bf16 v[2:5], v[146:149], v[186:189], 0
	v_mfma_f32_16x16x32_bf16 v[2:5], v[154:157], v[190:193], v[2:5]
	v_mfma_f32_16x16x32_bf16 v[6:9], v[130:133], v[186:189], 0
	v_mfma_f32_16x16x32_bf16 v[6:9], v[138:141], v[190:193], v[6:9]
	s_barrier
	s_add_i32 s84, 0, 0x18000
	s_add_i32 vcc_hi, 0, 0x1c000
	v_add_u32_e32 v122, s84, v248
	v_add_u32_e32 v154, vcc_hi, v248
	ds_read_b128 v[98:101], v122
	ds_read_b128 v[102:105], v122 offset:1024
	ds_read_b128 v[114:117], v122 offset:2048
	ds_read_b128 v[122:125], v122 offset:3072
	ds_read_b128 v[130:133], v154
	ds_read_b128 v[138:141], v154 offset:1024
	ds_read_b128 v[146:149], v154 offset:2048
	ds_read_b128 v[154:157], v154 offset:3072
	s_add_u32 s4, s8, s100
	s_addc_u32 s5, s9, 0
	s_mov_b32 m0, s71
	v_lshl_add_u64 v[222:223], s[4:5], 0, v[194:195]
	ds_read_b128 v[162:165], v249 offset:32768
	ds_read_b128 v[166:169], v249 offset:33792
	ds_read_b128 v[170:173], v249 offset:34816
	ds_read_b128 v[174:177], v249 offset:35840
	ds_read_b128 v[178:181], v249 offset:36864
	ds_read_b128 v[182:185], v249 offset:37888
	ds_read_b128 v[186:189], v249 offset:38912
	ds_read_b128 v[190:193], v249 offset:39936
	global_load_lds_dwordx4 v[222:223], off
	v_lshl_add_u64 v[222:223], s[4:5], 0, v[196:197]
	s_mov_b32 m0, s12
	s_nop 0
	global_load_lds_dwordx4 v[222:223], off
	s_waitcnt vmcnt(8)
	s_waitcnt lgkmcnt(0)
	s_barrier
	v_mfma_f32_16x16x32_bf16 v[158:161], v[98:101], v[162:165], v[158:161]
	v_mfma_f32_16x16x32_bf16 v[158:161], v[102:105], v[166:169], v[158:161]
	v_mfma_f32_16x16x32_bf16 v[150:153], v[114:117], v[162:165], v[150:153]
	v_mfma_f32_16x16x32_bf16 v[150:153], v[122:125], v[166:169], v[150:153]
	v_mfma_f32_16x16x32_bf16 v[118:121], v[114:117], v[170:173], v[118:121]
	v_mfma_f32_16x16x32_bf16 v[118:121], v[122:125], v[174:177], v[118:121]
	v_mfma_f32_16x16x32_bf16 v[126:129], v[98:101], v[170:173], v[126:129]
	v_mfma_f32_16x16x32_bf16 v[126:129], v[102:105], v[174:177], v[126:129]
	v_mfma_f32_16x16x32_bf16 v[94:97], v[98:101], v[178:181], v[94:97]
	v_mfma_f32_16x16x32_bf16 v[94:97], v[102:105], v[182:185], v[94:97]
	v_mfma_f32_16x16x32_bf16 v[90:93], v[114:117], v[178:181], v[90:93]
	v_mfma_f32_16x16x32_bf16 v[90:93], v[122:125], v[182:185], v[90:93]
	v_mfma_f32_16x16x32_bf16 v[74:77], v[114:117], v[186:189], v[74:77]
	v_mfma_f32_16x16x32_bf16 v[74:77], v[122:125], v[190:193], v[74:77]
	v_mfma_f32_16x16x32_bf16 v[78:81], v[98:101], v[186:189], v[78:81]
	v_mfma_f32_16x16x32_bf16 v[78:81], v[102:105], v[190:193], v[78:81]
	v_mfma_f32_16x16x32_bf16 v[142:145], v[130:133], v[162:165], v[142:145]
	v_mfma_f32_16x16x32_bf16 v[142:145], v[138:141], v[166:169], v[142:145]
	v_mfma_f32_16x16x32_bf16 v[134:137], v[146:149], v[162:165], v[134:137]
	v_mfma_f32_16x16x32_bf16 v[134:137], v[154:157], v[166:169], v[134:137]
	v_mfma_f32_16x16x32_bf16 v[106:109], v[146:149], v[170:173], v[106:109]
	v_mfma_f32_16x16x32_bf16 v[106:109], v[154:157], v[174:177], v[106:109]
	v_mfma_f32_16x16x32_bf16 v[110:113], v[130:133], v[170:173], v[110:113]
	v_mfma_f32_16x16x32_bf16 v[110:113], v[138:141], v[174:177], v[110:113]
	v_mfma_f32_16x16x32_bf16 v[86:89], v[130:133], v[178:181], v[86:89]
	v_mfma_f32_16x16x32_bf16 v[86:89], v[138:141], v[182:185], v[86:89]
	v_mfma_f32_16x16x32_bf16 v[82:85], v[146:149], v[178:181], v[82:85]
	v_mfma_f32_16x16x32_bf16 v[82:85], v[154:157], v[182:185], v[82:85]
	v_mfma_f32_16x16x32_bf16 v[66:69], v[146:149], v[186:189], v[66:69]
	v_mfma_f32_16x16x32_bf16 v[66:69], v[154:157], v[190:193], v[66:69]
	v_mfma_f32_16x16x32_bf16 v[70:73], v[130:133], v[186:189], v[70:73]
	v_mfma_f32_16x16x32_bf16 v[70:73], v[138:141], v[190:193], v[70:73]
	s_barrier
; #define PG8_STAGE(bufoff, gbase, voff) do { _Pragma("unroll") for (int _i = 0; _i < 2; ++_i) \
;         __builtin_amdgcn_global_load_lds((const unsigned*)((const char*)(gbase) + (voff)[_i]), (PG8_LAS unsigned*)(lds + (bufoff) + ldsw + _i * 8192), 16, 0, 0); } while (0)
; #define PG8_LDA(dst, b, h) do { _Pragma("unroll") for (int m = 0; m < 4; ++m) _Pragma("unroll") for (int k = 0; k < 2; ++k) dst[m][k] = *(const PG8_LAS bf16x8*)(lds + PG8_SA(b, h) + aoff + m * 2048 + k * 1024); } while (0)
; #define PG8_LDB(dst, b, h) do { _Pragma("unroll") for (int n = 0; n < 2; ++n) _Pragma("unroll") for (int k = 0; k < 2; ++k) dst[n][k] = *(const PG8_LAS bf16x8*)(lds + PG8_SB(b, h) + boff + n * 2048 + k * 1024); } while (0)
; #define PG8_MMA(ai, bj, At, Bt) do { __builtin_amdgcn_s_setprio(1); _Pragma("unroll") for (int m = 0; m < 4; ++m) _Pragma("unroll") for (int n = 0; n < 2; ++n) _Pragma("unroll") for (int k = 0; k < 2; ++k) \
;         acc[ai][bj][m][n] = mma16<Epi::I8>(Bt[n][k], At[m][k], acc[ai][bj][m][n]); __builtin_amdgcn_s_setprio(0); } while (0)
; #define PG8_WAIT_V(n) asm volatile("s_waitcnt vmcnt(" #n ")" ::: "memory")
; #define PG8_WAIT_L(n) asm volatile("s_waitcnt lgkmcnt(" #n ")" ::: "memory")
; #define PG8_BAR __builtin_amdgcn_s_barrier()
; template <class Epi, class Sched, bool ALIGN_EPI = false, bool SP2 = false>
; __device__ __forceinline__ void gemm_phase(PG8_LAS unsigned char* lds, const Gemm g, const Sched& S, const Epi& E) {
;     ...
;             const bool last = (t == nt - 2);
;             const char* a1 = cA + (size_t)(t + 1) * kstep;
;             const char* a2 = last ? nA : cA + (size_t)(t + 2) * kstep; const char* b2 = last ? nB : cB + (size_t)(t + 2) * kstep;
;             const char* a3 = a2 + kstep; const char* b3 = b2 + kstep;
;             if (last && has_next) S.a_ready(nxt);
;             if constexpr (SP2) {
;             PG8_LDB(B0, 0, 0); PG8_LDB(B1, 0, 1); PG8_SCHED; PG8_LDA(At, 0, 0); PG8_STAGE(PG8_SA(1, 1), a1 + hstep, voffA);
;             PG8_WAIT_V(8); PG8_WAIT_L(0); PG8_BAR; PG8_MMA(0, 0, At, B0); PG8_MMA(0, 1, At, B1); PG8_BAR; PG8_SCHED;
;     ...
;             PG8_LDA(At, 1, 1); PG8_STAGE(PG8_SB(1, 0), b3, voffB); PG8_STAGE(PG8_SB(1, 1), b3 + hstep, voffB); PG8_STAGE(PG8_SA(1, 0), a3, voffA);
;             PG8_WAIT_V(8); PG8_WAIT_L(0); PG8_BAR; PG8_MMA(1, 0, At, B0); PG8_MMA(1, 1, At, B1); PG8_BAR; PG8_SCHED;
	s_add_i32 s4, s84, s80
	v_lshl_add_u64 v[206:207], v[206:207], 0, s[98:99]
	s_mov_b32 m0, s4
	ds_read_b128 v[162:165], v249 offset:49152
	ds_read_b128 v[166:169], v249 offset:50176
	ds_read_b128 v[170:173], v249 offset:51200
	ds_read_b128 v[174:177], v249 offset:52224
	ds_read_b128 v[178:181], v249 offset:53248
	ds_read_b128 v[182:185], v249 offset:54272
	ds_read_b128 v[186:189], v249 offset:55296
	ds_read_b128 v[190:193], v249 offset:56320
	global_load_lds_dwordx4 v[206:207], off
	v_lshl_add_u64 v[206:207], v[212:213], 0, s[98:99]
	s_add_i32 m0, s4, 0x2000
	s_add_i32 s4, vcc_hi, s80
	global_load_lds_dwordx4 v[206:207], off
	v_lshl_add_u64 v[206:207], v[214:215], 0, s[98:99]
	s_mov_b32 m0, s4
	s_nop 0
	global_load_lds_dwordx4 v[206:207], off
	v_lshl_add_u64 v[206:207], v[216:217], 0, s[98:99]
	s_add_i32 m0, s4, 0x2000
	s_nop 0
	global_load_lds_dwordx4 v[206:207], off
	v_lshl_add_u64 v[206:207], v[218:219], 0, s[98:99]
	s_mov_b32 m0, s10
	s_nop 0
	global_load_lds_dwordx4 v[206:207], off
	v_lshl_add_u64 v[206:207], v[220:221], 0, s[98:99]
	s_mov_b32 m0, s11
	s_nop 0
	global_load_lds_dwordx4 v[206:207], off
	s_waitcnt vmcnt(8)
	s_waitcnt lgkmcnt(0)
	s_barrier
	v_mfma_f32_16x16x32_bf16 v[62:65], v[98:101], v[162:165], v[62:65]
	v_mfma_f32_16x16x32_bf16 v[62:65], v[102:105], v[166:169], v[62:65]
	v_mfma_f32_16x16x32_bf16 v[58:61], v[114:117], v[162:165], v[58:61]
	v_mfma_f32_16x16x32_bf16 v[58:61], v[122:125], v[166:169], v[58:61]
	v_mfma_f32_16x16x32_bf16 v[42:45], v[114:117], v[170:173], v[42:45]
	v_mfma_f32_16x16x32_bf16 v[42:45], v[122:125], v[174:177], v[42:45]
	v_mfma_f32_16x16x32_bf16 v[46:49], v[98:101], v[170:173], v[46:49]
	v_mfma_f32_16x16x32_bf16 v[46:49], v[102:105], v[174:177], v[46:49]
	v_mfma_f32_16x16x32_bf16 v[30:33], v[98:101], v[178:181], v[30:33]
	v_mfma_f32_16x16x32_bf16 v[30:33], v[102:105], v[182:185], v[30:33]
	v_mfma_f32_16x16x32_bf16 v[26:29], v[114:117], v[178:181], v[26:29]
	v_mfma_f32_16x16x32_bf16 v[26:29], v[122:125], v[182:185], v[26:29]
	v_mfma_f32_16x16x32_bf16 v[10:13], v[114:117], v[186:189], v[10:13]
	v_mfma_f32_16x16x32_bf16 v[10:13], v[122:125], v[190:193], v[10:13]
	v_mfma_f32_16x16x32_bf16 v[14:17], v[98:101], v[186:189], v[14:17]
	v_mfma_f32_16x16x32_bf16 v[14:17], v[102:105], v[190:193], v[14:17]
	v_mfma_f32_16x16x32_bf16 v[54:57], v[130:133], v[162:165], v[54:57]
	v_mfma_f32_16x16x32_bf16 v[54:57], v[138:141], v[166:169], v[54:57]
	v_mfma_f32_16x16x32_bf16 v[50:53], v[146:149], v[162:165], v[50:53]
	v_mfma_f32_16x16x32_bf16 v[50:53], v[154:157], v[166:169], v[50:53]
	v_mfma_f32_16x16x32_bf16 v[34:37], v[146:149], v[170:173], v[34:37]
	v_mfma_f32_16x16x32_bf16 v[34:37], v[154:157], v[174:177], v[34:37]
	v_mfma_f32_16x16x32_bf16 v[38:41], v[130:133], v[170:173], v[38:41]
	v_mfma_f32_16x16x32_bf16 v[38:41], v[138:141], v[174:177], v[38:41]
	v_mfma_f32_16x16x32_bf16 v[22:25], v[130:133], v[178:181], v[22:25]
	v_mfma_f32_16x16x32_bf16 v[22:25], v[138:141], v[182:185], v[22:25]
	v_mfma_f32_16x16x32_bf16 v[18:21], v[146:149], v[178:181], v[18:21]
	v_mfma_f32_16x16x32_bf16 v[18:21], v[154:157], v[182:185], v[18:21]
	v_mfma_f32_16x16x32_bf16 v[2:5], v[146:149], v[186:189], v[2:5]
	v_mfma_f32_16x16x32_bf16 v[2:5], v[154:157], v[190:193], v[2:5]
	v_mfma_f32_16x16x32_bf16 v[6:9], v[130:133], v[186:189], v[6:9]
	v_mfma_f32_16x16x32_bf16 v[6:9], v[138:141], v[190:193], v[6:9]
	s_barrier
	s_add_u32 s6, s6, s98
	s_addc_u32 s7, s7, 0
	s_add_u32 s6, s6, s98
	s_addc_u32 s7, s7, 0
	s_add_u32 s67, s67, s98
	s_addc_u32 s85, s85, 0
	s_add_u32 s67, s67, s98
	s_addc_u32 s85, s85, 0
	s_cmp_ge_u32 vcc_lo, s69
	s_mov_b32 s8, vcc_lo
	s_cbranch_scc0 .LBB0_175
	s_branch .Lpeelx175
.LBB0_175:
	s_add_i32 vcc_lo, s8, 2
	s_add_u32 s4, s6, s98
	s_addc_u32 s5, s7, 0
	s_add_i32 vcc_hi, 0, 0x10000
	s_cmp_eq_u32 s13, s8
	s_cselect_b32 s9, s1, s5
	s_cselect_b32 s8, s0, s4
	s_cselect_b32 s5, s97, s85
	s_cselect_b32 s4, s96, s67
	s_add_i32 s84, 0, 0x14000
	v_add_u32_e32 v122, vcc_hi, v248
	v_add_u32_e32 v154, s84, v248
	ds_read_b128 v[98:101], v122
	ds_read_b128 v[102:105], v122 offset:1024
	ds_read_b128 v[114:117], v122 offset:2048
	ds_read_b128 v[122:125], v122 offset:3072
	ds_read_b128 v[130:133], v154
	ds_read_b128 v[138:141], v154 offset:1024
	ds_read_b128 v[146:149], v154 offset:2048
	ds_read_b128 v[154:157], v154 offset:3072
	v_lshl_add_u64 v[206:207], s[6:7], 0, v[200:201]
	s_add_i32 m0, s81, 0xc000
	ds_read_b128 v[162:165], v249
	ds_read_b128 v[166:169], v249 offset:1024
	ds_read_b128 v[170:173], v249 offset:2048
	ds_read_b128 v[174:177], v249 offset:3072
	ds_read_b128 v[178:181], v249 offset:4096
	ds_read_b128 v[182:185], v249 offset:5120
	ds_read_b128 v[186:189], v249 offset:6144
	ds_read_b128 v[190:193], v249 offset:7168
	global_load_lds_dwordx4 v[206:207], off
	v_lshl_add_u64 v[206:207], s[6:7], 0, v[210:211]
	s_add_i32 m0, s81, 0xe000
	s_nop 0
	global_load_lds_dwordx4 v[206:207], off
	s_waitcnt vmcnt(8)
	s_waitcnt lgkmcnt(0)
	s_barrier
; #define PG8_STAGE(bufoff, gbase, voff) do { _Pragma("unroll") for (int _i = 0; _i < 2; ++_i) \
;         __builtin_amdgcn_global_load_lds((const unsigned*)((const char*)(gbase) + (voff)[_i]), (PG8_LAS unsigned*)(lds + (bufoff) + ldsw + _i * 8192), 16, 0, 0); } while (0)
; #define PG8_LDA(dst, b, h) do { _Pragma("unroll") for (int m = 0; m < 4; ++m) _Pragma("unroll") for (int k = 0; k < 2; ++k) dst[m][k] = *(const PG8_LAS bf16x8*)(lds + PG8_SA(b, h) + aoff + m * 2048 + k * 1024); } while (0)
; #define PG8_LDB(dst, b, h) do { _Pragma("unroll") for (int n = 0; n < 2; ++n) _Pragma("unroll") for (int k = 0; k < 2; ++k) dst[n][k] = *(const PG8_LAS bf16x8*)(lds + PG8_SB(b, h) + boff + n * 2048 + k * 1024); } while (0)
; #define PG8_MMA(ai, bj, At, Bt) do { __builtin_amdgcn_s_setprio(1); _Pragma("unroll") for (int m = 0; m < 4; ++m) _Pragma("unroll") for (int n = 0; n < 2; ++n) _Pragma("unroll") for (int k = 0; k < 2; ++k) \
;         acc[ai][bj][m][n] = mma16<Epi::I8>(Bt[n][k], At[m][k], acc[ai][bj][m][n]); __builtin_amdgcn_s_setprio(0); } while (0)
; #define PG8_WAIT_V(n) asm volatile("s_waitcnt vmcnt(" #n ")" ::: "memory")
; #define PG8_WAIT_L(n) asm volatile("s_waitcnt lgkmcnt(" #n ")" ::: "memory")
; #define PG8_BAR __builtin_amdgcn_s_barrier()
; #define PG8_SCHED __builtin_amdgcn_sched_barrier(0)
; template <class Epi, class Sched, bool ALIGN_EPI = false, bool SP2 = false>
; __device__ __forceinline__ void gemm_phase(PG8_LAS unsigned char* lds, const Gemm g, const Sched& S, const Epi& E) {
;     ...
;             PG8_LDB(B0, 0, 0); PG8_LDB(B1, 0, 1); PG8_SCHED; PG8_LDA(At, 0, 0); PG8_STAGE(PG8_SA(1, 1), a1 + hstep, voffA);
;             PG8_WAIT_V(8); PG8_WAIT_L(0); PG8_BAR; PG8_MMA(0, 0, At, B0); PG8_MMA(0, 1, At, B1); PG8_BAR; PG8_SCHED;
;             PG8_LDA(At, 0, 1); PG8_STAGE(PG8_SB(0, 0), b2, voffB); PG8_STAGE(PG8_SB(0, 1), b2 + hstep, voffB); PG8_STAGE(PG8_SA(0, 0), a2, voffA);
;             PG8_WAIT_V(8); PG8_WAIT_L(0); PG8_BAR; PG8_MMA(1, 0, At, B0); PG8_MMA(1, 1, At, B1); PG8_BAR; PG8_SCHED;
	v_mfma_f32_16x16x32_bf16 v[158:161], v[98:101], v[162:165], v[158:161]
	v_mfma_f32_16x16x32_bf16 v[158:161], v[102:105], v[166:169], v[158:161]
	v_mfma_f32_16x16x32_bf16 v[150:153], v[114:117], v[162:165], v[150:153]
	v_mfma_f32_16x16x32_bf16 v[150:153], v[122:125], v[166:169], v[150:153]
	v_mfma_f32_16x16x32_bf16 v[118:121], v[114:117], v[170:173], v[118:121]
	v_mfma_f32_16x16x32_bf16 v[118:121], v[122:125], v[174:177], v[118:121]
	v_mfma_f32_16x16x32_bf16 v[126:129], v[98:101], v[170:173], v[126:129]
	v_mfma_f32_16x16x32_bf16 v[126:129], v[102:105], v[174:177], v[126:129]
	v_mfma_f32_16x16x32_bf16 v[94:97], v[98:101], v[178:181], v[94:97]
	v_mfma_f32_16x16x32_bf16 v[94:97], v[102:105], v[182:185], v[94:97]
	v_mfma_f32_16x16x32_bf16 v[90:93], v[114:117], v[178:181], v[90:93]
	v_mfma_f32_16x16x32_bf16 v[90:93], v[122:125], v[182:185], v[90:93]
	v_mfma_f32_16x16x32_bf16 v[74:77], v[114:117], v[186:189], v[74:77]
	v_mfma_f32_16x16x32_bf16 v[74:77], v[122:125], v[190:193], v[74:77]
	v_mfma_f32_16x16x32_bf16 v[78:81], v[98:101], v[186:189], v[78:81]
	v_mfma_f32_16x16x32_bf16 v[78:81], v[102:105], v[190:193], v[78:81]
	v_mfma_f32_16x16x32_bf16 v[142:145], v[130:133], v[162:165], v[142:145]
	v_mfma_f32_16x16x32_bf16 v[142:145], v[138:141], v[166:169], v[142:145]
	v_mfma_f32_16x16x32_bf16 v[134:137], v[146:149], v[162:165], v[134:137]
	v_mfma_f32_16x16x32_bf16 v[134:137], v[154:157], v[166:169], v[134:137]
	v_mfma_f32_16x16x32_bf16 v[106:109], v[146:149], v[170:173], v[106:109]
	v_mfma_f32_16x16x32_bf16 v[106:109], v[154:157], v[174:177], v[106:109]
	v_mfma_f32_16x16x32_bf16 v[110:113], v[130:133], v[170:173], v[110:113]
	v_mfma_f32_16x16x32_bf16 v[110:113], v[138:141], v[174:177], v[110:113]
	v_mfma_f32_16x16x32_bf16 v[86:89], v[130:133], v[178:181], v[86:89]
	v_mfma_f32_16x16x32_bf16 v[86:89], v[138:141], v[182:185], v[86:89]
	v_mfma_f32_16x16x32_bf16 v[82:85], v[146:149], v[178:181], v[82:85]
	v_mfma_f32_16x16x32_bf16 v[82:85], v[154:157], v[182:185], v[82:85]
	v_mfma_f32_16x16x32_bf16 v[66:69], v[146:149], v[186:189], v[66:69]
	v_mfma_f32_16x16x32_bf16 v[66:69], v[154:157], v[190:193], v[66:69]
	v_mfma_f32_16x16x32_bf16 v[70:73], v[130:133], v[186:189], v[70:73]
	v_mfma_f32_16x16x32_bf16 v[70:73], v[138:141], v[190:193], v[70:73]
	s_barrier
	s_add_i32 vcc_hi, vcc_hi, s80
	v_lshl_add_u64 v[206:207], s[4:5], 0, v[0:1]
	s_mov_b32 m0, vcc_hi
	ds_read_b128 v[162:165], v249 offset:16384
	ds_read_b128 v[166:169], v249 offset:17408
	ds_read_b128 v[170:173], v249 offset:18432
	ds_read_b128 v[174:177], v249 offset:19456
	ds_read_b128 v[178:181], v249 offset:20480
	ds_read_b128 v[182:185], v249 offset:21504
	ds_read_b128 v[186:189], v249 offset:22528
	ds_read_b128 v[190:193], v249 offset:23552
	global_load_lds_dwordx4 v[206:207], off
	s_add_i32 m0, vcc_hi, 0x2000
	v_lshl_add_u64 v[212:213], s[4:5], 0, v[198:199]
	s_add_u32 s4, s4, s100
	s_addc_u32 s5, s5, 0
	s_add_i32 s84, s84, s80
	global_load_lds_dwordx4 v[212:213], off
	v_lshl_add_u64 v[214:215], s[4:5], 0, v[0:1]
	s_mov_b32 m0, s84
	v_lshl_add_u64 v[216:217], s[4:5], 0, v[198:199]
	global_load_lds_dwordx4 v[214:215], off
	s_add_i32 m0, s84, 0x2000
	v_lshl_add_u64 v[218:219], s[8:9], 0, v[194:195]
	global_load_lds_dwordx4 v[216:217], off
	s_mov_b32 m0, s81
	v_lshl_add_u64 v[220:221], s[8:9], 0, v[196:197]
	global_load_lds_dwordx4 v[218:219], off
	s_mov_b32 m0, s70
	s_nop 0
	global_load_lds_dwordx4 v[220:221], off
	s_waitcnt vmcnt(8)
	s_waitcnt lgkmcnt(0)
	s_barrier
	v_mfma_f32_16x16x32_bf16 v[62:65], v[98:101], v[162:165], v[62:65]
	v_mfma_f32_16x16x32_bf16 v[62:65], v[102:105], v[166:169], v[62:65]
	v_mfma_f32_16x16x32_bf16 v[58:61], v[114:117], v[162:165], v[58:61]
	v_mfma_f32_16x16x32_bf16 v[58:61], v[122:125], v[166:169], v[58:61]
	v_mfma_f32_16x16x32_bf16 v[42:45], v[114:117], v[170:173], v[42:45]
	v_mfma_f32_16x16x32_bf16 v[42:45], v[122:125], v[174:177], v[42:45]
	v_mfma_f32_16x16x32_bf16 v[46:49], v[98:101], v[170:173], v[46:49]
	v_mfma_f32_16x16x32_bf16 v[46:49], v[102:105], v[174:177], v[46:49]
	v_mfma_f32_16x16x32_bf16 v[30:33], v[98:101], v[178:181], v[30:33]
	v_mfma_f32_16x16x32_bf16 v[30:33], v[102:105], v[182:185], v[30:33]
	v_mfma_f32_16x16x32_bf16 v[26:29], v[114:117], v[178:181], v[26:29]
	v_mfma_f32_16x16x32_bf16 v[26:29], v[122:125], v[182:185], v[26:29]
	v_mfma_f32_16x16x32_bf16 v[10:13], v[114:117], v[186:189], v[10:13]
	v_mfma_f32_16x16x32_bf16 v[10:13], v[122:125], v[190:193], v[10:13]
	v_mfma_f32_16x16x32_bf16 v[14:17], v[98:101], v[186:189], v[14:17]
	v_mfma_f32_16x16x32_bf16 v[14:17], v[102:105], v[190:193], v[14:17]
	v_mfma_f32_16x16x32_bf16 v[54:57], v[130:133], v[162:165], v[54:57]
	v_mfma_f32_16x16x32_bf16 v[54:57], v[138:141], v[166:169], v[54:57]
	v_mfma_f32_16x16x32_bf16 v[50:53], v[146:149], v[162:165], v[50:53]
	v_mfma_f32_16x16x32_bf16 v[50:53], v[154:157], v[166:169], v[50:53]
	v_mfma_f32_16x16x32_bf16 v[34:37], v[146:149], v[170:173], v[34:37]
	v_mfma_f32_16x16x32_bf16 v[34:37], v[154:157], v[174:177], v[34:37]
	v_mfma_f32_16x16x32_bf16 v[38:41], v[130:133], v[170:173], v[38:41]
	v_mfma_f32_16x16x32_bf16 v[38:41], v[138:141], v[174:177], v[38:41]
	v_mfma_f32_16x16x32_bf16 v[22:25], v[130:133], v[178:181], v[22:25]
	v_mfma_f32_16x16x32_bf16 v[22:25], v[138:141], v[182:185], v[22:25]
	v_mfma_f32_16x16x32_bf16 v[18:21], v[146:149], v[178:181], v[18:21]
	v_mfma_f32_16x16x32_bf16 v[18:21], v[154:157], v[182:185], v[18:21]
	v_mfma_f32_16x16x32_bf16 v[2:5], v[146:149], v[186:189], v[2:5]
	v_mfma_f32_16x16x32_bf16 v[2:5], v[154:157], v[190:193], v[2:5]
	v_mfma_f32_16x16x32_bf16 v[6:9], v[130:133], v[186:189], v[6:9]
	v_mfma_f32_16x16x32_bf16 v[6:9], v[138:141], v[190:193], v[6:9]
	s_barrier
; #define PG8_STAGE(bufoff, gbase, voff) do { _Pragma("unroll") for (int _i = 0; _i < 2; ++_i) \
;         __builtin_amdgcn_global_load_lds((const unsigned*)((const char*)(gbase) + (voff)[_i]), (PG8_LAS unsigned*)(lds + (bufoff) + ldsw + _i * 8192), 16, 0, 0); } while (0)
; #define PG8_LDA(dst, b, h) do { _Pragma("unroll") for (int m = 0; m < 4; ++m) _Pragma("unroll") for (int k = 0; k < 2; ++k) dst[m][k] = *(const PG8_LAS bf16x8*)(lds + PG8_SA(b, h) + aoff + m * 2048 + k * 1024); } while (0)
; #define PG8_LDB(dst, b, h) do { _Pragma("unroll") for (int n = 0; n < 2; ++n) _Pragma("unroll") for (int k = 0; k < 2; ++k) dst[n][k] = *(const PG8_LAS bf16x8*)(lds + PG8_SB(b, h) + boff + n * 2048 + k * 1024); } while (0)
; #define PG8_MMA(ai, bj, At, Bt) do { __builtin_amdgcn_s_setprio(1); _Pragma("unroll") for (int m = 0; m < 4; ++m) _Pragma("unroll") for (int n = 0; n < 2; ++n) _Pragma("unroll") for (int k = 0; k < 2; ++k) \
;         acc[ai][bj][m][n] = mma16<Epi::I8>(Bt[n][k], At[m][k], acc[ai][bj][m][n]); __builtin_amdgcn_s_setprio(0); } while (0)
; #define PG8_WAIT_V(n) asm volatile("s_waitcnt vmcnt(" #n ")" ::: "memory")
; #define PG8_WAIT_L(n) asm volatile("s_waitcnt lgkmcnt(" #n ")" ::: "memory")
; #define PG8_BAR __builtin_amdgcn_s_barrier()
; #define PG8_SCHED __builtin_amdgcn_sched_barrier(0)
; template <class Epi, class Sched, bool ALIGN_EPI = false, bool SP2 = false>
; __device__ __forceinline__ void gemm_phase(PG8_LAS unsigned char* lds, const Gemm g, const Sched& S, const Epi& E) {
;     ...
;             PG8_LDB(B0, 1, 0); PG8_LDB(B1, 1, 1); PG8_SCHED; PG8_LDA(At, 1, 0); PG8_STAGE(PG8_SA(0, 1), a2 + hstep, voffA);
;             PG8_WAIT_V(8); PG8_WAIT_L(0); PG8_BAR; PG8_MMA(0, 0, At, B0); PG8_MMA(0, 1, At, B1); PG8_BAR; PG8_SCHED;
;             PG8_LDA(At, 1, 1); PG8_STAGE(PG8_SB(1, 0), b3, voffB); PG8_STAGE(PG8_SB(1, 1), b3 + hstep, voffB); PG8_STAGE(PG8_SA(1, 0), a3, voffA);
;             PG8_WAIT_V(8); PG8_WAIT_L(0); PG8_BAR; PG8_MMA(1, 0, At, B0); PG8_MMA(1, 1, At, B1); PG8_BAR; PG8_SCHED;
	s_add_i32 s84, 0, 0x18000
	s_add_i32 vcc_hi, 0, 0x1c000
	v_add_u32_e32 v122, s84, v248
	v_add_u32_e32 v154, vcc_hi, v248
	ds_read_b128 v[98:101], v122
	ds_read_b128 v[102:105], v122 offset:1024
	ds_read_b128 v[114:117], v122 offset:2048
	ds_read_b128 v[122:125], v122 offset:3072
	ds_read_b128 v[130:133], v154
	ds_read_b128 v[138:141], v154 offset:1024
	ds_read_b128 v[146:149], v154 offset:2048
	ds_read_b128 v[154:157], v154 offset:3072
	s_add_u32 s4, s8, s100
	s_addc_u32 s5, s9, 0
	s_mov_b32 m0, s71
	v_lshl_add_u64 v[222:223], s[4:5], 0, v[194:195]
	ds_read_b128 v[162:165], v249 offset:32768
	ds_read_b128 v[166:169], v249 offset:33792
	ds_read_b128 v[170:173], v249 offset:34816
	ds_read_b128 v[174:177], v249 offset:35840
	ds_read_b128 v[178:181], v249 offset:36864
	ds_read_b128 v[182:185], v249 offset:37888
	ds_read_b128 v[186:189], v249 offset:38912
	ds_read_b128 v[190:193], v249 offset:39936
	global_load_lds_dwordx4 v[222:223], off
	v_lshl_add_u64 v[222:223], s[4:5], 0, v[196:197]
	s_mov_b32 m0, s12
	s_nop 0
	global_load_lds_dwordx4 v[222:223], off
	s_waitcnt vmcnt(8)
	s_waitcnt lgkmcnt(0)
	s_barrier
	v_mfma_f32_16x16x32_bf16 v[158:161], v[98:101], v[162:165], v[158:161]
	v_mfma_f32_16x16x32_bf16 v[158:161], v[102:105], v[166:169], v[158:161]
	v_mfma_f32_16x16x32_bf16 v[150:153], v[114:117], v[162:165], v[150:153]
	v_mfma_f32_16x16x32_bf16 v[150:153], v[122:125], v[166:169], v[150:153]
	v_mfma_f32_16x16x32_bf16 v[118:121], v[114:117], v[170:173], v[118:121]
	v_mfma_f32_16x16x32_bf16 v[118:121], v[122:125], v[174:177], v[118:121]
	v_mfma_f32_16x16x32_bf16 v[126:129], v[98:101], v[170:173], v[126:129]
	v_mfma_f32_16x16x32_bf16 v[126:129], v[102:105], v[174:177], v[126:129]
	v_mfma_f32_16x16x32_bf16 v[94:97], v[98:101], v[178:181], v[94:97]
	v_mfma_f32_16x16x32_bf16 v[94:97], v[102:105], v[182:185], v[94:97]
	v_mfma_f32_16x16x32_bf16 v[90:93], v[114:117], v[178:181], v[90:93]
	v_mfma_f32_16x16x32_bf16 v[90:93], v[122:125], v[182:185], v[90:93]
	v_mfma_f32_16x16x32_bf16 v[74:77], v[114:117], v[186:189], v[74:77]
	v_mfma_f32_16x16x32_bf16 v[74:77], v[122:125], v[190:193], v[74:77]
	v_mfma_f32_16x16x32_bf16 v[78:81], v[98:101], v[186:189], v[78:81]
	v_mfma_f32_16x16x32_bf16 v[78:81], v[102:105], v[190:193], v[78:81]
	v_mfma_f32_16x16x32_bf16 v[142:145], v[130:133], v[162:165], v[142:145]
	v_mfma_f32_16x16x32_bf16 v[142:145], v[138:141], v[166:169], v[142:145]
	v_mfma_f32_16x16x32_bf16 v[134:137], v[146:149], v[162:165], v[134:137]
	v_mfma_f32_16x16x32_bf16 v[134:137], v[154:157], v[166:169], v[134:137]
	v_mfma_f32_16x16x32_bf16 v[106:109], v[146:149], v[170:173], v[106:109]
	v_mfma_f32_16x16x32_bf16 v[106:109], v[154:157], v[174:177], v[106:109]
	v_mfma_f32_16x16x32_bf16 v[110:113], v[130:133], v[170:173], v[110:113]
	v_mfma_f32_16x16x32_bf16 v[110:113], v[138:141], v[174:177], v[110:113]
	v_mfma_f32_16x16x32_bf16 v[86:89], v[130:133], v[178:181], v[86:89]
	v_mfma_f32_16x16x32_bf16 v[86:89], v[138:141], v[182:185], v[86:89]
	v_mfma_f32_16x16x32_bf16 v[82:85], v[146:149], v[178:181], v[82:85]
	v_mfma_f32_16x16x32_bf16 v[82:85], v[154:157], v[182:185], v[82:85]
	v_mfma_f32_16x16x32_bf16 v[66:69], v[146:149], v[186:189], v[66:69]
	v_mfma_f32_16x16x32_bf16 v[66:69], v[154:157], v[190:193], v[66:69]
	v_mfma_f32_16x16x32_bf16 v[70:73], v[130:133], v[186:189], v[70:73]
	v_mfma_f32_16x16x32_bf16 v[70:73], v[138:141], v[190:193], v[70:73]
	s_barrier
	s_add_i32 s4, s84, s80
	v_lshl_add_u64 v[206:207], v[206:207], 0, s[98:99]
	s_mov_b32 m0, s4
	ds_read_b128 v[162:165], v249 offset:49152
	ds_read_b128 v[166:169], v249 offset:50176
	ds_read_b128 v[170:173], v249 offset:51200
	ds_read_b128 v[174:177], v249 offset:52224
	ds_read_b128 v[178:181], v249 offset:53248
	ds_read_b128 v[182:185], v249 offset:54272
	ds_read_b128 v[186:189], v249 offset:55296
	ds_read_b128 v[190:193], v249 offset:56320
	global_load_lds_dwordx4 v[206:207], off
	v_lshl_add_u64 v[206:207], v[212:213], 0, s[98:99]
	s_add_i32 m0, s4, 0x2000
	s_add_i32 s4, vcc_hi, s80
	global_load_lds_dwordx4 v[206:207], off
	v_lshl_add_u64 v[206:207], v[214:215], 0, s[98:99]
	s_mov_b32 m0, s4
	s_nop 0
	global_load_lds_dwordx4 v[206:207], off
	v_lshl_add_u64 v[206:207], v[216:217], 0, s[98:99]
	s_add_i32 m0, s4, 0x2000
	s_nop 0
	global_load_lds_dwordx4 v[206:207], off
	v_lshl_add_u64 v[206:207], v[218:219], 0, s[98:99]
	s_mov_b32 m0, s10
	s_nop 0
	global_load_lds_dwordx4 v[206:207], off
	v_lshl_add_u64 v[206:207], v[220:221], 0, s[98:99]
	s_mov_b32 m0, s11
	s_nop 0
	global_load_lds_dwordx4 v[206:207], off
	s_waitcnt vmcnt(8)
	s_waitcnt lgkmcnt(0)
	s_barrier
	v_mfma_f32_16x16x32_bf16 v[62:65], v[98:101], v[162:165], v[62:65]
	v_mfma_f32_16x16x32_bf16 v[62:65], v[102:105], v[166:169], v[62:65]
	v_mfma_f32_16x16x32_bf16 v[58:61], v[114:117], v[162:165], v[58:61]
	v_mfma_f32_16x16x32_bf16 v[58:61], v[122:125], v[166:169], v[58:61]
	v_mfma_f32_16x16x32_bf16 v[42:45], v[114:117], v[170:173], v[42:45]
	v_mfma_f32_16x16x32_bf16 v[42:45], v[122:125], v[174:177], v[42:45]
	v_mfma_f32_16x16x32_bf16 v[46:49], v[98:101], v[170:173], v[46:49]
	v_mfma_f32_16x16x32_bf16 v[46:49], v[102:105], v[174:177], v[46:49]
	v_mfma_f32_16x16x32_bf16 v[30:33], v[98:101], v[178:181], v[30:33]
	v_mfma_f32_16x16x32_bf16 v[30:33], v[102:105], v[182:185], v[30:33]
	v_mfma_f32_16x16x32_bf16 v[26:29], v[114:117], v[178:181], v[26:29]
	v_mfma_f32_16x16x32_bf16 v[26:29], v[122:125], v[182:185], v[26:29]
	v_mfma_f32_16x16x32_bf16 v[10:13], v[114:117], v[186:189], v[10:13]
	v_mfma_f32_16x16x32_bf16 v[10:13], v[122:125], v[190:193], v[10:13]
	v_mfma_f32_16x16x32_bf16 v[14:17], v[98:101], v[186:189], v[14:17]
	v_mfma_f32_16x16x32_bf16 v[14:17], v[102:105], v[190:193], v[14:17]
	v_mfma_f32_16x16x32_bf16 v[54:57], v[130:133], v[162:165], v[54:57]
	v_mfma_f32_16x16x32_bf16 v[54:57], v[138:141], v[166:169], v[54:57]
	v_mfma_f32_16x16x32_bf16 v[50:53], v[146:149], v[162:165], v[50:53]
	v_mfma_f32_16x16x32_bf16 v[50:53], v[154:157], v[166:169], v[50:53]
	v_mfma_f32_16x16x32_bf16 v[34:37], v[146:149], v[170:173], v[34:37]
	v_mfma_f32_16x16x32_bf16 v[34:37], v[154:157], v[174:177], v[34:37]
	v_mfma_f32_16x16x32_bf16 v[38:41], v[130:133], v[170:173], v[38:41]
	v_mfma_f32_16x16x32_bf16 v[38:41], v[138:141], v[174:177], v[38:41]
	v_mfma_f32_16x16x32_bf16 v[22:25], v[130:133], v[178:181], v[22:25]
	v_mfma_f32_16x16x32_bf16 v[22:25], v[138:141], v[182:185], v[22:25]
	v_mfma_f32_16x16x32_bf16 v[18:21], v[146:149], v[178:181], v[18:21]
	v_mfma_f32_16x16x32_bf16 v[18:21], v[154:157], v[182:185], v[18:21]
	v_mfma_f32_16x16x32_bf16 v[2:5], v[146:149], v[186:189], v[2:5]
	v_mfma_f32_16x16x32_bf16 v[2:5], v[154:157], v[190:193], v[2:5]
	v_mfma_f32_16x16x32_bf16 v[6:9], v[130:133], v[186:189], v[6:9]
	v_mfma_f32_16x16x32_bf16 v[6:9], v[138:141], v[190:193], v[6:9]
	s_barrier
	s_add_u32 s6, s6, s98
	s_addc_u32 s7, s7, 0
	s_add_u32 s6, s6, s98
	s_addc_u32 s7, s7, 0
	s_add_u32 s67, s67, s98
	s_addc_u32 s85, s85, 0
	s_add_u32 s67, s67, s98
	s_addc_u32 s85, s85, 0
	s_cmp_ge_u32 vcc_lo, s69
	s_mov_b32 s8, vcc_lo
	s_cbranch_scc0 .LBB0_175

; #define PG8_STAGE(bufoff, gbase, voff) do { _Pragma("unroll") for (int _i = 0; _i < 2; ++_i) \
;         __builtin_amdgcn_global_load_lds((const unsigned*)((const char*)(gbase) + (voff)[_i]), (PG8_LAS unsigned*)(lds + (bufoff) + ldsw + _i * 8192), 16, 0, 0); } while (0)
; #define PG8_LDA(dst, b, h) do { _Pragma("unroll") for (int m = 0; m < 4; ++m) _Pragma("unroll") for (int k = 0; k < 2; ++k) dst[m][k] = *(const PG8_LAS bf16x8*)(lds + PG8_SA(b, h) + aoff + m * 2048 + k * 1024); } while (0)
; #define PG8_LDB(dst, b, h) do { _Pragma("unroll") for (int n = 0; n < 2; ++n) _Pragma("unroll") for (int k = 0; k < 2; ++k) dst[n][k] = *(const PG8_LAS bf16x8*)(lds + PG8_SB(b, h) + boff + n * 2048 + k * 1024); } while (0)
; #define PG8_MMA(ai, bj, At, Bt) do { __builtin_amdgcn_s_setprio(1); _Pragma("unroll") for (int m = 0; m < 4; ++m) _Pragma("unroll") for (int n = 0; n < 2; ++n) _Pragma("unroll") for (int k = 0; k < 2; ++k) \
;         acc[ai][bj][m][n] = mma16<Epi::I8>(Bt[n][k], At[m][k], acc[ai][bj][m][n]); __builtin_amdgcn_s_setprio(0); } while (0)
; #define PG8_WAIT_V(n) asm volatile("s_waitcnt vmcnt(" #n ")" ::: "memory")
; #define PG8_WAIT_L(n) asm volatile("s_waitcnt lgkmcnt(" #n ")" ::: "memory")
; #define PG8_BAR __builtin_amdgcn_s_barrier()
; template <class Epi, class Sched, bool ALIGN_EPI = false, bool SP2 = false>
; __device__ __forceinline__ void gemm_phase(PG8_LAS unsigned char* lds, const Gemm g, const Sched& S, const Epi& E) {
;     ...
;             const bool last = (t == nt - 2);
;             const char* a1 = cA + (size_t)(t + 1) * kstep;
;             const char* a2 = last ? nA : cA + (size_t)(t + 2) * kstep; const char* b2 = last ? nB : cB + (size_t)(t + 2) * kstep;
;             const char* a3 = a2 + kstep; const char* b3 = b2 + kstep;
;             if (last && has_next) S.a_ready(nxt);
;             if constexpr (SP2) {
;             PG8_LDB(B0, 0, 0); PG8_LDB(B1, 0, 1); PG8_SCHED; PG8_LDA(At, 0, 0); PG8_STAGE(PG8_SA(1, 1), a1 + hstep, voffA);
;             PG8_WAIT_V(8); PG8_WAIT_L(0); PG8_BAR; PG8_MMA(0, 0, At, B0); PG8_MMA(0, 1, At, B1); PG8_BAR; PG8_SCHED;
;             PG8_LDA(At, 0, 1); PG8_STAGE(PG8_SB(0, 0), b2, voffB); PG8_STAGE(PG8_SB(0, 1), b2 + hstep, voffB); PG8_STAGE(PG8_SA(0, 0), a2, voffA);
;             PG8_WAIT_V(8); PG8_WAIT_L(0); PG8_BAR; PG8_MMA(1, 0, At, B0); PG8_MMA(1, 1, At, B1); PG8_BAR; PG8_SCHED;
.Lpeel291:
	s_add_u32 s84, s8, 0x100
	s_addc_u32 s85, s9, 0
	s_add_i32 s66, 0, 0x10000
	s_cmp_eq_u32 s10, 12
	s_cselect_b32 vcc_hi, s5, s85
	s_cselect_b32 vcc_lo, s7, s84
	s_cselect_b32 s97, s11, s68
	s_cselect_b32 s96, s67, s69
	s_add_i32 s70, 0, 0x14000
	v_add_u32_e32 v110, s66, v175
	v_add_u32_e32 v168, s70, v175
	s_waitcnt vmcnt(0)
	ds_read_b128 v[66:69], v110
	ds_read_b128 v[70:73], v110 offset:1024
	ds_read_b128 v[106:109], v110 offset:2048
	ds_read_b128 v[110:113], v110 offset:3072
	ds_read_b128 v[114:117], v168
	ds_read_b128 v[118:121], v168 offset:1024
	ds_read_b128 v[126:129], v168 offset:2048
	ds_read_b128 v[178:181], v168 offset:3072
	v_lshl_add_u64 v[168:169], s[8:9], 0, v[164:165]
	s_add_i32 m0, s1, 0xc000
	ds_read_b128 v[182:185], v177
	ds_read_b128 v[186:189], v177 offset:1024
	ds_read_b128 v[190:193], v177 offset:2048
	ds_read_b128 v[194:197], v177 offset:3072
	ds_read_b128 v[198:201], v177 offset:4096
	ds_read_b128 v[210:213], v177 offset:5120
	ds_read_b128 v[214:217], v177 offset:6144
	ds_read_b128 v[218:221], v177 offset:7168
	global_load_lds_dwordx4 v[168:169], off
	v_lshl_add_u64 v[168:169], s[8:9], 0, v[166:167]
	s_add_i32 m0, s1, 0xe000
	s_nop 0
	global_load_lds_dwordx4 v[168:169], off
	s_waitcnt vmcnt(8)
	s_waitcnt lgkmcnt(0)
	s_barrier
	v_mfma_i32_16x16x64_i8 v[154:157], v[66:69], v[182:185], 0
	v_mfma_i32_16x16x64_i8 v[154:157], v[70:73], v[186:189], v[154:157]
	v_mfma_i32_16x16x64_i8 v[146:149], v[110:113], v[186:189], 0
	v_mfma_i32_16x16x64_i8 v[146:149], v[106:109], v[182:185], v[146:149]
	v_mfma_i32_16x16x64_i8 v[138:141], v[106:109], v[190:193], 0
	v_mfma_i32_16x16x64_i8 v[138:141], v[110:113], v[194:197], v[138:141]
	v_mfma_i32_16x16x64_i8 v[150:153], v[70:73], v[194:197], 0
	v_mfma_i32_16x16x64_i8 v[150:153], v[66:69], v[190:193], v[150:153]
	v_mfma_i32_16x16x64_i8 v[142:145], v[66:69], v[198:201], 0
	v_mfma_i32_16x16x64_i8 v[142:145], v[70:73], v[210:213], v[142:145]
	v_mfma_i32_16x16x64_i8 v[130:133], v[110:113], v[210:213], 0
	v_mfma_i32_16x16x64_i8 v[130:133], v[106:109], v[198:201], v[130:133]
	v_mfma_i32_16x16x64_i8 v[122:125], v[106:109], v[214:217], 0
	v_mfma_i32_16x16x64_i8 v[122:125], v[110:113], v[218:221], v[122:125]
	v_mfma_i32_16x16x64_i8 v[134:137], v[70:73], v[218:221], 0
	v_mfma_i32_16x16x64_i8 v[134:137], v[66:69], v[214:217], v[134:137]
	v_mfma_i32_16x16x64_i8 v[74:77], v[126:129], v[214:217], 0
	v_mfma_i32_16x16x64_i8 v[74:77], v[178:181], v[218:221], v[74:77]
	v_mfma_i32_16x16x64_i8 v[94:97], v[178:181], v[186:189], 0
	v_mfma_i32_16x16x64_i8 v[94:97], v[126:129], v[182:185], v[94:97]
	v_mfma_i32_16x16x64_i8 v[102:105], v[114:117], v[182:185], 0
	v_mfma_i32_16x16x64_i8 v[102:105], v[118:121], v[186:189], v[102:105]
	v_mfma_i32_16x16x64_i8 v[98:101], v[118:121], v[194:197], 0
	v_mfma_i32_16x16x64_i8 v[98:101], v[114:117], v[190:193], v[98:101]
	v_mfma_i32_16x16x64_i8 v[86:89], v[126:129], v[190:193], 0
	v_mfma_i32_16x16x64_i8 v[86:89], v[178:181], v[194:197], v[86:89]
	v_mfma_i32_16x16x64_i8 v[78:81], v[178:181], v[210:213], 0
	v_mfma_i32_16x16x64_i8 v[78:81], v[126:129], v[198:201], v[78:81]
	v_mfma_i32_16x16x64_i8 v[90:93], v[114:117], v[198:201], 0
	v_mfma_i32_16x16x64_i8 v[90:93], v[118:121], v[210:213], v[90:93]
	v_mfma_i32_16x16x64_i8 v[82:85], v[118:121], v[218:221], 0
	v_mfma_i32_16x16x64_i8 v[82:85], v[114:117], v[214:217], v[82:85]
	s_barrier
	s_add_i32 s8, s66, s81
	v_lshl_add_u64 v[168:169], s[96:97], 0, v[0:1]
	s_mov_b32 m0, s8
	ds_read_b128 v[182:185], v177 offset:16384
	ds_read_b128 v[186:189], v177 offset:17408
	ds_read_b128 v[190:193], v177 offset:18432
	ds_read_b128 v[194:197], v177 offset:19456
	ds_read_b128 v[198:201], v177 offset:20480
	ds_read_b128 v[210:213], v177 offset:21504
	ds_read_b128 v[214:217], v177 offset:22528
	ds_read_b128 v[218:221], v177 offset:23552
	global_load_lds_dwordx4 v[168:169], off
	s_add_i32 m0, s8, 0x2000
	s_add_u32 s8, s96, 0x40000
	v_lshl_add_u64 v[206:207], s[96:97], 0, v[158:159]
	s_addc_u32 s9, s97, 0
	s_add_i32 s66, s70, s81
	global_load_lds_dwordx4 v[206:207], off
	v_lshl_add_u64 v[222:223], s[8:9], 0, v[0:1]
	s_mov_b32 m0, s66
	v_lshl_add_u64 v[224:225], vcc, 0, v[160:161]
	global_load_lds_dwordx4 v[222:223], off
	v_lshl_add_u64 v[222:223], s[8:9], 0, v[158:159]
	s_add_i32 m0, s66, 0x2000
	s_nop 0
	global_load_lds_dwordx4 v[222:223], off
	v_lshl_add_u64 v[222:223], vcc, 0, v[162:163]
	s_mov_b32 m0, s1
	s_nop 0
	global_load_lds_dwordx4 v[222:223], off
	s_mov_b32 m0, s58
	s_nop 0
	global_load_lds_dwordx4 v[224:225], off
	s_waitcnt vmcnt(8)
	s_waitcnt lgkmcnt(0)
	s_barrier
	v_mfma_i32_16x16x64_i8 v[62:65], v[66:69], v[182:185], 0
	v_mfma_i32_16x16x64_i8 v[62:65], v[70:73], v[186:189], v[62:65]
	v_mfma_i32_16x16x64_i8 v[54:57], v[110:113], v[186:189], 0
	v_mfma_i32_16x16x64_i8 v[54:57], v[106:109], v[182:185], v[54:57]
	v_mfma_i32_16x16x64_i8 v[46:49], v[106:109], v[190:193], 0
	v_mfma_i32_16x16x64_i8 v[46:49], v[110:113], v[194:197], v[46:49]
	v_mfma_i32_16x16x64_i8 v[58:61], v[70:73], v[194:197], 0
	v_mfma_i32_16x16x64_i8 v[58:61], v[66:69], v[190:193], v[58:61]
	v_mfma_i32_16x16x64_i8 v[50:53], v[66:69], v[198:201], 0
	v_mfma_i32_16x16x64_i8 v[50:53], v[70:73], v[210:213], v[50:53]
	v_mfma_i32_16x16x64_i8 v[38:41], v[110:113], v[210:213], 0
	v_mfma_i32_16x16x64_i8 v[38:41], v[106:109], v[198:201], v[38:41]
	v_mfma_i32_16x16x64_i8 v[34:37], v[106:109], v[214:217], 0
	v_mfma_i32_16x16x64_i8 v[34:37], v[110:113], v[218:221], v[34:37]
	v_mfma_i32_16x16x64_i8 v[42:45], v[70:73], v[218:221], 0
	v_mfma_i32_16x16x64_i8 v[42:45], v[66:69], v[214:217], v[42:45]
	v_mfma_i32_16x16x64_i8 v[2:5], v[126:129], v[214:217], 0
	v_mfma_i32_16x16x64_i8 v[2:5], v[178:181], v[218:221], v[2:5]
	v_mfma_i32_16x16x64_i8 v[22:25], v[178:181], v[186:189], 0
	v_mfma_i32_16x16x64_i8 v[22:25], v[126:129], v[182:185], v[22:25]
	v_mfma_i32_16x16x64_i8 v[30:33], v[114:117], v[182:185], 0
	v_mfma_i32_16x16x64_i8 v[30:33], v[118:121], v[186:189], v[30:33]
	v_mfma_i32_16x16x64_i8 v[26:29], v[118:121], v[194:197], 0
	v_mfma_i32_16x16x64_i8 v[26:29], v[114:117], v[190:193], v[26:29]
	v_mfma_i32_16x16x64_i8 v[14:17], v[126:129], v[190:193], 0
	v_mfma_i32_16x16x64_i8 v[14:17], v[178:181], v[194:197], v[14:17]
	v_mfma_i32_16x16x64_i8 v[6:9], v[178:181], v[210:213], 0
	v_mfma_i32_16x16x64_i8 v[6:9], v[126:129], v[198:201], v[6:9]
	v_mfma_i32_16x16x64_i8 v[18:21], v[114:117], v[198:201], 0
	v_mfma_i32_16x16x64_i8 v[18:21], v[118:121], v[210:213], v[18:21]
	v_mfma_i32_16x16x64_i8 v[10:13], v[118:121], v[218:221], 0
	v_mfma_i32_16x16x64_i8 v[10:13], v[114:117], v[214:217], v[10:13]
	s_barrier
; #define PG8_STAGE(bufoff, gbase, voff) do { _Pragma("unroll") for (int _i = 0; _i < 2; ++_i) \
;         __builtin_amdgcn_global_load_lds((const unsigned*)((const char*)(gbase) + (voff)[_i]), (PG8_LAS unsigned*)(lds + (bufoff) + ldsw + _i * 8192), 16, 0, 0); } while (0)
; #define PG8_LDA(dst, b, h) do { _Pragma("unroll") for (int m = 0; m < 4; ++m) _Pragma("unroll") for (int k = 0; k < 2; ++k) dst[m][k] = *(const PG8_LAS bf16x8*)(lds + PG8_SA(b, h) + aoff + m * 2048 + k * 1024); } while (0)
; #define PG8_LDB(dst, b, h) do { _Pragma("unroll") for (int n = 0; n < 2; ++n) _Pragma("unroll") for (int k = 0; k < 2; ++k) dst[n][k] = *(const PG8_LAS bf16x8*)(lds + PG8_SB(b, h) + boff + n * 2048 + k * 1024); } while (0)
; #define PG8_MMA(ai, bj, At, Bt) do { __builtin_amdgcn_s_setprio(1); _Pragma("unroll") for (int m = 0; m < 4; ++m) _Pragma("unroll") for (int n = 0; n < 2; ++n) _Pragma("unroll") for (int k = 0; k < 2; ++k) \
;         acc[ai][bj][m][n] = mma16<Epi::I8>(Bt[n][k], At[m][k], acc[ai][bj][m][n]); __builtin_amdgcn_s_setprio(0); } while (0)
; #define PG8_WAIT_V(n) asm volatile("s_waitcnt vmcnt(" #n ")" ::: "memory")
; #define PG8_WAIT_L(n) asm volatile("s_waitcnt lgkmcnt(" #n ")" ::: "memory")
; #define PG8_BAR __builtin_amdgcn_s_barrier()
; #define PG8_SCHED __builtin_amdgcn_sched_barrier(0)
; template <class Epi, class Sched, bool ALIGN_EPI = false, bool SP2 = false>
; __device__ __forceinline__ void gemm_phase(PG8_LAS unsigned char* lds, const Gemm g, const Sched& S, const Epi& E) {
;     ...
;             PG8_LDB(B0, 1, 0); PG8_LDB(B1, 1, 1); PG8_SCHED; PG8_LDA(At, 1, 0); PG8_STAGE(PG8_SA(0, 1), a2 + hstep, voffA);
;             PG8_WAIT_V(8); PG8_WAIT_L(0); PG8_BAR; PG8_MMA(0, 0, At, B0); PG8_MMA(0, 1, At, B1); PG8_BAR; PG8_SCHED;
;             PG8_LDA(At, 1, 1); PG8_STAGE(PG8_SB(1, 0), b3, voffB); PG8_STAGE(PG8_SB(1, 1), b3 + hstep, voffB); PG8_STAGE(PG8_SA(1, 0), a3, voffA);
;             PG8_WAIT_V(8); PG8_WAIT_L(0); PG8_BAR; PG8_MMA(1, 0, At, B0); PG8_MMA(1, 1, At, B1); PG8_BAR; PG8_SCHED;
	s_add_i32 s66, 0, 0x18000
	s_add_i32 s70, 0, 0x1c000
	v_add_u32_e32 v110, s66, v175
	v_add_u32_e32 v170, s70, v175
	ds_read_b128 v[66:69], v110
	ds_read_b128 v[70:73], v110 offset:1024
	ds_read_b128 v[106:109], v110 offset:2048
	ds_read_b128 v[110:113], v110 offset:3072
	ds_read_b128 v[114:117], v170
	ds_read_b128 v[118:121], v170 offset:1024
	ds_read_b128 v[126:129], v170 offset:2048
	ds_read_b128 v[178:181], v170 offset:3072
	s_add_u32 s8, vcc_lo, 0x40000
	s_addc_u32 s9, vcc_hi, 0
	s_mov_b32 m0, s80
	v_lshl_add_u64 v[226:227], s[8:9], 0, v[162:163]
	ds_read_b128 v[182:185], v177 offset:32768
	ds_read_b128 v[186:189], v177 offset:33792
	ds_read_b128 v[190:193], v177 offset:34816
	ds_read_b128 v[194:197], v177 offset:35840
	ds_read_b128 v[198:201], v177 offset:36864
	ds_read_b128 v[210:213], v177 offset:37888
	ds_read_b128 v[214:217], v177 offset:38912
	ds_read_b128 v[218:221], v177 offset:39936
	global_load_lds_dwordx4 v[226:227], off
	v_lshl_add_u64 v[226:227], s[8:9], 0, v[160:161]
	s_mov_b32 m0, s0
	s_nop 0
	global_load_lds_dwordx4 v[226:227], off
	s_waitcnt vmcnt(8)
	s_waitcnt lgkmcnt(0)
	s_barrier
	v_mfma_i32_16x16x64_i8 v[154:157], v[66:69], v[182:185], v[154:157]
	v_mfma_i32_16x16x64_i8 v[154:157], v[70:73], v[186:189], v[154:157]
	v_mfma_i32_16x16x64_i8 v[146:149], v[110:113], v[186:189], v[146:149]
	v_mfma_i32_16x16x64_i8 v[146:149], v[106:109], v[182:185], v[146:149]
	v_mfma_i32_16x16x64_i8 v[138:141], v[106:109], v[190:193], v[138:141]
	v_mfma_i32_16x16x64_i8 v[138:141], v[110:113], v[194:197], v[138:141]
	v_mfma_i32_16x16x64_i8 v[150:153], v[70:73], v[194:197], v[150:153]
	v_mfma_i32_16x16x64_i8 v[150:153], v[66:69], v[190:193], v[150:153]
	v_mfma_i32_16x16x64_i8 v[142:145], v[66:69], v[198:201], v[142:145]
	v_mfma_i32_16x16x64_i8 v[142:145], v[70:73], v[210:213], v[142:145]
	v_mfma_i32_16x16x64_i8 v[130:133], v[110:113], v[210:213], v[130:133]
	v_mfma_i32_16x16x64_i8 v[130:133], v[106:109], v[198:201], v[130:133]
	v_mfma_i32_16x16x64_i8 v[122:125], v[106:109], v[214:217], v[122:125]
	v_mfma_i32_16x16x64_i8 v[122:125], v[110:113], v[218:221], v[122:125]
	v_mfma_i32_16x16x64_i8 v[134:137], v[70:73], v[218:221], v[134:137]
	v_mfma_i32_16x16x64_i8 v[134:137], v[66:69], v[214:217], v[134:137]
	v_mfma_i32_16x16x64_i8 v[74:77], v[126:129], v[214:217], v[74:77]
	v_mfma_i32_16x16x64_i8 v[74:77], v[178:181], v[218:221], v[74:77]
	v_mfma_i32_16x16x64_i8 v[94:97], v[178:181], v[186:189], v[94:97]
	v_mfma_i32_16x16x64_i8 v[94:97], v[126:129], v[182:185], v[94:97]
	v_mfma_i32_16x16x64_i8 v[102:105], v[114:117], v[182:185], v[102:105]
	v_mfma_i32_16x16x64_i8 v[102:105], v[118:121], v[186:189], v[102:105]
	v_mfma_i32_16x16x64_i8 v[98:101], v[118:121], v[194:197], v[98:101]
	v_mfma_i32_16x16x64_i8 v[98:101], v[114:117], v[190:193], v[98:101]
	v_mfma_i32_16x16x64_i8 v[86:89], v[126:129], v[190:193], v[86:89]
	v_mfma_i32_16x16x64_i8 v[86:89], v[178:181], v[194:197], v[86:89]
	v_mfma_i32_16x16x64_i8 v[78:81], v[178:181], v[210:213], v[78:81]
	v_mfma_i32_16x16x64_i8 v[78:81], v[126:129], v[198:201], v[78:81]
	v_mfma_i32_16x16x64_i8 v[90:93], v[114:117], v[198:201], v[90:93]
	v_mfma_i32_16x16x64_i8 v[90:93], v[118:121], v[210:213], v[90:93]
	v_mfma_i32_16x16x64_i8 v[82:85], v[118:121], v[218:221], v[82:85]
	v_mfma_i32_16x16x64_i8 v[82:85], v[114:117], v[214:217], v[82:85]
	s_barrier
	s_add_i32 s8, s66, s81
	v_lshl_add_u64 v[168:169], v[168:169], 0, s[92:93]
	s_mov_b32 m0, s8
	ds_read_b128 v[182:185], v177 offset:49152
	ds_read_b128 v[186:189], v177 offset:50176
	ds_read_b128 v[190:193], v177 offset:51200
	ds_read_b128 v[194:197], v177 offset:52224
	ds_read_b128 v[198:201], v177 offset:53248
	ds_read_b128 v[210:213], v177 offset:54272
	ds_read_b128 v[214:217], v177 offset:55296
	ds_read_b128 v[218:221], v177 offset:56320
	global_load_lds_dwordx4 v[168:169], off
	s_add_i32 m0, s8, 0x2000
	s_add_u32 s8, s96, 0x40080
	v_lshl_add_u64 v[168:169], v[206:207], 0, s[92:93]
	s_addc_u32 s9, s97, 0
	s_add_i32 s66, s70, s81
	global_load_lds_dwordx4 v[168:169], off
	v_lshl_add_u64 v[168:169], s[8:9], 0, v[0:1]
	s_mov_b32 m0, s66
	s_nop 0
	global_load_lds_dwordx4 v[168:169], off
	v_lshl_add_u64 v[168:169], s[8:9], 0, v[158:159]
	s_add_i32 m0, s66, 0x2000
	s_nop 0
	global_load_lds_dwordx4 v[168:169], off
	v_lshl_add_u64 v[168:169], v[222:223], 0, s[92:93]
	s_mov_b32 m0, s13
	s_nop 0
	global_load_lds_dwordx4 v[168:169], off
	v_lshl_add_u64 v[168:169], v[224:225], 0, s[92:93]
	s_mov_b32 m0, s12
	s_nop 0
	global_load_lds_dwordx4 v[168:169], off
	s_waitcnt vmcnt(8)
	s_waitcnt lgkmcnt(0)
	s_barrier
	v_mfma_i32_16x16x64_i8 v[62:65], v[66:69], v[182:185], v[62:65]
	v_mfma_i32_16x16x64_i8 v[62:65], v[70:73], v[186:189], v[62:65]
	v_mfma_i32_16x16x64_i8 v[54:57], v[110:113], v[186:189], v[54:57]
	v_mfma_i32_16x16x64_i8 v[54:57], v[106:109], v[182:185], v[54:57]
	v_mfma_i32_16x16x64_i8 v[46:49], v[106:109], v[190:193], v[46:49]
	v_mfma_i32_16x16x64_i8 v[46:49], v[110:113], v[194:197], v[46:49]
	v_mfma_i32_16x16x64_i8 v[58:61], v[70:73], v[194:197], v[58:61]
	v_mfma_i32_16x16x64_i8 v[58:61], v[66:69], v[190:193], v[58:61]
	v_mfma_i32_16x16x64_i8 v[50:53], v[66:69], v[198:201], v[50:53]
	v_mfma_i32_16x16x64_i8 v[50:53], v[70:73], v[210:213], v[50:53]
	v_mfma_i32_16x16x64_i8 v[38:41], v[110:113], v[210:213], v[38:41]
	v_mfma_i32_16x16x64_i8 v[38:41], v[106:109], v[198:201], v[38:41]
	v_mfma_i32_16x16x64_i8 v[34:37], v[106:109], v[214:217], v[34:37]
	v_mfma_i32_16x16x64_i8 v[34:37], v[110:113], v[218:221], v[34:37]
	v_mfma_i32_16x16x64_i8 v[42:45], v[70:73], v[218:221], v[42:45]
	v_mfma_i32_16x16x64_i8 v[42:45], v[66:69], v[214:217], v[42:45]
	v_mfma_i32_16x16x64_i8 v[2:5], v[126:129], v[214:217], v[2:5]
	v_mfma_i32_16x16x64_i8 v[2:5], v[178:181], v[218:221], v[2:5]
	v_mfma_i32_16x16x64_i8 v[22:25], v[178:181], v[186:189], v[22:25]
	v_mfma_i32_16x16x64_i8 v[22:25], v[126:129], v[182:185], v[22:25]
	v_mfma_i32_16x16x64_i8 v[30:33], v[114:117], v[182:185], v[30:33]
	v_mfma_i32_16x16x64_i8 v[30:33], v[118:121], v[186:189], v[30:33]
	v_mfma_i32_16x16x64_i8 v[26:29], v[118:121], v[194:197], v[26:29]
	v_mfma_i32_16x16x64_i8 v[26:29], v[114:117], v[190:193], v[26:29]
	v_mfma_i32_16x16x64_i8 v[14:17], v[126:129], v[190:193], v[14:17]
	v_mfma_i32_16x16x64_i8 v[14:17], v[178:181], v[194:197], v[14:17]
	v_mfma_i32_16x16x64_i8 v[6:9], v[178:181], v[210:213], v[6:9]
	v_mfma_i32_16x16x64_i8 v[6:9], v[126:129], v[198:201], v[6:9]
	v_mfma_i32_16x16x64_i8 v[18:21], v[114:117], v[198:201], v[18:21]
	v_mfma_i32_16x16x64_i8 v[18:21], v[118:121], v[210:213], v[18:21]
	v_mfma_i32_16x16x64_i8 v[10:13], v[118:121], v[218:221], v[10:13]
	v_mfma_i32_16x16x64_i8 v[10:13], v[114:117], v[214:217], v[10:13]
	s_barrier
	s_add_i32 s10, s10, 2
	s_add_u32 s69, s69, 0x100
	s_addc_u32 s68, s68, 0
	s_cmp_gt_u32 s10, 13
	s_mov_b64 s[8:9], s[84:85]
	s_cbranch_scc0 .LBB0_291
	s_branch .Lpeelx291
; #define PG8_STAGE(bufoff, gbase, voff) do { _Pragma("unroll") for (int _i = 0; _i < 2; ++_i) \
;         __builtin_amdgcn_global_load_lds((const unsigned*)((const char*)(gbase) + (voff)[_i]), (PG8_LAS unsigned*)(lds + (bufoff) + ldsw + _i * 8192), 16, 0, 0); } while (0)
; #define PG8_LDA(dst, b, h) do { _Pragma("unroll") for (int m = 0; m < 4; ++m) _Pragma("unroll") for (int k = 0; k < 2; ++k) dst[m][k] = *(const PG8_LAS bf16x8*)(lds + PG8_SA(b, h) + aoff + m * 2048 + k * 1024); } while (0)
; #define PG8_LDB(dst, b, h) do { _Pragma("unroll") for (int n = 0; n < 2; ++n) _Pragma("unroll") for (int k = 0; k < 2; ++k) dst[n][k] = *(const PG8_LAS bf16x8*)(lds + PG8_SB(b, h) + boff + n * 2048 + k * 1024); } while (0)
; #define PG8_MMA(ai, bj, At, Bt) do { __builtin_amdgcn_s_setprio(1); _Pragma("unroll") for (int m = 0; m < 4; ++m) _Pragma("unroll") for (int n = 0; n < 2; ++n) _Pragma("unroll") for (int k = 0; k < 2; ++k) \
;         acc[ai][bj][m][n] = mma16<Epi::I8>(Bt[n][k], At[m][k], acc[ai][bj][m][n]); __builtin_amdgcn_s_setprio(0); } while (0)
; #define PG8_WAIT_V(n) asm volatile("s_waitcnt vmcnt(" #n ")" ::: "memory")
; #define PG8_WAIT_L(n) asm volatile("s_waitcnt lgkmcnt(" #n ")" ::: "memory")
; #define PG8_BAR __builtin_amdgcn_s_barrier()
; template <class Epi, class Sched, bool ALIGN_EPI = false, bool SP2 = false>
; __device__ __forceinline__ void gemm_phase(PG8_LAS unsigned char* lds, const Gemm g, const Sched& S, const Epi& E) {
;     ...
;             const bool last = (t == nt - 2);
;             const char* a1 = cA + (size_t)(t + 1) * kstep;
;             const char* a2 = last ? nA : cA + (size_t)(t + 2) * kstep; const char* b2 = last ? nB : cB + (size_t)(t + 2) * kstep;
;             const char* a3 = a2 + kstep; const char* b3 = b2 + kstep;
;             if (last && has_next) S.a_ready(nxt);
;             if constexpr (SP2) {
;             PG8_LDB(B0, 0, 0); PG8_LDB(B1, 0, 1); PG8_SCHED; PG8_LDA(At, 0, 0); PG8_STAGE(PG8_SA(1, 1), a1 + hstep, voffA);
;             PG8_WAIT_V(8); PG8_WAIT_L(0); PG8_BAR; PG8_MMA(0, 0, At, B0); PG8_MMA(0, 1, At, B1); PG8_BAR; PG8_SCHED;
;             PG8_LDA(At, 0, 1); PG8_STAGE(PG8_SB(0, 0), b2, voffB); PG8_STAGE(PG8_SB(0, 1), b2 + hstep, voffB); PG8_STAGE(PG8_SA(0, 0), a2, voffA);
;             PG8_WAIT_V(8); PG8_WAIT_L(0); PG8_BAR; PG8_MMA(1, 0, At, B0); PG8_MMA(1, 1, At, B1); PG8_BAR; PG8_SCHED;
.LBB0_291:
	s_add_u32 s84, s8, 0x100
	s_addc_u32 s85, s9, 0
	s_add_i32 s66, 0, 0x10000
	s_cmp_eq_u32 s10, 12
	s_cselect_b32 vcc_hi, s5, s85
	s_cselect_b32 vcc_lo, s7, s84
	s_cselect_b32 s97, s11, s68
	s_cselect_b32 s96, s67, s69
	s_add_i32 s70, 0, 0x14000
	v_add_u32_e32 v110, s66, v175
	v_add_u32_e32 v168, s70, v175
	s_waitcnt vmcnt(0)
	ds_read_b128 v[66:69], v110
	ds_read_b128 v[70:73], v110 offset:1024
	ds_read_b128 v[106:109], v110 offset:2048
	ds_read_b128 v[110:113], v110 offset:3072
	ds_read_b128 v[114:117], v168
	ds_read_b128 v[118:121], v168 offset:1024
	ds_read_b128 v[126:129], v168 offset:2048
	ds_read_b128 v[178:181], v168 offset:3072
	v_lshl_add_u64 v[168:169], s[8:9], 0, v[164:165]
	s_add_i32 m0, s1, 0xc000
	ds_read_b128 v[182:185], v177
	ds_read_b128 v[186:189], v177 offset:1024
	ds_read_b128 v[190:193], v177 offset:2048
	ds_read_b128 v[194:197], v177 offset:3072
	ds_read_b128 v[198:201], v177 offset:4096
	ds_read_b128 v[210:213], v177 offset:5120
	ds_read_b128 v[214:217], v177 offset:6144
	ds_read_b128 v[218:221], v177 offset:7168
	global_load_lds_dwordx4 v[168:169], off
	v_lshl_add_u64 v[168:169], s[8:9], 0, v[166:167]
	s_add_i32 m0, s1, 0xe000
	s_nop 0
	global_load_lds_dwordx4 v[168:169], off
	s_waitcnt vmcnt(8)
	s_waitcnt lgkmcnt(0)
	s_barrier
	v_mfma_i32_16x16x64_i8 v[154:157], v[66:69], v[182:185], v[154:157]
	v_mfma_i32_16x16x64_i8 v[154:157], v[70:73], v[186:189], v[154:157]
	v_mfma_i32_16x16x64_i8 v[146:149], v[110:113], v[186:189], v[146:149]
	v_mfma_i32_16x16x64_i8 v[146:149], v[106:109], v[182:185], v[146:149]
	v_mfma_i32_16x16x64_i8 v[138:141], v[106:109], v[190:193], v[138:141]
	v_mfma_i32_16x16x64_i8 v[138:141], v[110:113], v[194:197], v[138:141]
	v_mfma_i32_16x16x64_i8 v[150:153], v[70:73], v[194:197], v[150:153]
	v_mfma_i32_16x16x64_i8 v[150:153], v[66:69], v[190:193], v[150:153]
	v_mfma_i32_16x16x64_i8 v[142:145], v[66:69], v[198:201], v[142:145]
	v_mfma_i32_16x16x64_i8 v[142:145], v[70:73], v[210:213], v[142:145]
	v_mfma_i32_16x16x64_i8 v[130:133], v[110:113], v[210:213], v[130:133]
	v_mfma_i32_16x16x64_i8 v[130:133], v[106:109], v[198:201], v[130:133]
	v_mfma_i32_16x16x64_i8 v[122:125], v[106:109], v[214:217], v[122:125]
	v_mfma_i32_16x16x64_i8 v[122:125], v[110:113], v[218:221], v[122:125]
	v_mfma_i32_16x16x64_i8 v[134:137], v[70:73], v[218:221], v[134:137]
	v_mfma_i32_16x16x64_i8 v[134:137], v[66:69], v[214:217], v[134:137]
	v_mfma_i32_16x16x64_i8 v[74:77], v[126:129], v[214:217], v[74:77]
	v_mfma_i32_16x16x64_i8 v[74:77], v[178:181], v[218:221], v[74:77]
	v_mfma_i32_16x16x64_i8 v[94:97], v[178:181], v[186:189], v[94:97]
	v_mfma_i32_16x16x64_i8 v[94:97], v[126:129], v[182:185], v[94:97]
	v_mfma_i32_16x16x64_i8 v[102:105], v[114:117], v[182:185], v[102:105]
	v_mfma_i32_16x16x64_i8 v[102:105], v[118:121], v[186:189], v[102:105]
	v_mfma_i32_16x16x64_i8 v[98:101], v[118:121], v[194:197], v[98:101]
	v_mfma_i32_16x16x64_i8 v[98:101], v[114:117], v[190:193], v[98:101]
	v_mfma_i32_16x16x64_i8 v[86:89], v[126:129], v[190:193], v[86:89]
	v_mfma_i32_16x16x64_i8 v[86:89], v[178:181], v[194:197], v[86:89]
	v_mfma_i32_16x16x64_i8 v[78:81], v[178:181], v[210:213], v[78:81]
	v_mfma_i32_16x16x64_i8 v[78:81], v[126:129], v[198:201], v[78:81]
	v_mfma_i32_16x16x64_i8 v[90:93], v[114:117], v[198:201], v[90:93]
	v_mfma_i32_16x16x64_i8 v[90:93], v[118:121], v[210:213], v[90:93]
	v_mfma_i32_16x16x64_i8 v[82:85], v[118:121], v[218:221], v[82:85]
	v_mfma_i32_16x16x64_i8 v[82:85], v[114:117], v[214:217], v[82:85]
	s_barrier
	s_add_i32 s8, s66, s81
	v_lshl_add_u64 v[168:169], s[96:97], 0, v[0:1]
	s_mov_b32 m0, s8
	ds_read_b128 v[182:185], v177 offset:16384
	ds_read_b128 v[186:189], v177 offset:17408
	ds_read_b128 v[190:193], v177 offset:18432
	ds_read_b128 v[194:197], v177 offset:19456
	ds_read_b128 v[198:201], v177 offset:20480
	ds_read_b128 v[210:213], v177 offset:21504
	ds_read_b128 v[214:217], v177 offset:22528
	ds_read_b128 v[218:221], v177 offset:23552
	global_load_lds_dwordx4 v[168:169], off
	s_add_i32 m0, s8, 0x2000
	s_add_u32 s8, s96, 0x40000
	v_lshl_add_u64 v[206:207], s[96:97], 0, v[158:159]
	s_addc_u32 s9, s97, 0
	s_add_i32 s66, s70, s81
	global_load_lds_dwordx4 v[206:207], off
	v_lshl_add_u64 v[222:223], s[8:9], 0, v[0:1]
	s_mov_b32 m0, s66
	v_lshl_add_u64 v[224:225], vcc, 0, v[160:161]
	global_load_lds_dwordx4 v[222:223], off
	v_lshl_add_u64 v[222:223], s[8:9], 0, v[158:159]
	s_add_i32 m0, s66, 0x2000
	s_nop 0
	global_load_lds_dwordx4 v[222:223], off
	v_lshl_add_u64 v[222:223], vcc, 0, v[162:163]
	s_mov_b32 m0, s1
	s_nop 0
	global_load_lds_dwordx4 v[222:223], off
	s_mov_b32 m0, s58
	s_nop 0
	global_load_lds_dwordx4 v[224:225], off
	s_waitcnt vmcnt(8)
	s_waitcnt lgkmcnt(0)
	s_barrier
; #define PG8_STAGE(bufoff, gbase, voff) do { _Pragma("unroll") for (int _i = 0; _i < 2; ++_i) \
;         __builtin_amdgcn_global_load_lds((const unsigned*)((const char*)(gbase) + (voff)[_i]), (PG8_LAS unsigned*)(lds + (bufoff) + ldsw + _i * 8192), 16, 0, 0); } while (0)
; #define PG8_LDA(dst, b, h) do { _Pragma("unroll") for (int m = 0; m < 4; ++m) _Pragma("unroll") for (int k = 0; k < 2; ++k) dst[m][k] = *(const PG8_LAS bf16x8*)(lds + PG8_SA(b, h) + aoff + m * 2048 + k * 1024); } while (0)
; #define PG8_LDB(dst, b, h) do { _Pragma("unroll") for (int n = 0; n < 2; ++n) _Pragma("unroll") for (int k = 0; k < 2; ++k) dst[n][k] = *(const PG8_LAS bf16x8*)(lds + PG8_SB(b, h) + boff + n * 2048 + k * 1024); } while (0)
; #define PG8_MMA(ai, bj, At, Bt) do { __builtin_amdgcn_s_setprio(1); _Pragma("unroll") for (int m = 0; m < 4; ++m) _Pragma("unroll") for (int n = 0; n < 2; ++n) _Pragma("unroll") for (int k = 0; k < 2; ++k) \
;         acc[ai][bj][m][n] = mma16<Epi::I8>(Bt[n][k], At[m][k], acc[ai][bj][m][n]); __builtin_amdgcn_s_setprio(0); } while (0)
; #define PG8_WAIT_V(n) asm volatile("s_waitcnt vmcnt(" #n ")" ::: "memory")
; #define PG8_WAIT_L(n) asm volatile("s_waitcnt lgkmcnt(" #n ")" ::: "memory")
; #define PG8_BAR __builtin_amdgcn_s_barrier()
; #define PG8_SCHED __builtin_amdgcn_sched_barrier(0)
; template <class Epi, class Sched, bool ALIGN_EPI = false, bool SP2 = false>
; __device__ __forceinline__ void gemm_phase(PG8_LAS unsigned char* lds, const Gemm g, const Sched& S, const Epi& E) {
;     ...
;             PG8_WAIT_V(8); PG8_WAIT_L(0); PG8_BAR; PG8_MMA(1, 0, At, B0); PG8_MMA(1, 1, At, B1); PG8_BAR; PG8_SCHED;
;             PG8_LDB(B0, 1, 0); PG8_LDB(B1, 1, 1); PG8_SCHED; PG8_LDA(At, 1, 0); PG8_STAGE(PG8_SA(0, 1), a2 + hstep, voffA);
;             PG8_WAIT_V(8); PG8_WAIT_L(0); PG8_BAR; PG8_MMA(0, 0, At, B0); PG8_MMA(0, 1, At, B1); PG8_BAR; PG8_SCHED;
	v_mfma_i32_16x16x64_i8 v[62:65], v[66:69], v[182:185], v[62:65]
	v_mfma_i32_16x16x64_i8 v[62:65], v[70:73], v[186:189], v[62:65]
	v_mfma_i32_16x16x64_i8 v[54:57], v[110:113], v[186:189], v[54:57]
	v_mfma_i32_16x16x64_i8 v[54:57], v[106:109], v[182:185], v[54:57]
	v_mfma_i32_16x16x64_i8 v[46:49], v[106:109], v[190:193], v[46:49]
	v_mfma_i32_16x16x64_i8 v[46:49], v[110:113], v[194:197], v[46:49]
	v_mfma_i32_16x16x64_i8 v[58:61], v[70:73], v[194:197], v[58:61]
	v_mfma_i32_16x16x64_i8 v[58:61], v[66:69], v[190:193], v[58:61]
	v_mfma_i32_16x16x64_i8 v[50:53], v[66:69], v[198:201], v[50:53]
	v_mfma_i32_16x16x64_i8 v[50:53], v[70:73], v[210:213], v[50:53]
	v_mfma_i32_16x16x64_i8 v[38:41], v[110:113], v[210:213], v[38:41]
	v_mfma_i32_16x16x64_i8 v[38:41], v[106:109], v[198:201], v[38:41]
	v_mfma_i32_16x16x64_i8 v[34:37], v[106:109], v[214:217], v[34:37]
	v_mfma_i32_16x16x64_i8 v[34:37], v[110:113], v[218:221], v[34:37]
	v_mfma_i32_16x16x64_i8 v[42:45], v[70:73], v[218:221], v[42:45]
	v_mfma_i32_16x16x64_i8 v[42:45], v[66:69], v[214:217], v[42:45]
	v_mfma_i32_16x16x64_i8 v[2:5], v[126:129], v[214:217], v[2:5]
	v_mfma_i32_16x16x64_i8 v[2:5], v[178:181], v[218:221], v[2:5]
	v_mfma_i32_16x16x64_i8 v[22:25], v[178:181], v[186:189], v[22:25]
	v_mfma_i32_16x16x64_i8 v[22:25], v[126:129], v[182:185], v[22:25]
	v_mfma_i32_16x16x64_i8 v[30:33], v[114:117], v[182:185], v[30:33]
	v_mfma_i32_16x16x64_i8 v[30:33], v[118:121], v[186:189], v[30:33]
	v_mfma_i32_16x16x64_i8 v[26:29], v[118:121], v[194:197], v[26:29]
	v_mfma_i32_16x16x64_i8 v[26:29], v[114:117], v[190:193], v[26:29]
	v_mfma_i32_16x16x64_i8 v[14:17], v[126:129], v[190:193], v[14:17]
	v_mfma_i32_16x16x64_i8 v[14:17], v[178:181], v[194:197], v[14:17]
	v_mfma_i32_16x16x64_i8 v[6:9], v[178:181], v[210:213], v[6:9]
	v_mfma_i32_16x16x64_i8 v[6:9], v[126:129], v[198:201], v[6:9]
	v_mfma_i32_16x16x64_i8 v[18:21], v[114:117], v[198:201], v[18:21]
	v_mfma_i32_16x16x64_i8 v[18:21], v[118:121], v[210:213], v[18:21]
	v_mfma_i32_16x16x64_i8 v[10:13], v[118:121], v[218:221], v[10:13]
	v_mfma_i32_16x16x64_i8 v[10:13], v[114:117], v[214:217], v[10:13]
	s_barrier
	s_add_i32 s66, 0, 0x18000
	s_add_i32 s70, 0, 0x1c000
	v_add_u32_e32 v110, s66, v175
	v_add_u32_e32 v170, s70, v175
	ds_read_b128 v[66:69], v110
	ds_read_b128 v[70:73], v110 offset:1024
	ds_read_b128 v[106:109], v110 offset:2048
	ds_read_b128 v[110:113], v110 offset:3072
	ds_read_b128 v[114:117], v170
	ds_read_b128 v[118:121], v170 offset:1024
	ds_read_b128 v[126:129], v170 offset:2048
	ds_read_b128 v[178:181], v170 offset:3072
	s_add_u32 s8, vcc_lo, 0x40000
	s_addc_u32 s9, vcc_hi, 0
	s_mov_b32 m0, s80
	v_lshl_add_u64 v[226:227], s[8:9], 0, v[162:163]
	ds_read_b128 v[182:185], v177 offset:32768
	ds_read_b128 v[186:189], v177 offset:33792
	ds_read_b128 v[190:193], v177 offset:34816
	ds_read_b128 v[194:197], v177 offset:35840
	ds_read_b128 v[198:201], v177 offset:36864
	ds_read_b128 v[210:213], v177 offset:37888
	ds_read_b128 v[214:217], v177 offset:38912
	ds_read_b128 v[218:221], v177 offset:39936
	global_load_lds_dwordx4 v[226:227], off
	v_lshl_add_u64 v[226:227], s[8:9], 0, v[160:161]
	s_mov_b32 m0, s0
	s_nop 0
	global_load_lds_dwordx4 v[226:227], off
	s_waitcnt vmcnt(8)
	s_waitcnt lgkmcnt(0)
	s_barrier
	v_mfma_i32_16x16x64_i8 v[154:157], v[66:69], v[182:185], v[154:157]
	v_mfma_i32_16x16x64_i8 v[154:157], v[70:73], v[186:189], v[154:157]
	v_mfma_i32_16x16x64_i8 v[146:149], v[110:113], v[186:189], v[146:149]
	v_mfma_i32_16x16x64_i8 v[146:149], v[106:109], v[182:185], v[146:149]
	v_mfma_i32_16x16x64_i8 v[138:141], v[106:109], v[190:193], v[138:141]
	v_mfma_i32_16x16x64_i8 v[138:141], v[110:113], v[194:197], v[138:141]
	v_mfma_i32_16x16x64_i8 v[150:153], v[70:73], v[194:197], v[150:153]
	v_mfma_i32_16x16x64_i8 v[150:153], v[66:69], v[190:193], v[150:153]
	v_mfma_i32_16x16x64_i8 v[142:145], v[66:69], v[198:201], v[142:145]
	v_mfma_i32_16x16x64_i8 v[142:145], v[70:73], v[210:213], v[142:145]
	v_mfma_i32_16x16x64_i8 v[130:133], v[110:113], v[210:213], v[130:133]
	v_mfma_i32_16x16x64_i8 v[130:133], v[106:109], v[198:201], v[130:133]
	v_mfma_i32_16x16x64_i8 v[122:125], v[106:109], v[214:217], v[122:125]
	v_mfma_i32_16x16x64_i8 v[122:125], v[110:113], v[218:221], v[122:125]
	v_mfma_i32_16x16x64_i8 v[134:137], v[70:73], v[218:221], v[134:137]
	v_mfma_i32_16x16x64_i8 v[134:137], v[66:69], v[214:217], v[134:137]
	v_mfma_i32_16x16x64_i8 v[74:77], v[126:129], v[214:217], v[74:77]
	v_mfma_i32_16x16x64_i8 v[74:77], v[178:181], v[218:221], v[74:77]
	v_mfma_i32_16x16x64_i8 v[94:97], v[178:181], v[186:189], v[94:97]
	v_mfma_i32_16x16x64_i8 v[94:97], v[126:129], v[182:185], v[94:97]
	v_mfma_i32_16x16x64_i8 v[102:105], v[114:117], v[182:185], v[102:105]
	v_mfma_i32_16x16x64_i8 v[102:105], v[118:121], v[186:189], v[102:105]
	v_mfma_i32_16x16x64_i8 v[98:101], v[118:121], v[194:197], v[98:101]
	v_mfma_i32_16x16x64_i8 v[98:101], v[114:117], v[190:193], v[98:101]
	v_mfma_i32_16x16x64_i8 v[86:89], v[126:129], v[190:193], v[86:89]
	v_mfma_i32_16x16x64_i8 v[86:89], v[178:181], v[194:197], v[86:89]
	v_mfma_i32_16x16x64_i8 v[78:81], v[178:181], v[210:213], v[78:81]
	v_mfma_i32_16x16x64_i8 v[78:81], v[126:129], v[198:201], v[78:81]
	v_mfma_i32_16x16x64_i8 v[90:93], v[114:117], v[198:201], v[90:93]
	v_mfma_i32_16x16x64_i8 v[90:93], v[118:121], v[210:213], v[90:93]
	v_mfma_i32_16x16x64_i8 v[82:85], v[118:121], v[218:221], v[82:85]
	v_mfma_i32_16x16x64_i8 v[82:85], v[114:117], v[214:217], v[82:85]
	s_barrier
; #define PG8_STAGE(bufoff, gbase, voff) do { _Pragma("unroll") for (int _i = 0; _i < 2; ++_i) \
;         __builtin_amdgcn_global_load_lds((const unsigned*)((const char*)(gbase) + (voff)[_i]), (PG8_LAS unsigned*)(lds + (bufoff) + ldsw + _i * 8192), 16, 0, 0); } while (0)
; #define PG8_LDA(dst, b, h) do { _Pragma("unroll") for (int m = 0; m < 4; ++m) _Pragma("unroll") for (int k = 0; k < 2; ++k) dst[m][k] = *(const PG8_LAS bf16x8*)(lds + PG8_SA(b, h) + aoff + m * 2048 + k * 1024); } while (0)
; #define PG8_MMA(ai, bj, At, Bt) do { __builtin_amdgcn_s_setprio(1); _Pragma("unroll") for (int m = 0; m < 4; ++m) _Pragma("unroll") for (int n = 0; n < 2; ++n) _Pragma("unroll") for (int k = 0; k < 2; ++k) \
;         acc[ai][bj][m][n] = mma16<Epi::I8>(Bt[n][k], At[m][k], acc[ai][bj][m][n]); __builtin_amdgcn_s_setprio(0); } while (0)
; #define PG8_WAIT_V(n) asm volatile("s_waitcnt vmcnt(" #n ")" ::: "memory")
; #define PG8_WAIT_L(n) asm volatile("s_waitcnt lgkmcnt(" #n ")" ::: "memory")
; #define PG8_BAR __builtin_amdgcn_s_barrier()
; #define PG8_SCHED __builtin_amdgcn_sched_barrier(0)
; template <class Epi, class Sched, bool ALIGN_EPI = false, bool SP2 = false>
; __device__ __forceinline__ void gemm_phase(PG8_LAS unsigned char* lds, const Gemm g, const Sched& S, const Epi& E) {
;     ...
;             PG8_LDA(At, 1, 1); PG8_STAGE(PG8_SB(1, 0), b3, voffB); PG8_STAGE(PG8_SB(1, 1), b3 + hstep, voffB); PG8_STAGE(PG8_SA(1, 0), a3, voffA);
;             PG8_WAIT_V(8); PG8_WAIT_L(0); PG8_BAR; PG8_MMA(1, 0, At, B0); PG8_MMA(1, 1, At, B1); PG8_BAR; PG8_SCHED;
	s_add_i32 s8, s66, s81
	v_lshl_add_u64 v[168:169], v[168:169], 0, s[92:93]
	s_mov_b32 m0, s8
	ds_read_b128 v[182:185], v177 offset:49152
	ds_read_b128 v[186:189], v177 offset:50176
	ds_read_b128 v[190:193], v177 offset:51200
	ds_read_b128 v[194:197], v177 offset:52224
	ds_read_b128 v[198:201], v177 offset:53248
	ds_read_b128 v[210:213], v177 offset:54272
	ds_read_b128 v[214:217], v177 offset:55296
	ds_read_b128 v[218:221], v177 offset:56320
	global_load_lds_dwordx4 v[168:169], off
	s_add_i32 m0, s8, 0x2000
	s_add_u32 s8, s96, 0x40080
	v_lshl_add_u64 v[168:169], v[206:207], 0, s[92:93]
	s_addc_u32 s9, s97, 0
	s_add_i32 s66, s70, s81
	global_load_lds_dwordx4 v[168:169], off
	v_lshl_add_u64 v[168:169], s[8:9], 0, v[0:1]
	s_mov_b32 m0, s66
	s_nop 0
	global_load_lds_dwordx4 v[168:169], off
	v_lshl_add_u64 v[168:169], s[8:9], 0, v[158:159]
	s_add_i32 m0, s66, 0x2000
	s_nop 0
	global_load_lds_dwordx4 v[168:169], off
	v_lshl_add_u64 v[168:169], v[222:223], 0, s[92:93]
	s_mov_b32 m0, s13
	s_nop 0
	global_load_lds_dwordx4 v[168:169], off
	v_lshl_add_u64 v[168:169], v[224:225], 0, s[92:93]
	s_mov_b32 m0, s12
	s_nop 0
	global_load_lds_dwordx4 v[168:169], off
	s_waitcnt vmcnt(8)
	s_waitcnt lgkmcnt(0)
	s_barrier
	v_mfma_i32_16x16x64_i8 v[62:65], v[66:69], v[182:185], v[62:65]
	v_mfma_i32_16x16x64_i8 v[62:65], v[70:73], v[186:189], v[62:65]
	v_mfma_i32_16x16x64_i8 v[54:57], v[110:113], v[186:189], v[54:57]
	v_mfma_i32_16x16x64_i8 v[54:57], v[106:109], v[182:185], v[54:57]
	v_mfma_i32_16x16x64_i8 v[46:49], v[106:109], v[190:193], v[46:49]
	v_mfma_i32_16x16x64_i8 v[46:49], v[110:113], v[194:197], v[46:49]
	v_mfma_i32_16x16x64_i8 v[58:61], v[70:73], v[194:197], v[58:61]
	v_mfma_i32_16x16x64_i8 v[58:61], v[66:69], v[190:193], v[58:61]
	v_mfma_i32_16x16x64_i8 v[50:53], v[66:69], v[198:201], v[50:53]
	v_mfma_i32_16x16x64_i8 v[50:53], v[70:73], v[210:213], v[50:53]
	v_mfma_i32_16x16x64_i8 v[38:41], v[110:113], v[210:213], v[38:41]
	v_mfma_i32_16x16x64_i8 v[38:41], v[106:109], v[198:201], v[38:41]
	v_mfma_i32_16x16x64_i8 v[34:37], v[106:109], v[214:217], v[34:37]
	v_mfma_i32_16x16x64_i8 v[34:37], v[110:113], v[218:221], v[34:37]
	v_mfma_i32_16x16x64_i8 v[42:45], v[70:73], v[218:221], v[42:45]
	v_mfma_i32_16x16x64_i8 v[42:45], v[66:69], v[214:217], v[42:45]
	v_mfma_i32_16x16x64_i8 v[2:5], v[126:129], v[214:217], v[2:5]
	v_mfma_i32_16x16x64_i8 v[2:5], v[178:181], v[218:221], v[2:5]
	v_mfma_i32_16x16x64_i8 v[22:25], v[178:181], v[186:189], v[22:25]
	v_mfma_i32_16x16x64_i8 v[22:25], v[126:129], v[182:185], v[22:25]
	v_mfma_i32_16x16x64_i8 v[30:33], v[114:117], v[182:185], v[30:33]
	v_mfma_i32_16x16x64_i8 v[30:33], v[118:121], v[186:189], v[30:33]
	v_mfma_i32_16x16x64_i8 v[26:29], v[118:121], v[194:197], v[26:29]
	v_mfma_i32_16x16x64_i8 v[26:29], v[114:117], v[190:193], v[26:29]
	v_mfma_i32_16x16x64_i8 v[14:17], v[126:129], v[190:193], v[14:17]
	v_mfma_i32_16x16x64_i8 v[14:17], v[178:181], v[194:197], v[14:17]
	v_mfma_i32_16x16x64_i8 v[6:9], v[178:181], v[210:213], v[6:9]
	v_mfma_i32_16x16x64_i8 v[6:9], v[126:129], v[198:201], v[6:9]
	v_mfma_i32_16x16x64_i8 v[18:21], v[114:117], v[198:201], v[18:21]
	v_mfma_i32_16x16x64_i8 v[18:21], v[118:121], v[210:213], v[18:21]
	v_mfma_i32_16x16x64_i8 v[10:13], v[118:121], v[218:221], v[10:13]
	v_mfma_i32_16x16x64_i8 v[10:13], v[114:117], v[214:217], v[10:13]
	s_barrier
	s_add_i32 s10, s10, 2
	s_add_u32 s69, s69, 0x100
	s_addc_u32 s68, s68, 0
	s_cmp_gt_u32 s10, 13
	s_mov_b64 s[8:9], s[84:85]
	s_cbranch_scc0 .LBB0_291

; #define PG8_STAGE(bufoff, gbase, voff) do { _Pragma("unroll") for (int _i = 0; _i < 2; ++_i) \
;         __builtin_amdgcn_global_load_lds((const unsigned*)((const char*)(gbase) + (voff)[_i]), (PG8_LAS unsigned*)(lds + (bufoff) + ldsw + _i * 8192), 16, 0, 0); } while (0)
; #define PG8_LDA(dst, b, h) do { _Pragma("unroll") for (int m = 0; m < 4; ++m) _Pragma("unroll") for (int k = 0; k < 2; ++k) dst[m][k] = *(const PG8_LAS bf16x8*)(lds + PG8_SA(b, h) + aoff + m * 2048 + k * 1024); } while (0)
; #define PG8_LDB(dst, b, h) do { _Pragma("unroll") for (int n = 0; n < 2; ++n) _Pragma("unroll") for (int k = 0; k < 2; ++k) dst[n][k] = *(const PG8_LAS bf16x8*)(lds + PG8_SB(b, h) + boff + n * 2048 + k * 1024); } while (0)
; #define PG8_MMA(ai, bj, At, Bt) do { __builtin_amdgcn_s_setprio(1); _Pragma("unroll") for (int m = 0; m < 4; ++m) _Pragma("unroll") for (int n = 0; n < 2; ++n) _Pragma("unroll") for (int k = 0; k < 2; ++k) \
;         acc[ai][bj][m][n] = mma16<Epi::I8>(Bt[n][k], At[m][k], acc[ai][bj][m][n]); __builtin_amdgcn_s_setprio(0); } while (0)
; #define PG8_WAIT_V(n) asm volatile("s_waitcnt vmcnt(" #n ")" ::: "memory")
; #define PG8_WAIT_L(n) asm volatile("s_waitcnt lgkmcnt(" #n ")" ::: "memory")
; #define PG8_BAR __builtin_amdgcn_s_barrier()
; #define PG8_SCHED __builtin_amdgcn_sched_barrier(0)
; template <class Epi, class Sched, bool ALIGN_EPI = false, bool SP2 = false>
; __device__ __forceinline__ void gemm_phase(PG8_LAS unsigned char* lds, const Gemm g, const Sched& S, const Epi& E) {
;     ...
;             PG8_LDB(B0, 0, 0); PG8_LDB(B1, 0, 1); PG8_SCHED; PG8_LDA(At, 0, 0); PG8_STAGE(PG8_SA(1, 1), a1 + hstep, voffA);
;             PG8_WAIT_V(8); PG8_WAIT_L(0); PG8_BAR; PG8_MMA(0, 0, At, B0); PG8_MMA(0, 1, At, B1); PG8_BAR; PG8_SCHED;
;             PG8_LDA(At, 0, 1); PG8_STAGE(PG8_SB(0, 0), b2, voffB); PG8_STAGE(PG8_SB(0, 1), b2 + hstep, voffB); PG8_STAGE(PG8_SA(0, 0), a2, voffA);
;             PG8_WAIT_V(8); PG8_WAIT_L(0); PG8_BAR; PG8_MMA(1, 0, At, B0); PG8_MMA(1, 1, At, B1); PG8_BAR; PG8_SCHED;
.Lpeel327:
	s_add_u32 s68, s8, 0x100
	s_addc_u32 s69, s9, 0
	s_add_i32 s84, 0, 0x10000
	s_cmp_eq_u32 s4, 28
	s_cselect_b32 vcc_hi, s1, s69
	s_cselect_b32 vcc_lo, s5, s68
	v_add_u32_e32 v0, s84, v188
	s_cselect_b32 s71, s7, s96
	s_cselect_b32 s70, s85, s97
	s_add_i32 s10, 0, 0x14000
	ds_read_b128 v[52:55], v0
	ds_read_b128 v[56:59], v0 offset:1024
	ds_read_b128 v[76:79], v0 offset:2048
	ds_read_b128 v[80:83], v0 offset:3072
	v_add_u32_e32 v0, s10, v188
	ds_read_b128 v[116:119], v0
	ds_read_b128 v[120:123], v0 offset:1024
	ds_read_b128 v[168:171], v0 offset:2048
	ds_read_b128 v[172:175], v0 offset:3072
	v_lshl_add_u64 v[2:3], s[8:9], 0, v[164:165]
	s_add_i32 m0, s58, 0xc000
	ds_read_b128 v[176:179], v189
	ds_read_b128 v[180:183], v189 offset:1024
	ds_read_b128 v[190:193], v189 offset:2048
	ds_read_b128 v[194:197], v189 offset:3072
	ds_read_b128 v[198:201], v189 offset:4096
	ds_read_b128 v[210:213], v189 offset:5120
	ds_read_b128 v[214:217], v189 offset:6144
	ds_read_b128 v[218:221], v189 offset:7168
	global_load_lds_dwordx4 v[2:3], off
	v_lshl_add_u64 v[2:3], s[8:9], 0, v[166:167]
	s_add_i32 m0, s58, 0xe000
	s_nop 0
	global_load_lds_dwordx4 v[2:3], off
	s_waitcnt vmcnt(8)
	s_waitcnt lgkmcnt(0)
	s_barrier
	v_mfma_f32_16x16x32_bf16 v[152:155], v[52:55], v[176:179], 0
	v_mfma_f32_16x16x32_bf16 v[152:155], v[56:59], v[180:183], v[152:155]
	v_mfma_f32_16x16x32_bf16 v[144:147], v[76:79], v[176:179], 0
	v_mfma_f32_16x16x32_bf16 v[144:147], v[80:83], v[180:183], v[144:147]
	v_mfma_f32_16x16x32_bf16 v[140:143], v[76:79], v[190:193], 0
	v_mfma_f32_16x16x32_bf16 v[140:143], v[80:83], v[194:197], v[140:143]
	v_mfma_f32_16x16x32_bf16 v[148:151], v[52:55], v[190:193], 0
	v_mfma_f32_16x16x32_bf16 v[148:151], v[56:59], v[194:197], v[148:151]
	v_mfma_f32_16x16x32_bf16 v[136:139], v[52:55], v[198:201], 0
	v_mfma_f32_16x16x32_bf16 v[136:139], v[56:59], v[210:213], v[136:139]
	v_mfma_f32_16x16x32_bf16 v[132:135], v[76:79], v[198:201], 0
	v_mfma_f32_16x16x32_bf16 v[132:135], v[80:83], v[210:213], v[132:135]
	v_mfma_f32_16x16x32_bf16 v[124:127], v[76:79], v[214:217], 0
	v_mfma_f32_16x16x32_bf16 v[124:127], v[80:83], v[218:221], v[124:127]
	v_mfma_f32_16x16x32_bf16 v[128:131], v[52:55], v[214:217], 0
	v_mfma_f32_16x16x32_bf16 v[128:131], v[56:59], v[218:221], v[128:131]
	v_mfma_f32_16x16x32_bf16 v[112:115], v[116:119], v[176:179], 0
	v_mfma_f32_16x16x32_bf16 v[112:115], v[120:123], v[180:183], v[112:115]
	v_mfma_f32_16x16x32_bf16 v[104:107], v[168:171], v[176:179], 0
	v_mfma_f32_16x16x32_bf16 v[104:107], v[172:175], v[180:183], v[104:107]
	v_mfma_f32_16x16x32_bf16 v[100:103], v[168:171], v[190:193], 0
	v_mfma_f32_16x16x32_bf16 v[100:103], v[172:175], v[194:197], v[100:103]
	v_mfma_f32_16x16x32_bf16 v[108:111], v[116:119], v[190:193], 0
	v_mfma_f32_16x16x32_bf16 v[108:111], v[120:123], v[194:197], v[108:111]
	v_mfma_f32_16x16x32_bf16 v[96:99], v[116:119], v[198:201], 0
	v_mfma_f32_16x16x32_bf16 v[96:99], v[120:123], v[210:213], v[96:99]
	v_mfma_f32_16x16x32_bf16 v[92:95], v[168:171], v[198:201], 0
	v_mfma_f32_16x16x32_bf16 v[92:95], v[172:175], v[210:213], v[92:95]
	v_mfma_f32_16x16x32_bf16 v[84:87], v[168:171], v[214:217], 0
	v_mfma_f32_16x16x32_bf16 v[84:87], v[172:175], v[218:221], v[84:87]
	v_mfma_f32_16x16x32_bf16 v[88:91], v[116:119], v[214:217], 0
	v_mfma_f32_16x16x32_bf16 v[88:91], v[120:123], v[218:221], v[88:91]
	s_barrier
	s_add_i32 s8, s84, s80
	v_lshl_add_u64 v[184:185], s[70:71], 0, v[158:159]
	s_mov_b32 m0, s8
	ds_read_b128 v[176:179], v189 offset:16384
	ds_read_b128 v[180:183], v189 offset:17408
	ds_read_b128 v[190:193], v189 offset:18432
	ds_read_b128 v[194:197], v189 offset:19456
	ds_read_b128 v[198:201], v189 offset:20480
	ds_read_b128 v[210:213], v189 offset:21504
	ds_read_b128 v[214:217], v189 offset:22528
	ds_read_b128 v[218:221], v189 offset:23552
	global_load_lds_dwordx4 v[184:185], off
	s_add_i32 m0, s8, 0x2000
	s_add_u32 s8, s70, 0x80000
	v_lshl_add_u64 v[206:207], s[70:71], 0, v[162:163]
	s_addc_u32 s9, s71, 0
	s_add_i32 s10, s10, s80
	global_load_lds_dwordx4 v[206:207], off
	v_lshl_add_u64 v[2:3], s[8:9], 0, v[158:159]
	s_mov_b32 m0, s10
	v_lshl_add_u64 v[222:223], vcc, 0, v[156:157]
	global_load_lds_dwordx4 v[2:3], off
	v_lshl_add_u64 v[2:3], s[8:9], 0, v[162:163]
	s_add_i32 m0, s10, 0x2000
	v_lshl_add_u64 v[224:225], vcc, 0, v[160:161]
	global_load_lds_dwordx4 v[2:3], off
	s_mov_b32 m0, s58
	s_nop 0
	global_load_lds_dwordx4 v[222:223], off
	s_mov_b32 m0, s12
	s_nop 0
	global_load_lds_dwordx4 v[224:225], off
	s_waitcnt vmcnt(8)
	s_waitcnt lgkmcnt(0)
	s_barrier
	v_mfma_f32_16x16x32_bf16 v[72:75], v[52:55], v[176:179], 0
	v_mfma_f32_16x16x32_bf16 v[72:75], v[56:59], v[180:183], v[72:75]
	v_mfma_f32_16x16x32_bf16 v[64:67], v[76:79], v[176:179], 0
	v_mfma_f32_16x16x32_bf16 v[64:67], v[80:83], v[180:183], v[64:67]
	v_mfma_f32_16x16x32_bf16 v[60:63], v[76:79], v[190:193], 0
	v_mfma_f32_16x16x32_bf16 v[60:63], v[80:83], v[194:197], v[60:63]
	v_mfma_f32_16x16x32_bf16 v[68:71], v[52:55], v[190:193], 0
	v_mfma_f32_16x16x32_bf16 v[68:71], v[56:59], v[194:197], v[68:71]
	v_mfma_f32_16x16x32_bf16 v[48:51], v[52:55], v[198:201], 0
	v_mfma_f32_16x16x32_bf16 v[48:51], v[56:59], v[210:213], v[48:51]
	v_mfma_f32_16x16x32_bf16 v[44:47], v[76:79], v[198:201], 0
	v_mfma_f32_16x16x32_bf16 v[44:47], v[80:83], v[210:213], v[44:47]
	v_mfma_f32_16x16x32_bf16 v[36:39], v[76:79], v[214:217], 0
	v_mfma_f32_16x16x32_bf16 v[36:39], v[80:83], v[218:221], v[36:39]
	v_mfma_f32_16x16x32_bf16 v[40:43], v[52:55], v[214:217], 0
	v_mfma_f32_16x16x32_bf16 v[40:43], v[56:59], v[218:221], v[40:43]
	v_mfma_f32_16x16x32_bf16 v[32:35], v[116:119], v[176:179], 0
	v_mfma_f32_16x16x32_bf16 v[32:35], v[120:123], v[180:183], v[32:35]
	v_mfma_f32_16x16x32_bf16 v[24:27], v[168:171], v[176:179], 0
	v_mfma_f32_16x16x32_bf16 v[24:27], v[172:175], v[180:183], v[24:27]
	v_mfma_f32_16x16x32_bf16 v[20:23], v[168:171], v[190:193], 0
	v_mfma_f32_16x16x32_bf16 v[20:23], v[172:175], v[194:197], v[20:23]
	v_mfma_f32_16x16x32_bf16 v[28:31], v[116:119], v[190:193], 0
	v_mfma_f32_16x16x32_bf16 v[28:31], v[120:123], v[194:197], v[28:31]
	v_mfma_f32_16x16x32_bf16 v[16:19], v[116:119], v[198:201], 0
	v_mfma_f32_16x16x32_bf16 v[16:19], v[120:123], v[210:213], v[16:19]
	v_mfma_f32_16x16x32_bf16 v[12:15], v[168:171], v[198:201], 0
	v_mfma_f32_16x16x32_bf16 v[12:15], v[172:175], v[210:213], v[12:15]
	v_mfma_f32_16x16x32_bf16 v[2:5], v[168:171], v[214:217], 0
	v_mfma_f32_16x16x32_bf16 v[2:5], v[172:175], v[218:221], v[2:5]
	v_mfma_f32_16x16x32_bf16 v[8:11], v[116:119], v[214:217], 0
	v_mfma_f32_16x16x32_bf16 v[8:11], v[120:123], v[218:221], v[8:11]
	s_barrier
; #define PG8_STAGE(bufoff, gbase, voff) do { _Pragma("unroll") for (int _i = 0; _i < 2; ++_i) \
;         __builtin_amdgcn_global_load_lds((const unsigned*)((const char*)(gbase) + (voff)[_i]), (PG8_LAS unsigned*)(lds + (bufoff) + ldsw + _i * 8192), 16, 0, 0); } while (0)
; #define PG8_LDA(dst, b, h) do { _Pragma("unroll") for (int m = 0; m < 4; ++m) _Pragma("unroll") for (int k = 0; k < 2; ++k) dst[m][k] = *(const PG8_LAS bf16x8*)(lds + PG8_SA(b, h) + aoff + m * 2048 + k * 1024); } while (0)
; #define PG8_LDB(dst, b, h) do { _Pragma("unroll") for (int n = 0; n < 2; ++n) _Pragma("unroll") for (int k = 0; k < 2; ++k) dst[n][k] = *(const PG8_LAS bf16x8*)(lds + PG8_SB(b, h) + boff + n * 2048 + k * 1024); } while (0)
; #define PG8_MMA(ai, bj, At, Bt) do { __builtin_amdgcn_s_setprio(1); _Pragma("unroll") for (int m = 0; m < 4; ++m) _Pragma("unroll") for (int n = 0; n < 2; ++n) _Pragma("unroll") for (int k = 0; k < 2; ++k) \
;         acc[ai][bj][m][n] = mma16<Epi::I8>(Bt[n][k], At[m][k], acc[ai][bj][m][n]); __builtin_amdgcn_s_setprio(0); } while (0)
; #define PG8_WAIT_V(n) asm volatile("s_waitcnt vmcnt(" #n ")" ::: "memory")
; #define PG8_WAIT_L(n) asm volatile("s_waitcnt lgkmcnt(" #n ")" ::: "memory")
; #define PG8_BAR __builtin_amdgcn_s_barrier()
; #define PG8_SCHED __builtin_amdgcn_sched_barrier(0)
; template <class Epi, class Sched, bool ALIGN_EPI = false, bool SP2 = false>
; __device__ __forceinline__ void gemm_phase(PG8_LAS unsigned char* lds, const Gemm g, const Sched& S, const Epi& E) {
;     ...
;             PG8_LDB(B0, 1, 0); PG8_LDB(B1, 1, 1); PG8_SCHED; PG8_LDA(At, 1, 0); PG8_STAGE(PG8_SA(0, 1), a2 + hstep, voffA);
;             PG8_WAIT_V(8); PG8_WAIT_L(0); PG8_BAR; PG8_MMA(0, 0, At, B0); PG8_MMA(0, 1, At, B1); PG8_BAR; PG8_SCHED;
;             PG8_LDA(At, 1, 1); PG8_STAGE(PG8_SB(1, 0), b3, voffB); PG8_STAGE(PG8_SB(1, 1), b3 + hstep, voffB); PG8_STAGE(PG8_SA(1, 0), a3, voffA);
;             PG8_WAIT_V(8); PG8_WAIT_L(0); PG8_BAR; PG8_MMA(1, 0, At, B0); PG8_MMA(1, 1, At, B1); PG8_BAR; PG8_SCHED;
	s_add_i32 s10, 0, 0x18000
	v_add_u32_e32 v0, s10, v188
	s_add_i32 s11, 0, 0x1c000
	ds_read_b128 v[52:55], v0
	ds_read_b128 v[56:59], v0 offset:1024
	ds_read_b128 v[76:79], v0 offset:2048
	ds_read_b128 v[80:83], v0 offset:3072
	v_add_u32_e32 v0, s11, v188
	ds_read_b128 v[116:119], v0
	ds_read_b128 v[120:123], v0 offset:1024
	ds_read_b128 v[168:171], v0 offset:2048
	ds_read_b128 v[172:175], v0 offset:3072
	s_add_u32 s8, vcc_lo, 0x80000
	s_addc_u32 s9, vcc_hi, 0
	s_mov_b32 m0, s13
	v_lshl_add_u64 v[6:7], s[8:9], 0, v[156:157]
	ds_read_b128 v[176:179], v189 offset:32768
	ds_read_b128 v[180:183], v189 offset:33792
	ds_read_b128 v[190:193], v189 offset:34816
	ds_read_b128 v[194:197], v189 offset:35840
	ds_read_b128 v[198:201], v189 offset:36864
	ds_read_b128 v[210:213], v189 offset:37888
	ds_read_b128 v[214:217], v189 offset:38912
	ds_read_b128 v[218:221], v189 offset:39936
	global_load_lds_dwordx4 v[6:7], off
	v_lshl_add_u64 v[6:7], s[8:9], 0, v[160:161]
	s_mov_b32 m0, s66
	s_nop 0
	global_load_lds_dwordx4 v[6:7], off
	s_waitcnt vmcnt(8)
	s_waitcnt lgkmcnt(0)
	s_barrier
	v_mfma_f32_16x16x32_bf16 v[152:155], v[52:55], v[176:179], v[152:155]
	v_mfma_f32_16x16x32_bf16 v[152:155], v[56:59], v[180:183], v[152:155]
	v_mfma_f32_16x16x32_bf16 v[144:147], v[76:79], v[176:179], v[144:147]
	v_mfma_f32_16x16x32_bf16 v[144:147], v[80:83], v[180:183], v[144:147]
	v_mfma_f32_16x16x32_bf16 v[140:143], v[76:79], v[190:193], v[140:143]
	v_mfma_f32_16x16x32_bf16 v[140:143], v[80:83], v[194:197], v[140:143]
	v_mfma_f32_16x16x32_bf16 v[148:151], v[52:55], v[190:193], v[148:151]
	v_mfma_f32_16x16x32_bf16 v[148:151], v[56:59], v[194:197], v[148:151]
	v_mfma_f32_16x16x32_bf16 v[136:139], v[52:55], v[198:201], v[136:139]
	v_mfma_f32_16x16x32_bf16 v[136:139], v[56:59], v[210:213], v[136:139]
	v_mfma_f32_16x16x32_bf16 v[132:135], v[76:79], v[198:201], v[132:135]
	v_mfma_f32_16x16x32_bf16 v[132:135], v[80:83], v[210:213], v[132:135]
	v_mfma_f32_16x16x32_bf16 v[124:127], v[76:79], v[214:217], v[124:127]
	v_mfma_f32_16x16x32_bf16 v[124:127], v[80:83], v[218:221], v[124:127]
	v_mfma_f32_16x16x32_bf16 v[128:131], v[52:55], v[214:217], v[128:131]
	v_mfma_f32_16x16x32_bf16 v[128:131], v[56:59], v[218:221], v[128:131]
	v_mfma_f32_16x16x32_bf16 v[112:115], v[116:119], v[176:179], v[112:115]
	v_mfma_f32_16x16x32_bf16 v[112:115], v[120:123], v[180:183], v[112:115]
	v_mfma_f32_16x16x32_bf16 v[104:107], v[168:171], v[176:179], v[104:107]
	v_mfma_f32_16x16x32_bf16 v[104:107], v[172:175], v[180:183], v[104:107]
	v_mfma_f32_16x16x32_bf16 v[100:103], v[168:171], v[190:193], v[100:103]
	v_mfma_f32_16x16x32_bf16 v[100:103], v[172:175], v[194:197], v[100:103]
	v_mfma_f32_16x16x32_bf16 v[108:111], v[116:119], v[190:193], v[108:111]
	v_mfma_f32_16x16x32_bf16 v[108:111], v[120:123], v[194:197], v[108:111]
	v_mfma_f32_16x16x32_bf16 v[96:99], v[116:119], v[198:201], v[96:99]
	v_mfma_f32_16x16x32_bf16 v[96:99], v[120:123], v[210:213], v[96:99]
	v_mfma_f32_16x16x32_bf16 v[92:95], v[168:171], v[198:201], v[92:95]
	v_mfma_f32_16x16x32_bf16 v[92:95], v[172:175], v[210:213], v[92:95]
	v_mfma_f32_16x16x32_bf16 v[84:87], v[168:171], v[214:217], v[84:87]
	v_mfma_f32_16x16x32_bf16 v[84:87], v[172:175], v[218:221], v[84:87]
	v_mfma_f32_16x16x32_bf16 v[88:91], v[116:119], v[214:217], v[88:91]
	v_mfma_f32_16x16x32_bf16 v[88:91], v[120:123], v[218:221], v[88:91]
	s_barrier
	s_add_i32 s8, s10, s80
	v_lshl_add_u64 v[6:7], v[184:185], 0, s[92:93]
	s_mov_b32 m0, s8
	ds_read_b128 v[176:179], v189 offset:49152
	ds_read_b128 v[180:183], v189 offset:50176
	ds_read_b128 v[190:193], v189 offset:51200
	ds_read_b128 v[194:197], v189 offset:52224
	ds_read_b128 v[198:201], v189 offset:53248
	ds_read_b128 v[210:213], v189 offset:54272
	ds_read_b128 v[214:217], v189 offset:55296
	ds_read_b128 v[218:221], v189 offset:56320
	global_load_lds_dwordx4 v[6:7], off
	s_add_i32 m0, s8, 0x2000
	s_add_u32 s8, s70, 0x80080
	v_lshl_add_u64 v[6:7], v[206:207], 0, s[92:93]
	s_addc_u32 s9, s71, 0
	s_add_i32 s10, s11, s80
	global_load_lds_dwordx4 v[6:7], off
	v_lshl_add_u64 v[6:7], s[8:9], 0, v[158:159]
	s_mov_b32 m0, s10
	s_nop 0
	global_load_lds_dwordx4 v[6:7], off
	v_lshl_add_u64 v[6:7], s[8:9], 0, v[162:163]
	s_add_i32 m0, s10, 0x2000
	s_nop 0
	global_load_lds_dwordx4 v[6:7], off
	v_lshl_add_u64 v[6:7], v[222:223], 0, s[92:93]
	s_mov_b32 m0, s67
	s_nop 0
	global_load_lds_dwordx4 v[6:7], off
	v_lshl_add_u64 v[6:7], v[224:225], 0, s[92:93]
	s_mov_b32 m0, s81
	s_nop 0
	global_load_lds_dwordx4 v[6:7], off
	s_waitcnt vmcnt(8)
	s_waitcnt lgkmcnt(0)
	s_barrier
	v_mfma_f32_16x16x32_bf16 v[72:75], v[52:55], v[176:179], v[72:75]
	v_mfma_f32_16x16x32_bf16 v[72:75], v[56:59], v[180:183], v[72:75]
	v_mfma_f32_16x16x32_bf16 v[64:67], v[76:79], v[176:179], v[64:67]
	v_mfma_f32_16x16x32_bf16 v[64:67], v[80:83], v[180:183], v[64:67]
	v_mfma_f32_16x16x32_bf16 v[60:63], v[76:79], v[190:193], v[60:63]
	v_mfma_f32_16x16x32_bf16 v[60:63], v[80:83], v[194:197], v[60:63]
	v_mfma_f32_16x16x32_bf16 v[68:71], v[52:55], v[190:193], v[68:71]
	v_mfma_f32_16x16x32_bf16 v[68:71], v[56:59], v[194:197], v[68:71]
	v_mfma_f32_16x16x32_bf16 v[48:51], v[52:55], v[198:201], v[48:51]
	v_mfma_f32_16x16x32_bf16 v[48:51], v[56:59], v[210:213], v[48:51]
	v_mfma_f32_16x16x32_bf16 v[44:47], v[76:79], v[198:201], v[44:47]
	v_mfma_f32_16x16x32_bf16 v[44:47], v[80:83], v[210:213], v[44:47]
	v_mfma_f32_16x16x32_bf16 v[36:39], v[76:79], v[214:217], v[36:39]
	v_mfma_f32_16x16x32_bf16 v[36:39], v[80:83], v[218:221], v[36:39]
	v_mfma_f32_16x16x32_bf16 v[40:43], v[52:55], v[214:217], v[40:43]
	v_mfma_f32_16x16x32_bf16 v[40:43], v[56:59], v[218:221], v[40:43]
	v_mfma_f32_16x16x32_bf16 v[32:35], v[116:119], v[176:179], v[32:35]
	v_mfma_f32_16x16x32_bf16 v[32:35], v[120:123], v[180:183], v[32:35]
	v_mfma_f32_16x16x32_bf16 v[24:27], v[168:171], v[176:179], v[24:27]
	v_mfma_f32_16x16x32_bf16 v[24:27], v[172:175], v[180:183], v[24:27]
	v_mfma_f32_16x16x32_bf16 v[20:23], v[168:171], v[190:193], v[20:23]
	v_mfma_f32_16x16x32_bf16 v[20:23], v[172:175], v[194:197], v[20:23]
	v_mfma_f32_16x16x32_bf16 v[28:31], v[116:119], v[190:193], v[28:31]
	v_mfma_f32_16x16x32_bf16 v[28:31], v[120:123], v[194:197], v[28:31]
	v_mfma_f32_16x16x32_bf16 v[16:19], v[116:119], v[198:201], v[16:19]
	v_mfma_f32_16x16x32_bf16 v[16:19], v[120:123], v[210:213], v[16:19]
	v_mfma_f32_16x16x32_bf16 v[12:15], v[168:171], v[198:201], v[12:15]
	v_mfma_f32_16x16x32_bf16 v[12:15], v[172:175], v[210:213], v[12:15]
	v_mfma_f32_16x16x32_bf16 v[2:5], v[168:171], v[214:217], v[2:5]
	v_mfma_f32_16x16x32_bf16 v[6:9], v[116:119], v[214:217], v[8:11]
	v_mfma_f32_16x16x32_bf16 v[8:11], v[120:123], v[218:221], v[6:9]
	v_mfma_f32_16x16x32_bf16 v[4:7], v[172:175], v[218:221], v[2:5]
	s_barrier
	s_add_i32 s4, s4, 2
	s_add_u32 s97, s97, 0x100
	s_addc_u32 s96, s96, 0
	s_cmp_gt_u32 s4, 29
	s_mov_b64 s[8:9], s[68:69]
	s_cbranch_scc0 .LBB0_327
	s_branch .Lpeelx327
; #define PG8_STAGE(bufoff, gbase, voff) do { _Pragma("unroll") for (int _i = 0; _i < 2; ++_i) \
;         __builtin_amdgcn_global_load_lds((const unsigned*)((const char*)(gbase) + (voff)[_i]), (PG8_LAS unsigned*)(lds + (bufoff) + ldsw + _i * 8192), 16, 0, 0); } while (0)
; #define PG8_LDA(dst, b, h) do { _Pragma("unroll") for (int m = 0; m < 4; ++m) _Pragma("unroll") for (int k = 0; k < 2; ++k) dst[m][k] = *(const PG8_LAS bf16x8*)(lds + PG8_SA(b, h) + aoff + m * 2048 + k * 1024); } while (0)
; #define PG8_LDB(dst, b, h) do { _Pragma("unroll") for (int n = 0; n < 2; ++n) _Pragma("unroll") for (int k = 0; k < 2; ++k) dst[n][k] = *(const PG8_LAS bf16x8*)(lds + PG8_SB(b, h) + boff + n * 2048 + k * 1024); } while (0)
; #define PG8_MMA(ai, bj, At, Bt) do { __builtin_amdgcn_s_setprio(1); _Pragma("unroll") for (int m = 0; m < 4; ++m) _Pragma("unroll") for (int n = 0; n < 2; ++n) _Pragma("unroll") for (int k = 0; k < 2; ++k) \
;         acc[ai][bj][m][n] = mma16<Epi::I8>(Bt[n][k], At[m][k], acc[ai][bj][m][n]); __builtin_amdgcn_s_setprio(0); } while (0)
; #define PG8_WAIT_V(n) asm volatile("s_waitcnt vmcnt(" #n ")" ::: "memory")
; #define PG8_WAIT_L(n) asm volatile("s_waitcnt lgkmcnt(" #n ")" ::: "memory")
; #define PG8_BAR __builtin_amdgcn_s_barrier()
; template <class Epi, class Sched, bool ALIGN_EPI = false, bool SP2 = false>
; __device__ __forceinline__ void gemm_phase(PG8_LAS unsigned char* lds, const Gemm g, const Sched& S, const Epi& E) {
;     ...
;             const bool last = (t == nt - 2);
;             const char* a1 = cA + (size_t)(t + 1) * kstep;
;             const char* a2 = last ? nA : cA + (size_t)(t + 2) * kstep; const char* b2 = last ? nB : cB + (size_t)(t + 2) * kstep;
;             const char* a3 = a2 + kstep; const char* b3 = b2 + kstep;
;             if (last && has_next) S.a_ready(nxt);
;             if constexpr (SP2) {
;             PG8_LDB(B0, 0, 0); PG8_LDB(B1, 0, 1); PG8_SCHED; PG8_LDA(At, 0, 0); PG8_STAGE(PG8_SA(1, 1), a1 + hstep, voffA);
;             PG8_WAIT_V(8); PG8_WAIT_L(0); PG8_BAR; PG8_MMA(0, 0, At, B0); PG8_MMA(0, 1, At, B1); PG8_BAR; PG8_SCHED;
;             PG8_LDA(At, 0, 1); PG8_STAGE(PG8_SB(0, 0), b2, voffB); PG8_STAGE(PG8_SB(0, 1), b2 + hstep, voffB); PG8_STAGE(PG8_SA(0, 0), a2, voffA);
;             PG8_WAIT_V(8); PG8_WAIT_L(0); PG8_BAR; PG8_MMA(1, 0, At, B0); PG8_MMA(1, 1, At, B1); PG8_BAR; PG8_SCHED;
.LBB0_327:
	s_add_u32 s68, s8, 0x100
	s_addc_u32 s69, s9, 0
	s_add_i32 s84, 0, 0x10000
	s_cmp_eq_u32 s4, 28
	s_cselect_b32 vcc_hi, s1, s69
	s_cselect_b32 vcc_lo, s5, s68
	v_add_u32_e32 v0, s84, v188
	s_cselect_b32 s71, s7, s96
	s_cselect_b32 s70, s85, s97
	s_add_i32 s10, 0, 0x14000
	ds_read_b128 v[52:55], v0
	ds_read_b128 v[56:59], v0 offset:1024
	ds_read_b128 v[76:79], v0 offset:2048
	ds_read_b128 v[80:83], v0 offset:3072
	v_add_u32_e32 v0, s10, v188
	ds_read_b128 v[116:119], v0
	ds_read_b128 v[120:123], v0 offset:1024
	ds_read_b128 v[168:171], v0 offset:2048
	ds_read_b128 v[172:175], v0 offset:3072
	v_lshl_add_u64 v[2:3], s[8:9], 0, v[164:165]
	s_add_i32 m0, s58, 0xc000
	ds_read_b128 v[176:179], v189
	ds_read_b128 v[180:183], v189 offset:1024
	ds_read_b128 v[190:193], v189 offset:2048
	ds_read_b128 v[194:197], v189 offset:3072
	ds_read_b128 v[198:201], v189 offset:4096
	ds_read_b128 v[210:213], v189 offset:5120
	ds_read_b128 v[214:217], v189 offset:6144
	ds_read_b128 v[218:221], v189 offset:7168
	global_load_lds_dwordx4 v[2:3], off
	v_lshl_add_u64 v[2:3], s[8:9], 0, v[166:167]
	s_add_i32 m0, s58, 0xe000
	s_nop 0
	global_load_lds_dwordx4 v[2:3], off
	s_waitcnt vmcnt(8)
	s_waitcnt lgkmcnt(0)
	s_barrier
	v_mfma_f32_16x16x32_bf16 v[152:155], v[52:55], v[176:179], v[152:155]
	v_mfma_f32_16x16x32_bf16 v[152:155], v[56:59], v[180:183], v[152:155]
	v_mfma_f32_16x16x32_bf16 v[144:147], v[76:79], v[176:179], v[144:147]
	v_mfma_f32_16x16x32_bf16 v[144:147], v[80:83], v[180:183], v[144:147]
	v_mfma_f32_16x16x32_bf16 v[140:143], v[76:79], v[190:193], v[140:143]
	v_mfma_f32_16x16x32_bf16 v[140:143], v[80:83], v[194:197], v[140:143]
	v_mfma_f32_16x16x32_bf16 v[148:151], v[52:55], v[190:193], v[148:151]
	v_mfma_f32_16x16x32_bf16 v[148:151], v[56:59], v[194:197], v[148:151]
	v_mfma_f32_16x16x32_bf16 v[136:139], v[52:55], v[198:201], v[136:139]
	v_mfma_f32_16x16x32_bf16 v[136:139], v[56:59], v[210:213], v[136:139]
	v_mfma_f32_16x16x32_bf16 v[132:135], v[76:79], v[198:201], v[132:135]
	v_mfma_f32_16x16x32_bf16 v[132:135], v[80:83], v[210:213], v[132:135]
	v_mfma_f32_16x16x32_bf16 v[124:127], v[76:79], v[214:217], v[124:127]
	v_mfma_f32_16x16x32_bf16 v[124:127], v[80:83], v[218:221], v[124:127]
	v_mfma_f32_16x16x32_bf16 v[128:131], v[52:55], v[214:217], v[128:131]
	v_mfma_f32_16x16x32_bf16 v[128:131], v[56:59], v[218:221], v[128:131]
	v_mfma_f32_16x16x32_bf16 v[112:115], v[116:119], v[176:179], v[112:115]
	v_mfma_f32_16x16x32_bf16 v[112:115], v[120:123], v[180:183], v[112:115]
	v_mfma_f32_16x16x32_bf16 v[104:107], v[168:171], v[176:179], v[104:107]
	v_mfma_f32_16x16x32_bf16 v[104:107], v[172:175], v[180:183], v[104:107]
	v_mfma_f32_16x16x32_bf16 v[100:103], v[168:171], v[190:193], v[100:103]
	v_mfma_f32_16x16x32_bf16 v[100:103], v[172:175], v[194:197], v[100:103]
	v_mfma_f32_16x16x32_bf16 v[108:111], v[116:119], v[190:193], v[108:111]
	v_mfma_f32_16x16x32_bf16 v[108:111], v[120:123], v[194:197], v[108:111]
	v_mfma_f32_16x16x32_bf16 v[96:99], v[116:119], v[198:201], v[96:99]
	v_mfma_f32_16x16x32_bf16 v[96:99], v[120:123], v[210:213], v[96:99]
	v_mfma_f32_16x16x32_bf16 v[92:95], v[168:171], v[198:201], v[92:95]
	v_mfma_f32_16x16x32_bf16 v[92:95], v[172:175], v[210:213], v[92:95]
	v_mfma_f32_16x16x32_bf16 v[84:87], v[168:171], v[214:217], v[84:87]
	v_mfma_f32_16x16x32_bf16 v[84:87], v[172:175], v[218:221], v[84:87]
	v_mfma_f32_16x16x32_bf16 v[88:91], v[116:119], v[214:217], v[88:91]
	v_mfma_f32_16x16x32_bf16 v[88:91], v[120:123], v[218:221], v[88:91]
	s_barrier
	s_add_i32 s8, s84, s80
	v_lshl_add_u64 v[184:185], s[70:71], 0, v[158:159]
	s_mov_b32 m0, s8
	ds_read_b128 v[176:179], v189 offset:16384
	ds_read_b128 v[180:183], v189 offset:17408
	ds_read_b128 v[190:193], v189 offset:18432
	ds_read_b128 v[194:197], v189 offset:19456
	ds_read_b128 v[198:201], v189 offset:20480
	ds_read_b128 v[210:213], v189 offset:21504
	ds_read_b128 v[214:217], v189 offset:22528
	ds_read_b128 v[218:221], v189 offset:23552
	global_load_lds_dwordx4 v[184:185], off
	s_add_i32 m0, s8, 0x2000
	s_add_u32 s8, s70, 0x80000
	v_lshl_add_u64 v[206:207], s[70:71], 0, v[162:163]
	s_addc_u32 s9, s71, 0
	s_add_i32 s10, s10, s80
	global_load_lds_dwordx4 v[206:207], off
	v_lshl_add_u64 v[2:3], s[8:9], 0, v[158:159]
	s_mov_b32 m0, s10
	v_lshl_add_u64 v[222:223], vcc, 0, v[156:157]
	global_load_lds_dwordx4 v[2:3], off
	v_lshl_add_u64 v[2:3], s[8:9], 0, v[162:163]
	s_add_i32 m0, s10, 0x2000
	v_lshl_add_u64 v[224:225], vcc, 0, v[160:161]
	global_load_lds_dwordx4 v[2:3], off
	s_mov_b32 m0, s58
	s_nop 0
	global_load_lds_dwordx4 v[222:223], off
	s_mov_b32 m0, s12
	s_nop 0
	global_load_lds_dwordx4 v[224:225], off
	s_waitcnt vmcnt(8)
	s_waitcnt lgkmcnt(0)
	s_barrier
; #define PG8_STAGE(bufoff, gbase, voff) do { _Pragma("unroll") for (int _i = 0; _i < 2; ++_i) \
;         __builtin_amdgcn_global_load_lds((const unsigned*)((const char*)(gbase) + (voff)[_i]), (PG8_LAS unsigned*)(lds + (bufoff) + ldsw + _i * 8192), 16, 0, 0); } while (0)
; #define PG8_LDA(dst, b, h) do { _Pragma("unroll") for (int m = 0; m < 4; ++m) _Pragma("unroll") for (int k = 0; k < 2; ++k) dst[m][k] = *(const PG8_LAS bf16x8*)(lds + PG8_SA(b, h) + aoff + m * 2048 + k * 1024); } while (0)
; #define PG8_LDB(dst, b, h) do { _Pragma("unroll") for (int n = 0; n < 2; ++n) _Pragma("unroll") for (int k = 0; k < 2; ++k) dst[n][k] = *(const PG8_LAS bf16x8*)(lds + PG8_SB(b, h) + boff + n * 2048 + k * 1024); } while (0)
; #define PG8_MMA(ai, bj, At, Bt) do { __builtin_amdgcn_s_setprio(1); _Pragma("unroll") for (int m = 0; m < 4; ++m) _Pragma("unroll") for (int n = 0; n < 2; ++n) _Pragma("unroll") for (int k = 0; k < 2; ++k) \
;         acc[ai][bj][m][n] = mma16<Epi::I8>(Bt[n][k], At[m][k], acc[ai][bj][m][n]); __builtin_amdgcn_s_setprio(0); } while (0)
; #define PG8_WAIT_V(n) asm volatile("s_waitcnt vmcnt(" #n ")" ::: "memory")
; #define PG8_WAIT_L(n) asm volatile("s_waitcnt lgkmcnt(" #n ")" ::: "memory")
; #define PG8_BAR __builtin_amdgcn_s_barrier()
; #define PG8_SCHED __builtin_amdgcn_sched_barrier(0)
; template <class Epi, class Sched, bool ALIGN_EPI = false, bool SP2 = false>
; __device__ __forceinline__ void gemm_phase(PG8_LAS unsigned char* lds, const Gemm g, const Sched& S, const Epi& E) {
;     ...
;             PG8_WAIT_V(8); PG8_WAIT_L(0); PG8_BAR; PG8_MMA(1, 0, At, B0); PG8_MMA(1, 1, At, B1); PG8_BAR; PG8_SCHED;
;             PG8_LDB(B0, 1, 0); PG8_LDB(B1, 1, 1); PG8_SCHED; PG8_LDA(At, 1, 0); PG8_STAGE(PG8_SA(0, 1), a2 + hstep, voffA);
;             PG8_WAIT_V(8); PG8_WAIT_L(0); PG8_BAR; PG8_MMA(0, 0, At, B0); PG8_MMA(0, 1, At, B1); PG8_BAR; PG8_SCHED;
	v_mfma_f32_16x16x32_bf16 v[72:75], v[52:55], v[176:179], v[72:75]
	v_mfma_f32_16x16x32_bf16 v[72:75], v[56:59], v[180:183], v[72:75]
	v_mfma_f32_16x16x32_bf16 v[64:67], v[76:79], v[176:179], v[64:67]
	v_mfma_f32_16x16x32_bf16 v[64:67], v[80:83], v[180:183], v[64:67]
	v_mfma_f32_16x16x32_bf16 v[60:63], v[76:79], v[190:193], v[60:63]
	v_mfma_f32_16x16x32_bf16 v[60:63], v[80:83], v[194:197], v[60:63]
	v_mfma_f32_16x16x32_bf16 v[68:71], v[52:55], v[190:193], v[68:71]
	v_mfma_f32_16x16x32_bf16 v[68:71], v[56:59], v[194:197], v[68:71]
	v_mfma_f32_16x16x32_bf16 v[48:51], v[52:55], v[198:201], v[48:51]
	v_mfma_f32_16x16x32_bf16 v[48:51], v[56:59], v[210:213], v[48:51]
	v_mfma_f32_16x16x32_bf16 v[44:47], v[76:79], v[198:201], v[44:47]
	v_mfma_f32_16x16x32_bf16 v[44:47], v[80:83], v[210:213], v[44:47]
	v_mfma_f32_16x16x32_bf16 v[36:39], v[76:79], v[214:217], v[36:39]
	v_mfma_f32_16x16x32_bf16 v[36:39], v[80:83], v[218:221], v[36:39]
	v_mfma_f32_16x16x32_bf16 v[40:43], v[52:55], v[214:217], v[40:43]
	v_mfma_f32_16x16x32_bf16 v[40:43], v[56:59], v[218:221], v[40:43]
	v_mfma_f32_16x16x32_bf16 v[32:35], v[116:119], v[176:179], v[32:35]
	v_mfma_f32_16x16x32_bf16 v[32:35], v[120:123], v[180:183], v[32:35]
	v_mfma_f32_16x16x32_bf16 v[24:27], v[168:171], v[176:179], v[24:27]
	v_mfma_f32_16x16x32_bf16 v[24:27], v[172:175], v[180:183], v[24:27]
	v_mfma_f32_16x16x32_bf16 v[20:23], v[168:171], v[190:193], v[20:23]
	v_mfma_f32_16x16x32_bf16 v[20:23], v[172:175], v[194:197], v[20:23]
	v_mfma_f32_16x16x32_bf16 v[28:31], v[116:119], v[190:193], v[28:31]
	v_mfma_f32_16x16x32_bf16 v[28:31], v[120:123], v[194:197], v[28:31]
	v_mfma_f32_16x16x32_bf16 v[16:19], v[116:119], v[198:201], v[16:19]
	v_mfma_f32_16x16x32_bf16 v[16:19], v[120:123], v[210:213], v[16:19]
	v_mfma_f32_16x16x32_bf16 v[12:15], v[168:171], v[198:201], v[12:15]
	v_mfma_f32_16x16x32_bf16 v[12:15], v[172:175], v[210:213], v[12:15]
	v_mfma_f32_16x16x32_bf16 v[2:5], v[168:171], v[214:217], v[4:7]
	v_mfma_f32_16x16x32_bf16 v[2:5], v[172:175], v[218:221], v[2:5]
	v_mfma_f32_16x16x32_bf16 v[8:11], v[116:119], v[214:217], v[8:11]
	v_mfma_f32_16x16x32_bf16 v[8:11], v[120:123], v[218:221], v[8:11]
	s_barrier
	s_add_i32 s10, 0, 0x18000
	v_add_u32_e32 v0, s10, v188
	s_add_i32 s11, 0, 0x1c000
	ds_read_b128 v[52:55], v0
	ds_read_b128 v[56:59], v0 offset:1024
	ds_read_b128 v[76:79], v0 offset:2048
	ds_read_b128 v[80:83], v0 offset:3072
	v_add_u32_e32 v0, s11, v188
	ds_read_b128 v[116:119], v0
	ds_read_b128 v[120:123], v0 offset:1024
	ds_read_b128 v[168:171], v0 offset:2048
	ds_read_b128 v[172:175], v0 offset:3072
	s_add_u32 s8, vcc_lo, 0x80000
	s_addc_u32 s9, vcc_hi, 0
	s_mov_b32 m0, s13
	v_lshl_add_u64 v[6:7], s[8:9], 0, v[156:157]
	ds_read_b128 v[176:179], v189 offset:32768
	ds_read_b128 v[180:183], v189 offset:33792
	ds_read_b128 v[190:193], v189 offset:34816
	ds_read_b128 v[194:197], v189 offset:35840
	ds_read_b128 v[198:201], v189 offset:36864
	ds_read_b128 v[210:213], v189 offset:37888
	ds_read_b128 v[214:217], v189 offset:38912
	ds_read_b128 v[218:221], v189 offset:39936
	global_load_lds_dwordx4 v[6:7], off
	v_lshl_add_u64 v[6:7], s[8:9], 0, v[160:161]
	s_mov_b32 m0, s66
	s_nop 0
	global_load_lds_dwordx4 v[6:7], off
	s_waitcnt vmcnt(8)
	s_waitcnt lgkmcnt(0)
	s_barrier
	v_mfma_f32_16x16x32_bf16 v[152:155], v[52:55], v[176:179], v[152:155]
	v_mfma_f32_16x16x32_bf16 v[152:155], v[56:59], v[180:183], v[152:155]
	v_mfma_f32_16x16x32_bf16 v[144:147], v[76:79], v[176:179], v[144:147]
	v_mfma_f32_16x16x32_bf16 v[144:147], v[80:83], v[180:183], v[144:147]
	v_mfma_f32_16x16x32_bf16 v[140:143], v[76:79], v[190:193], v[140:143]
	v_mfma_f32_16x16x32_bf16 v[140:143], v[80:83], v[194:197], v[140:143]
	v_mfma_f32_16x16x32_bf16 v[148:151], v[52:55], v[190:193], v[148:151]
	v_mfma_f32_16x16x32_bf16 v[148:151], v[56:59], v[194:197], v[148:151]
	v_mfma_f32_16x16x32_bf16 v[136:139], v[52:55], v[198:201], v[136:139]
	v_mfma_f32_16x16x32_bf16 v[136:139], v[56:59], v[210:213], v[136:139]
	v_mfma_f32_16x16x32_bf16 v[132:135], v[76:79], v[198:201], v[132:135]
	v_mfma_f32_16x16x32_bf16 v[132:135], v[80:83], v[210:213], v[132:135]
	v_mfma_f32_16x16x32_bf16 v[124:127], v[76:79], v[214:217], v[124:127]
	v_mfma_f32_16x16x32_bf16 v[124:127], v[80:83], v[218:221], v[124:127]
	v_mfma_f32_16x16x32_bf16 v[128:131], v[52:55], v[214:217], v[128:131]
	v_mfma_f32_16x16x32_bf16 v[128:131], v[56:59], v[218:221], v[128:131]
	v_mfma_f32_16x16x32_bf16 v[112:115], v[116:119], v[176:179], v[112:115]
	v_mfma_f32_16x16x32_bf16 v[112:115], v[120:123], v[180:183], v[112:115]
	v_mfma_f32_16x16x32_bf16 v[104:107], v[168:171], v[176:179], v[104:107]
	v_mfma_f32_16x16x32_bf16 v[104:107], v[172:175], v[180:183], v[104:107]
	v_mfma_f32_16x16x32_bf16 v[100:103], v[168:171], v[190:193], v[100:103]
	v_mfma_f32_16x16x32_bf16 v[100:103], v[172:175], v[194:197], v[100:103]
	v_mfma_f32_16x16x32_bf16 v[108:111], v[116:119], v[190:193], v[108:111]
	v_mfma_f32_16x16x32_bf16 v[108:111], v[120:123], v[194:197], v[108:111]
	v_mfma_f32_16x16x32_bf16 v[96:99], v[116:119], v[198:201], v[96:99]
	v_mfma_f32_16x16x32_bf16 v[96:99], v[120:123], v[210:213], v[96:99]
	v_mfma_f32_16x16x32_bf16 v[92:95], v[168:171], v[198:201], v[92:95]
	v_mfma_f32_16x16x32_bf16 v[92:95], v[172:175], v[210:213], v[92:95]
	v_mfma_f32_16x16x32_bf16 v[84:87], v[168:171], v[214:217], v[84:87]
	v_mfma_f32_16x16x32_bf16 v[84:87], v[172:175], v[218:221], v[84:87]
	v_mfma_f32_16x16x32_bf16 v[88:91], v[116:119], v[214:217], v[88:91]
	v_mfma_f32_16x16x32_bf16 v[88:91], v[120:123], v[218:221], v[88:91]
	s_barrier
; #define PG8_STAGE(bufoff, gbase, voff) do { _Pragma("unroll") for (int _i = 0; _i < 2; ++_i) \
;         __builtin_amdgcn_global_load_lds((const unsigned*)((const char*)(gbase) + (voff)[_i]), (PG8_LAS unsigned*)(lds + (bufoff) + ldsw + _i * 8192), 16, 0, 0); } while (0)
; #define PG8_LDA(dst, b, h) do { _Pragma("unroll") for (int m = 0; m < 4; ++m) _Pragma("unroll") for (int k = 0; k < 2; ++k) dst[m][k] = *(const PG8_LAS bf16x8*)(lds + PG8_SA(b, h) + aoff + m * 2048 + k * 1024); } while (0)
; #define PG8_MMA(ai, bj, At, Bt) do { __builtin_amdgcn_s_setprio(1); _Pragma("unroll") for (int m = 0; m < 4; ++m) _Pragma("unroll") for (int n = 0; n < 2; ++n) _Pragma("unroll") for (int k = 0; k < 2; ++k) \
;         acc[ai][bj][m][n] = mma16<Epi::I8>(Bt[n][k], At[m][k], acc[ai][bj][m][n]); __builtin_amdgcn_s_setprio(0); } while (0)
; #define PG8_WAIT_V(n) asm volatile("s_waitcnt vmcnt(" #n ")" ::: "memory")
; #define PG8_WAIT_L(n) asm volatile("s_waitcnt lgkmcnt(" #n ")" ::: "memory")
; #define PG8_BAR __builtin_amdgcn_s_barrier()
; #define PG8_SCHED __builtin_amdgcn_sched_barrier(0)
; template <class Epi, class Sched, bool ALIGN_EPI = false, bool SP2 = false>
; __device__ __forceinline__ void gemm_phase(PG8_LAS unsigned char* lds, const Gemm g, const Sched& S, const Epi& E) {
;     ...
;             PG8_LDA(At, 1, 1); PG8_STAGE(PG8_SB(1, 0), b3, voffB); PG8_STAGE(PG8_SB(1, 1), b3 + hstep, voffB); PG8_STAGE(PG8_SA(1, 0), a3, voffA);
;             PG8_WAIT_V(8); PG8_WAIT_L(0); PG8_BAR; PG8_MMA(1, 0, At, B0); PG8_MMA(1, 1, At, B1); PG8_BAR; PG8_SCHED;
	s_add_i32 s8, s10, s80
	v_lshl_add_u64 v[6:7], v[184:185], 0, s[92:93]
	s_mov_b32 m0, s8
	ds_read_b128 v[176:179], v189 offset:49152
	ds_read_b128 v[180:183], v189 offset:50176
	ds_read_b128 v[190:193], v189 offset:51200
	ds_read_b128 v[194:197], v189 offset:52224
	ds_read_b128 v[198:201], v189 offset:53248
	ds_read_b128 v[210:213], v189 offset:54272
	ds_read_b128 v[214:217], v189 offset:55296
	ds_read_b128 v[218:221], v189 offset:56320
	global_load_lds_dwordx4 v[6:7], off
	s_add_i32 m0, s8, 0x2000
	s_add_u32 s8, s70, 0x80080
	v_lshl_add_u64 v[6:7], v[206:207], 0, s[92:93]
	s_addc_u32 s9, s71, 0
	s_add_i32 s10, s11, s80
	global_load_lds_dwordx4 v[6:7], off
	v_lshl_add_u64 v[6:7], s[8:9], 0, v[158:159]
	s_mov_b32 m0, s10
	s_nop 0
	global_load_lds_dwordx4 v[6:7], off
	v_lshl_add_u64 v[6:7], s[8:9], 0, v[162:163]
	s_add_i32 m0, s10, 0x2000
	s_nop 0
	global_load_lds_dwordx4 v[6:7], off
	v_lshl_add_u64 v[6:7], v[222:223], 0, s[92:93]
	s_mov_b32 m0, s67
	s_nop 0
	global_load_lds_dwordx4 v[6:7], off
	v_lshl_add_u64 v[6:7], v[224:225], 0, s[92:93]
	s_mov_b32 m0, s81
	s_nop 0
	global_load_lds_dwordx4 v[6:7], off
	s_waitcnt vmcnt(8)
	s_waitcnt lgkmcnt(0)
	s_barrier
	v_mfma_f32_16x16x32_bf16 v[72:75], v[52:55], v[176:179], v[72:75]
	v_mfma_f32_16x16x32_bf16 v[72:75], v[56:59], v[180:183], v[72:75]
	v_mfma_f32_16x16x32_bf16 v[64:67], v[76:79], v[176:179], v[64:67]
	v_mfma_f32_16x16x32_bf16 v[64:67], v[80:83], v[180:183], v[64:67]
	v_mfma_f32_16x16x32_bf16 v[60:63], v[76:79], v[190:193], v[60:63]
	v_mfma_f32_16x16x32_bf16 v[60:63], v[80:83], v[194:197], v[60:63]
	v_mfma_f32_16x16x32_bf16 v[68:71], v[52:55], v[190:193], v[68:71]
	v_mfma_f32_16x16x32_bf16 v[68:71], v[56:59], v[194:197], v[68:71]
	v_mfma_f32_16x16x32_bf16 v[48:51], v[52:55], v[198:201], v[48:51]
	v_mfma_f32_16x16x32_bf16 v[48:51], v[56:59], v[210:213], v[48:51]
	v_mfma_f32_16x16x32_bf16 v[44:47], v[76:79], v[198:201], v[44:47]
	v_mfma_f32_16x16x32_bf16 v[44:47], v[80:83], v[210:213], v[44:47]
	v_mfma_f32_16x16x32_bf16 v[36:39], v[76:79], v[214:217], v[36:39]
	v_mfma_f32_16x16x32_bf16 v[36:39], v[80:83], v[218:221], v[36:39]
	v_mfma_f32_16x16x32_bf16 v[40:43], v[52:55], v[214:217], v[40:43]
	v_mfma_f32_16x16x32_bf16 v[40:43], v[56:59], v[218:221], v[40:43]
	v_mfma_f32_16x16x32_bf16 v[32:35], v[116:119], v[176:179], v[32:35]
	v_mfma_f32_16x16x32_bf16 v[32:35], v[120:123], v[180:183], v[32:35]
	v_mfma_f32_16x16x32_bf16 v[24:27], v[168:171], v[176:179], v[24:27]
	v_mfma_f32_16x16x32_bf16 v[24:27], v[172:175], v[180:183], v[24:27]
	v_mfma_f32_16x16x32_bf16 v[20:23], v[168:171], v[190:193], v[20:23]
	v_mfma_f32_16x16x32_bf16 v[20:23], v[172:175], v[194:197], v[20:23]
	v_mfma_f32_16x16x32_bf16 v[28:31], v[116:119], v[190:193], v[28:31]
	v_mfma_f32_16x16x32_bf16 v[28:31], v[120:123], v[194:197], v[28:31]
	v_mfma_f32_16x16x32_bf16 v[16:19], v[116:119], v[198:201], v[16:19]
	v_mfma_f32_16x16x32_bf16 v[16:19], v[120:123], v[210:213], v[16:19]
	v_mfma_f32_16x16x32_bf16 v[12:15], v[168:171], v[198:201], v[12:15]
	v_mfma_f32_16x16x32_bf16 v[12:15], v[172:175], v[210:213], v[12:15]
	v_mfma_f32_16x16x32_bf16 v[2:5], v[168:171], v[214:217], v[2:5]
	v_mfma_f32_16x16x32_bf16 v[6:9], v[116:119], v[214:217], v[8:11]
	v_mfma_f32_16x16x32_bf16 v[8:11], v[120:123], v[218:221], v[6:9]
	v_mfma_f32_16x16x32_bf16 v[4:7], v[172:175], v[218:221], v[2:5]
	s_barrier
	s_add_i32 s4, s4, 2
	s_add_u32 s97, s97, 0x100
	s_addc_u32 s96, s96, 0
	s_cmp_gt_u32 s4, 29
	s_mov_b64 s[8:9], s[68:69]
	s_cbranch_scc0 .LBB0_327

; #define PG8_STAGE(bufoff, gbase, voff) do { _Pragma("unroll") for (int _i = 0; _i < 2; ++_i) \
;         __builtin_amdgcn_global_load_lds((const unsigned*)((const char*)(gbase) + (voff)[_i]), (PG8_LAS unsigned*)(lds + (bufoff) + ldsw + _i * 8192), 16, 0, 0); } while (0)
; #define PG8_LDA(dst, b, h) do { _Pragma("unroll") for (int m = 0; m < 4; ++m) _Pragma("unroll") for (int k = 0; k < 2; ++k) dst[m][k] = *(const PG8_LAS bf16x8*)(lds + PG8_SA(b, h) + aoff + m * 2048 + k * 1024); } while (0)
; #define PG8_LDB(dst, b, h) do { _Pragma("unroll") for (int n = 0; n < 2; ++n) _Pragma("unroll") for (int k = 0; k < 2; ++k) dst[n][k] = *(const PG8_LAS bf16x8*)(lds + PG8_SB(b, h) + boff + n * 2048 + k * 1024); } while (0)
; #define PG8_MMA(ai, bj, At, Bt) do { __builtin_amdgcn_s_setprio(1); _Pragma("unroll") for (int m = 0; m < 4; ++m) _Pragma("unroll") for (int n = 0; n < 2; ++n) _Pragma("unroll") for (int k = 0; k < 2; ++k) \
;         acc[ai][bj][m][n] = mma16<Epi::I8>(Bt[n][k], At[m][k], acc[ai][bj][m][n]); __builtin_amdgcn_s_setprio(0); } while (0)
; #define PG8_WAIT_V(n) asm volatile("s_waitcnt vmcnt(" #n ")" ::: "memory")
; #define PG8_WAIT_L(n) asm volatile("s_waitcnt lgkmcnt(" #n ")" ::: "memory")
; #define PG8_BAR __builtin_amdgcn_s_barrier()
; #define PG8_SCHED __builtin_amdgcn_sched_barrier(0)
; template <class Epi, class Sched, bool ALIGN_EPI = false, bool SP2 = false>
; __device__ __forceinline__ void gemm_phase(PG8_LAS unsigned char* lds, const Gemm g, const Sched& S, const Epi& E) {
;     ...
;             PG8_LDB(B0, 0, 0); PG8_LDB(B1, 0, 1); PG8_SCHED; PG8_LDA(At, 0, 0); PG8_STAGE(PG8_SA(1, 1), a1 + hstep, voffA);
;             PG8_WAIT_V(8); PG8_WAIT_L(0); PG8_BAR; PG8_MMA(0, 0, At, B0); PG8_MMA(0, 1, At, B1); PG8_BAR; PG8_SCHED;
;             PG8_LDA(At, 0, 1); PG8_STAGE(PG8_SB(0, 0), b2, voffB); PG8_STAGE(PG8_SB(0, 1), b2 + hstep, voffB); PG8_STAGE(PG8_SA(0, 0), a2, voffA);
;             PG8_WAIT_V(8); PG8_WAIT_L(0); PG8_BAR; PG8_MMA(1, 0, At, B0); PG8_MMA(1, 1, At, B1); PG8_BAR; PG8_SCHED;
.Lpeel385:
	s_add_u32 s70, s8, 0x100
	s_addc_u32 s71, s9, 0
	s_add_i32 s84, 0, 0x10000
	s_cmp_eq_u32 s5, 12
	s_cselect_b32 vcc_hi, s1, s71
	s_cselect_b32 vcc_lo, s7, s70
	v_add_u32_e32 v0, s84, v214
	s_cselect_b32 s83, s69, s68
	s_cselect_b32 s82, s81, s85
	s_add_i32 s10, 0, 0x14000
	ds_read_b128 v[44:47], v0
	ds_read_b128 v[52:55], v0 offset:1024
	ds_read_b128 v[60:63], v0 offset:2048
	ds_read_b128 v[64:67], v0 offset:3072
	v_add_u32_e32 v0, s10, v214
	ds_read_b128 v[84:87], v0
	ds_read_b128 v[88:91], v0 offset:1024
	ds_read_b128 v[92:95], v0 offset:2048
	ds_read_b128 v[100:103], v0 offset:3072
	v_lshl_add_u64 v[2:3], s[8:9], 0, v[184:185]
	s_add_i32 m0, s13, 0xc000
	ds_read_b128 v[124:127], v215
	ds_read_b128 v[128:131], v215 offset:1024
	ds_read_b128 v[140:143], v215 offset:2048
	ds_read_b128 v[188:191], v215 offset:3072
	ds_read_b128 v[192:195], v215 offset:4096
	ds_read_b128 v[196:199], v215 offset:5120
	ds_read_b128 v[216:219], v215 offset:6144
	ds_read_b128 v[220:223], v215 offset:7168
	global_load_lds_dwordx4 v[2:3], off
	v_lshl_add_u64 v[2:3], s[8:9], 0, v[186:187]
	s_add_i32 m0, s13, 0xe000
	s_nop 0
	global_load_lds_dwordx4 v[2:3], off
	s_waitcnt vmcnt(8)
	s_waitcnt lgkmcnt(0)
	s_barrier
	v_mfma_i32_16x16x64_i8 v[172:175], v[44:47], v[124:127], 0
	v_mfma_i32_16x16x64_i8 v[172:175], v[52:55], v[128:131], v[172:175]
	v_mfma_i32_16x16x64_i8 v[164:167], v[64:67], v[128:131], 0
	v_mfma_i32_16x16x64_i8 v[164:167], v[60:63], v[124:127], v[164:167]
	v_mfma_i32_16x16x64_i8 v[160:163], v[60:63], v[140:143], 0
	v_mfma_i32_16x16x64_i8 v[160:163], v[64:67], v[188:191], v[160:163]
	v_mfma_i32_16x16x64_i8 v[168:171], v[52:55], v[188:191], 0
	v_mfma_i32_16x16x64_i8 v[168:171], v[44:47], v[140:143], v[168:171]
	v_mfma_i32_16x16x64_i8 v[156:159], v[44:47], v[192:195], 0
	v_mfma_i32_16x16x64_i8 v[156:159], v[52:55], v[196:199], v[156:159]
	v_mfma_i32_16x16x64_i8 v[152:155], v[64:67], v[196:199], 0
	v_mfma_i32_16x16x64_i8 v[152:155], v[60:63], v[192:195], v[152:155]
	v_mfma_i32_16x16x64_i8 v[144:147], v[60:63], v[216:219], 0
	v_mfma_i32_16x16x64_i8 v[144:147], v[64:67], v[220:223], v[144:147]
	v_mfma_i32_16x16x64_i8 v[148:151], v[52:55], v[220:223], 0
	v_mfma_i32_16x16x64_i8 v[148:151], v[44:47], v[216:219], v[148:151]
	v_mfma_i32_16x16x64_i8 v[104:107], v[84:87], v[216:219], 0
	v_mfma_i32_16x16x64_i8 v[104:107], v[88:91], v[220:223], v[104:107]
	v_mfma_i32_16x16x64_i8 v[136:139], v[88:91], v[128:131], 0
	v_mfma_i32_16x16x64_i8 v[136:139], v[84:87], v[124:127], v[136:139]
	v_mfma_i32_16x16x64_i8 v[120:123], v[92:95], v[124:127], 0
	v_mfma_i32_16x16x64_i8 v[120:123], v[100:103], v[128:131], v[120:123]
	v_mfma_i32_16x16x64_i8 v[116:119], v[100:103], v[188:191], 0
	v_mfma_i32_16x16x64_i8 v[116:119], v[92:95], v[140:143], v[116:119]
	v_mfma_i32_16x16x64_i8 v[108:111], v[92:95], v[192:195], 0
	v_mfma_i32_16x16x64_i8 v[108:111], v[100:103], v[196:199], v[108:111]
	v_mfma_i32_16x16x64_i8 v[112:115], v[88:91], v[196:199], 0
	v_mfma_i32_16x16x64_i8 v[112:115], v[84:87], v[192:195], v[112:115]
	v_mfma_i32_16x16x64_i8 v[124:127], v[84:87], v[140:143], 0
	v_mfma_i32_16x16x64_i8 v[124:127], v[88:91], v[188:191], v[124:127]
	v_mfma_i32_16x16x64_i8 v[96:99], v[92:95], v[216:219], 0
	v_mfma_i32_16x16x64_i8 v[96:99], v[100:103], v[220:223], v[96:99]
	s_barrier
	s_add_i32 s8, s84, s12
	v_lshl_add_u64 v[200:201], s[82:83], 0, v[178:179]
	s_mov_b32 m0, s8
	ds_read_b128 v[128:131], v215 offset:16384
	ds_read_b128 v[132:135], v215 offset:17408
	ds_read_b128 v[140:143], v215 offset:18432
	ds_read_b128 v[188:191], v215 offset:19456
	ds_read_b128 v[192:195], v215 offset:20480
	ds_read_b128 v[196:199], v215 offset:21504
	ds_read_b128 v[216:219], v215 offset:22528
	ds_read_b128 v[220:223], v215 offset:23552
	global_load_lds_dwordx4 v[200:201], off
	s_add_i32 m0, s8, 0x2000
	s_add_u32 s8, s82, 0x40000
	v_lshl_add_u64 v[206:207], s[82:83], 0, v[182:183]
	s_addc_u32 s9, s83, 0
	s_add_i32 s10, s10, s12
	global_load_lds_dwordx4 v[206:207], off
	v_lshl_add_u64 v[2:3], s[8:9], 0, v[178:179]
	s_mov_b32 m0, s10
	v_lshl_add_u64 v[210:211], vcc, 0, v[176:177]
	global_load_lds_dwordx4 v[2:3], off
	v_lshl_add_u64 v[2:3], s[8:9], 0, v[182:183]
	s_add_i32 m0, s10, 0x2000
	v_lshl_add_u64 v[224:225], vcc, 0, v[180:181]
	global_load_lds_dwordx4 v[2:3], off
	s_mov_b32 m0, s13
	s_nop 0
	global_load_lds_dwordx4 v[210:211], off
	s_mov_b32 m0, s66
	s_nop 0
	global_load_lds_dwordx4 v[224:225], off
	s_waitcnt vmcnt(8)
	s_waitcnt lgkmcnt(0)
	s_barrier
	v_mfma_i32_16x16x64_i8 v[80:83], v[44:47], v[128:131], 0
	v_mfma_i32_16x16x64_i8 v[80:83], v[52:55], v[132:135], v[80:83]
	v_mfma_i32_16x16x64_i8 v[72:75], v[64:67], v[132:135], 0
	v_mfma_i32_16x16x64_i8 v[72:75], v[60:63], v[128:131], v[72:75]
	v_mfma_i32_16x16x64_i8 v[68:71], v[60:63], v[140:143], 0
	v_mfma_i32_16x16x64_i8 v[68:71], v[64:67], v[188:191], v[68:71]
	v_mfma_i32_16x16x64_i8 v[76:79], v[52:55], v[188:191], 0
	v_mfma_i32_16x16x64_i8 v[76:79], v[44:47], v[140:143], v[76:79]
	v_mfma_i32_16x16x64_i8 v[56:59], v[44:47], v[192:195], 0
	v_mfma_i32_16x16x64_i8 v[56:59], v[52:55], v[196:199], v[56:59]
	v_mfma_i32_16x16x64_i8 v[48:51], v[64:67], v[196:199], 0
	v_mfma_i32_16x16x64_i8 v[48:51], v[60:63], v[192:195], v[48:51]
	v_mfma_i32_16x16x64_i8 v[36:39], v[60:63], v[216:219], 0
	v_mfma_i32_16x16x64_i8 v[36:39], v[64:67], v[220:223], v[36:39]
	v_mfma_i32_16x16x64_i8 v[40:43], v[52:55], v[220:223], 0
	v_mfma_i32_16x16x64_i8 v[40:43], v[44:47], v[216:219], v[40:43]
	v_mfma_i32_16x16x64_i8 v[2:5], v[92:95], v[216:219], 0
	v_mfma_i32_16x16x64_i8 v[2:5], v[100:103], v[220:223], v[2:5]
	v_mfma_i32_16x16x64_i8 v[24:27], v[100:103], v[132:135], 0
	v_mfma_i32_16x16x64_i8 v[24:27], v[92:95], v[128:131], v[24:27]
	v_mfma_i32_16x16x64_i8 v[32:35], v[84:87], v[128:131], 0
	v_mfma_i32_16x16x64_i8 v[32:35], v[88:91], v[132:135], v[32:35]
	v_mfma_i32_16x16x64_i8 v[28:31], v[88:91], v[188:191], 0
	v_mfma_i32_16x16x64_i8 v[28:31], v[84:87], v[140:143], v[28:31]
	v_mfma_i32_16x16x64_i8 v[20:23], v[92:95], v[140:143], 0
	v_mfma_i32_16x16x64_i8 v[20:23], v[100:103], v[188:191], v[20:23]
	v_mfma_i32_16x16x64_i8 v[12:15], v[100:103], v[196:199], 0
	v_mfma_i32_16x16x64_i8 v[12:15], v[92:95], v[192:195], v[12:15]
	v_mfma_i32_16x16x64_i8 v[16:19], v[84:87], v[192:195], 0
	v_mfma_i32_16x16x64_i8 v[16:19], v[88:91], v[196:199], v[16:19]
	v_mfma_i32_16x16x64_i8 v[8:11], v[88:91], v[220:223], 0
	v_mfma_i32_16x16x64_i8 v[8:11], v[84:87], v[216:219], v[8:11]
	s_barrier
; #define PG8_STAGE(bufoff, gbase, voff) do { _Pragma("unroll") for (int _i = 0; _i < 2; ++_i) \
;         __builtin_amdgcn_global_load_lds((const unsigned*)((const char*)(gbase) + (voff)[_i]), (PG8_LAS unsigned*)(lds + (bufoff) + ldsw + _i * 8192), 16, 0, 0); } while (0)
; #define PG8_LDA(dst, b, h) do { _Pragma("unroll") for (int m = 0; m < 4; ++m) _Pragma("unroll") for (int k = 0; k < 2; ++k) dst[m][k] = *(const PG8_LAS bf16x8*)(lds + PG8_SA(b, h) + aoff + m * 2048 + k * 1024); } while (0)
; #define PG8_LDB(dst, b, h) do { _Pragma("unroll") for (int n = 0; n < 2; ++n) _Pragma("unroll") for (int k = 0; k < 2; ++k) dst[n][k] = *(const PG8_LAS bf16x8*)(lds + PG8_SB(b, h) + boff + n * 2048 + k * 1024); } while (0)
; #define PG8_MMA(ai, bj, At, Bt) do { __builtin_amdgcn_s_setprio(1); _Pragma("unroll") for (int m = 0; m < 4; ++m) _Pragma("unroll") for (int n = 0; n < 2; ++n) _Pragma("unroll") for (int k = 0; k < 2; ++k) \
;         acc[ai][bj][m][n] = mma16<Epi::I8>(Bt[n][k], At[m][k], acc[ai][bj][m][n]); __builtin_amdgcn_s_setprio(0); } while (0)
; #define PG8_WAIT_V(n) asm volatile("s_waitcnt vmcnt(" #n ")" ::: "memory")
; #define PG8_WAIT_L(n) asm volatile("s_waitcnt lgkmcnt(" #n ")" ::: "memory")
; #define PG8_BAR __builtin_amdgcn_s_barrier()
; #define PG8_SCHED __builtin_amdgcn_sched_barrier(0)
; template <class Epi, class Sched, bool ALIGN_EPI = false, bool SP2 = false>
; __device__ __forceinline__ void gemm_phase(PG8_LAS unsigned char* lds, const Gemm g, const Sched& S, const Epi& E) {
;     ...
;             PG8_LDB(B0, 1, 0); PG8_LDB(B1, 1, 1); PG8_SCHED; PG8_LDA(At, 1, 0); PG8_STAGE(PG8_SA(0, 1), a2 + hstep, voffA);
;             PG8_WAIT_V(8); PG8_WAIT_L(0); PG8_BAR; PG8_MMA(0, 0, At, B0); PG8_MMA(0, 1, At, B1); PG8_BAR; PG8_SCHED;
;             PG8_LDA(At, 1, 1); PG8_STAGE(PG8_SB(1, 0), b3, voffB); PG8_STAGE(PG8_SB(1, 1), b3 + hstep, voffB); PG8_STAGE(PG8_SA(1, 0), a3, voffA);
;             PG8_WAIT_V(8); PG8_WAIT_L(0); PG8_BAR; PG8_MMA(1, 0, At, B0); PG8_MMA(1, 1, At, B1); PG8_BAR; PG8_SCHED;
	s_add_i32 s10, 0, 0x18000
	v_add_u32_e32 v0, s10, v214
	s_add_i32 s11, 0, 0x1c000
	ds_read_b128 v[44:47], v0
	ds_read_b128 v[52:55], v0 offset:1024
	ds_read_b128 v[60:63], v0 offset:2048
	ds_read_b128 v[64:67], v0 offset:3072
	v_add_u32_e32 v0, s11, v214
	ds_read_b128 v[84:87], v0
	ds_read_b128 v[88:91], v0 offset:1024
	ds_read_b128 v[92:95], v0 offset:2048
	ds_read_b128 v[100:103], v0 offset:3072
	s_add_u32 s8, vcc_lo, 0x40000
	s_addc_u32 s9, vcc_hi, 0
	s_mov_b32 m0, s67
	v_lshl_add_u64 v[6:7], s[8:9], 0, v[176:177]
	ds_read_b128 v[128:131], v215 offset:32768
	ds_read_b128 v[132:135], v215 offset:33792
	ds_read_b128 v[140:143], v215 offset:34816
	ds_read_b128 v[188:191], v215 offset:35840
	ds_read_b128 v[192:195], v215 offset:36864
	ds_read_b128 v[196:199], v215 offset:37888
	ds_read_b128 v[216:219], v215 offset:38912
	ds_read_b128 v[220:223], v215 offset:39936
	global_load_lds_dwordx4 v[6:7], off
	v_lshl_add_u64 v[6:7], s[8:9], 0, v[180:181]
	s_mov_b32 m0, s80
	s_nop 0
	global_load_lds_dwordx4 v[6:7], off
	s_waitcnt vmcnt(8)
	s_waitcnt lgkmcnt(0)
	s_barrier
	v_mfma_i32_16x16x64_i8 v[172:175], v[44:47], v[128:131], v[172:175]
	v_mfma_i32_16x16x64_i8 v[172:175], v[52:55], v[132:135], v[172:175]
	v_mfma_i32_16x16x64_i8 v[164:167], v[60:63], v[128:131], v[164:167]
	v_mfma_i32_16x16x64_i8 v[164:167], v[64:67], v[132:135], v[164:167]
	v_mfma_i32_16x16x64_i8 v[160:163], v[60:63], v[140:143], v[160:163]
	v_mfma_i32_16x16x64_i8 v[160:163], v[64:67], v[188:191], v[160:163]
	v_mfma_i32_16x16x64_i8 v[168:171], v[44:47], v[140:143], v[168:171]
	v_mfma_i32_16x16x64_i8 v[168:171], v[52:55], v[188:191], v[168:171]
	v_mfma_i32_16x16x64_i8 v[156:159], v[44:47], v[192:195], v[156:159]
	v_mfma_i32_16x16x64_i8 v[156:159], v[52:55], v[196:199], v[156:159]
	v_mfma_i32_16x16x64_i8 v[152:155], v[60:63], v[192:195], v[152:155]
	v_mfma_i32_16x16x64_i8 v[152:155], v[64:67], v[196:199], v[152:155]
	v_mfma_i32_16x16x64_i8 v[144:147], v[60:63], v[216:219], v[144:147]
	v_mfma_i32_16x16x64_i8 v[144:147], v[64:67], v[220:223], v[144:147]
	v_mfma_i32_16x16x64_i8 v[148:151], v[44:47], v[216:219], v[148:151]
	v_mfma_i32_16x16x64_i8 v[148:151], v[52:55], v[220:223], v[148:151]
	v_mfma_i32_16x16x64_i8 v[136:139], v[84:87], v[128:131], v[136:139]
	v_mfma_i32_16x16x64_i8 v[136:139], v[88:91], v[132:135], v[136:139]
	v_mfma_i32_16x16x64_i8 v[120:123], v[92:95], v[128:131], v[120:123]
	v_mfma_i32_16x16x64_i8 v[120:123], v[100:103], v[132:135], v[120:123]
	v_mfma_i32_16x16x64_i8 v[116:119], v[92:95], v[140:143], v[116:119]
	v_mfma_i32_16x16x64_i8 v[116:119], v[100:103], v[188:191], v[116:119]
	v_mfma_i32_16x16x64_i8 v[124:127], v[84:87], v[140:143], v[124:127]
	v_mfma_i32_16x16x64_i8 v[132:135], v[88:91], v[188:191], v[124:127]
	v_mfma_i32_16x16x64_i8 v[112:115], v[84:87], v[192:195], v[112:115]
	v_mfma_i32_16x16x64_i8 v[112:115], v[88:91], v[196:199], v[112:115]
	v_mfma_i32_16x16x64_i8 v[108:111], v[92:95], v[192:195], v[108:111]
	v_mfma_i32_16x16x64_i8 v[108:111], v[100:103], v[196:199], v[108:111]
	v_mfma_i32_16x16x64_i8 v[96:99], v[92:95], v[216:219], v[96:99]
	v_mfma_i32_16x16x64_i8 v[96:99], v[100:103], v[220:223], v[96:99]
	v_mfma_i32_16x16x64_i8 v[104:107], v[84:87], v[216:219], v[104:107]
	v_mfma_i32_16x16x64_i8 v[104:107], v[88:91], v[220:223], v[104:107]
	s_barrier
	s_add_i32 s8, s10, s12
	v_lshl_add_u64 v[6:7], v[200:201], 0, s[92:93]
	s_mov_b32 m0, s8
	ds_read_b128 v[124:127], v215 offset:49152
	ds_read_b128 v[128:131], v215 offset:50176
	ds_read_b128 v[140:143], v215 offset:51200
	ds_read_b128 v[188:191], v215 offset:52224
	ds_read_b128 v[192:195], v215 offset:53248
	ds_read_b128 v[196:199], v215 offset:54272
	ds_read_b128 v[216:219], v215 offset:55296
	ds_read_b128 v[220:223], v215 offset:56320
	global_load_lds_dwordx4 v[6:7], off
	s_add_i32 m0, s8, 0x2000
	s_add_u32 s8, s82, 0x40080
	v_lshl_add_u64 v[6:7], v[206:207], 0, s[92:93]
	s_addc_u32 s9, s83, 0
	s_add_i32 s10, s11, s12
	global_load_lds_dwordx4 v[6:7], off
	v_lshl_add_u64 v[6:7], s[8:9], 0, v[178:179]
	s_mov_b32 m0, s10
	s_nop 0
	global_load_lds_dwordx4 v[6:7], off
	v_lshl_add_u64 v[6:7], s[8:9], 0, v[182:183]
	s_add_i32 m0, s10, 0x2000
	s_nop 0
	global_load_lds_dwordx4 v[6:7], off
	v_lshl_add_u64 v[6:7], v[210:211], 0, s[92:93]
	s_mov_b32 m0, s58
	s_nop 0
	global_load_lds_dwordx4 v[6:7], off
	v_lshl_add_u64 v[6:7], v[224:225], 0, s[92:93]
	s_mov_b32 m0, s4
	s_nop 0
	global_load_lds_dwordx4 v[6:7], off
	s_waitcnt vmcnt(8)
	s_waitcnt lgkmcnt(0)
	s_barrier
	v_mfma_i32_16x16x64_i8 v[80:83], v[44:47], v[124:127], v[80:83]
	v_mfma_i32_16x16x64_i8 v[80:83], v[52:55], v[128:131], v[80:83]
	v_mfma_i32_16x16x64_i8 v[72:75], v[60:63], v[124:127], v[72:75]
	v_mfma_i32_16x16x64_i8 v[72:75], v[64:67], v[128:131], v[72:75]
	v_mfma_i32_16x16x64_i8 v[68:71], v[60:63], v[140:143], v[68:71]
	v_mfma_i32_16x16x64_i8 v[68:71], v[64:67], v[188:191], v[68:71]
	v_mfma_i32_16x16x64_i8 v[76:79], v[44:47], v[140:143], v[76:79]
	v_mfma_i32_16x16x64_i8 v[76:79], v[52:55], v[188:191], v[76:79]
	v_mfma_i32_16x16x64_i8 v[56:59], v[44:47], v[192:195], v[56:59]
	v_mfma_i32_16x16x64_i8 v[56:59], v[52:55], v[196:199], v[56:59]
	v_mfma_i32_16x16x64_i8 v[48:51], v[60:63], v[192:195], v[48:51]
	v_mfma_i32_16x16x64_i8 v[48:51], v[64:67], v[196:199], v[48:51]
	v_mfma_i32_16x16x64_i8 v[36:39], v[60:63], v[216:219], v[36:39]
	v_mfma_i32_16x16x64_i8 v[36:39], v[64:67], v[220:223], v[36:39]
	v_mfma_i32_16x16x64_i8 v[40:43], v[44:47], v[216:219], v[40:43]
	v_mfma_i32_16x16x64_i8 v[40:43], v[52:55], v[220:223], v[40:43]
	v_mfma_i32_16x16x64_i8 v[32:35], v[84:87], v[124:127], v[32:35]
	v_mfma_i32_16x16x64_i8 v[32:35], v[88:91], v[128:131], v[32:35]
	v_mfma_i32_16x16x64_i8 v[24:27], v[92:95], v[124:127], v[24:27]
	v_mfma_i32_16x16x64_i8 v[24:27], v[100:103], v[128:131], v[24:27]
	v_mfma_i32_16x16x64_i8 v[20:23], v[92:95], v[140:143], v[20:23]
	v_mfma_i32_16x16x64_i8 v[20:23], v[100:103], v[188:191], v[20:23]
	v_mfma_i32_16x16x64_i8 v[28:31], v[84:87], v[140:143], v[28:31]
	v_mfma_i32_16x16x64_i8 v[28:31], v[88:91], v[188:191], v[28:31]
	v_mfma_i32_16x16x64_i8 v[16:19], v[84:87], v[192:195], v[16:19]
	v_mfma_i32_16x16x64_i8 v[16:19], v[88:91], v[196:199], v[16:19]
	v_mfma_i32_16x16x64_i8 v[12:15], v[92:95], v[192:195], v[12:15]
	v_mfma_i32_16x16x64_i8 v[12:15], v[100:103], v[196:199], v[12:15]
	v_mfma_i32_16x16x64_i8 v[2:5], v[92:95], v[216:219], v[2:5]
	v_mfma_i32_16x16x64_i8 v[6:9], v[84:87], v[216:219], v[8:11]
	v_mfma_i32_16x16x64_i8 v[8:11], v[88:91], v[220:223], v[6:9]
	v_mfma_i32_16x16x64_i8 v[4:7], v[100:103], v[220:223], v[2:5]
	s_barrier
	s_add_i32 s5, s5, 2
	s_add_u32 s85, s85, 0x100
	s_addc_u32 s68, s68, 0
	s_cmp_gt_u32 s5, 13
	s_mov_b64 s[8:9], s[70:71]
	s_cbranch_scc0 .LBB0_385
	s_branch .Lpeelx385
; #define PG8_STAGE(bufoff, gbase, voff) do { _Pragma("unroll") for (int _i = 0; _i < 2; ++_i) \
;         __builtin_amdgcn_global_load_lds((const unsigned*)((const char*)(gbase) + (voff)[_i]), (PG8_LAS unsigned*)(lds + (bufoff) + ldsw + _i * 8192), 16, 0, 0); } while (0)
; #define PG8_LDA(dst, b, h) do { _Pragma("unroll") for (int m = 0; m < 4; ++m) _Pragma("unroll") for (int k = 0; k < 2; ++k) dst[m][k] = *(const PG8_LAS bf16x8*)(lds + PG8_SA(b, h) + aoff + m * 2048 + k * 1024); } while (0)
; #define PG8_LDB(dst, b, h) do { _Pragma("unroll") for (int n = 0; n < 2; ++n) _Pragma("unroll") for (int k = 0; k < 2; ++k) dst[n][k] = *(const PG8_LAS bf16x8*)(lds + PG8_SB(b, h) + boff + n * 2048 + k * 1024); } while (0)
; #define PG8_MMA(ai, bj, At, Bt) do { __builtin_amdgcn_s_setprio(1); _Pragma("unroll") for (int m = 0; m < 4; ++m) _Pragma("unroll") for (int n = 0; n < 2; ++n) _Pragma("unroll") for (int k = 0; k < 2; ++k) \
;         acc[ai][bj][m][n] = mma16<Epi::I8>(Bt[n][k], At[m][k], acc[ai][bj][m][n]); __builtin_amdgcn_s_setprio(0); } while (0)
; #define PG8_WAIT_V(n) asm volatile("s_waitcnt vmcnt(" #n ")" ::: "memory")
; #define PG8_WAIT_L(n) asm volatile("s_waitcnt lgkmcnt(" #n ")" ::: "memory")
; #define PG8_BAR __builtin_amdgcn_s_barrier()
; template <class Epi, class Sched, bool ALIGN_EPI = false, bool SP2 = false>
; __device__ __forceinline__ void gemm_phase(PG8_LAS unsigned char* lds, const Gemm g, const Sched& S, const Epi& E) {
;     ...
;             const bool last = (t == nt - 2);
;             const char* a1 = cA + (size_t)(t + 1) * kstep;
;             const char* a2 = last ? nA : cA + (size_t)(t + 2) * kstep; const char* b2 = last ? nB : cB + (size_t)(t + 2) * kstep;
;             const char* a3 = a2 + kstep; const char* b3 = b2 + kstep;
;             if (last && has_next) S.a_ready(nxt);
;             if constexpr (SP2) {
;             PG8_LDB(B0, 0, 0); PG8_LDB(B1, 0, 1); PG8_SCHED; PG8_LDA(At, 0, 0); PG8_STAGE(PG8_SA(1, 1), a1 + hstep, voffA);
;             PG8_WAIT_V(8); PG8_WAIT_L(0); PG8_BAR; PG8_MMA(0, 0, At, B0); PG8_MMA(0, 1, At, B1); PG8_BAR; PG8_SCHED;
;             PG8_LDA(At, 0, 1); PG8_STAGE(PG8_SB(0, 0), b2, voffB); PG8_STAGE(PG8_SB(0, 1), b2 + hstep, voffB); PG8_STAGE(PG8_SA(0, 0), a2, voffA);
;             PG8_WAIT_V(8); PG8_WAIT_L(0); PG8_BAR; PG8_MMA(1, 0, At, B0); PG8_MMA(1, 1, At, B1); PG8_BAR; PG8_SCHED;
.LBB0_385:
	s_add_u32 s70, s8, 0x100
	s_addc_u32 s71, s9, 0
	s_add_i32 s84, 0, 0x10000
	s_cmp_eq_u32 s5, 12
	s_cselect_b32 vcc_hi, s1, s71
	s_cselect_b32 vcc_lo, s7, s70
	v_add_u32_e32 v0, s84, v214
	s_cselect_b32 s83, s69, s68
	s_cselect_b32 s82, s81, s85
	s_add_i32 s10, 0, 0x14000
	ds_read_b128 v[44:47], v0
	ds_read_b128 v[52:55], v0 offset:1024
	ds_read_b128 v[60:63], v0 offset:2048
	ds_read_b128 v[64:67], v0 offset:3072
	v_add_u32_e32 v0, s10, v214
	ds_read_b128 v[84:87], v0
	ds_read_b128 v[88:91], v0 offset:1024
	ds_read_b128 v[92:95], v0 offset:2048
	ds_read_b128 v[100:103], v0 offset:3072
	v_lshl_add_u64 v[2:3], s[8:9], 0, v[184:185]
	s_add_i32 m0, s13, 0xc000
	ds_read_b128 v[124:127], v215
	ds_read_b128 v[128:131], v215 offset:1024
	ds_read_b128 v[140:143], v215 offset:2048
	ds_read_b128 v[188:191], v215 offset:3072
	ds_read_b128 v[192:195], v215 offset:4096
	ds_read_b128 v[196:199], v215 offset:5120
	ds_read_b128 v[216:219], v215 offset:6144
	ds_read_b128 v[220:223], v215 offset:7168
	global_load_lds_dwordx4 v[2:3], off
	v_lshl_add_u64 v[2:3], s[8:9], 0, v[186:187]
	s_add_i32 m0, s13, 0xe000
	s_nop 0
	global_load_lds_dwordx4 v[2:3], off
	s_waitcnt vmcnt(8)
	s_waitcnt lgkmcnt(0)
	s_barrier
	v_mfma_i32_16x16x64_i8 v[172:175], v[44:47], v[124:127], v[172:175]
	v_mfma_i32_16x16x64_i8 v[172:175], v[52:55], v[128:131], v[172:175]
	v_mfma_i32_16x16x64_i8 v[164:167], v[60:63], v[124:127], v[164:167]
	v_mfma_i32_16x16x64_i8 v[164:167], v[64:67], v[128:131], v[164:167]
	v_mfma_i32_16x16x64_i8 v[160:163], v[60:63], v[140:143], v[160:163]
	v_mfma_i32_16x16x64_i8 v[160:163], v[64:67], v[188:191], v[160:163]
	v_mfma_i32_16x16x64_i8 v[168:171], v[44:47], v[140:143], v[168:171]
	v_mfma_i32_16x16x64_i8 v[168:171], v[52:55], v[188:191], v[168:171]
	v_mfma_i32_16x16x64_i8 v[156:159], v[44:47], v[192:195], v[156:159]
	v_mfma_i32_16x16x64_i8 v[156:159], v[52:55], v[196:199], v[156:159]
	v_mfma_i32_16x16x64_i8 v[152:155], v[60:63], v[192:195], v[152:155]
	v_mfma_i32_16x16x64_i8 v[152:155], v[64:67], v[196:199], v[152:155]
	v_mfma_i32_16x16x64_i8 v[144:147], v[60:63], v[216:219], v[144:147]
	v_mfma_i32_16x16x64_i8 v[144:147], v[64:67], v[220:223], v[144:147]
	v_mfma_i32_16x16x64_i8 v[148:151], v[44:47], v[216:219], v[148:151]
	v_mfma_i32_16x16x64_i8 v[148:151], v[52:55], v[220:223], v[148:151]
	v_mfma_i32_16x16x64_i8 v[136:139], v[84:87], v[124:127], v[136:139]
	v_mfma_i32_16x16x64_i8 v[136:139], v[88:91], v[128:131], v[136:139]
	v_mfma_i32_16x16x64_i8 v[120:123], v[92:95], v[124:127], v[120:123]
	v_mfma_i32_16x16x64_i8 v[120:123], v[100:103], v[128:131], v[120:123]
	v_mfma_i32_16x16x64_i8 v[116:119], v[92:95], v[140:143], v[116:119]
	v_mfma_i32_16x16x64_i8 v[116:119], v[100:103], v[188:191], v[116:119]
	v_mfma_i32_16x16x64_i8 v[108:111], v[92:95], v[192:195], v[108:111]
	v_mfma_i32_16x16x64_i8 v[108:111], v[100:103], v[196:199], v[108:111]
	v_mfma_i32_16x16x64_i8 v[112:115], v[84:87], v[192:195], v[112:115]
	v_mfma_i32_16x16x64_i8 v[112:115], v[88:91], v[196:199], v[112:115]
	v_mfma_i32_16x16x64_i8 v[104:107], v[84:87], v[216:219], v[104:107]
	v_mfma_i32_16x16x64_i8 v[104:107], v[88:91], v[220:223], v[104:107]
	v_mfma_i32_16x16x64_i8 v[96:99], v[92:95], v[216:219], v[96:99]
	v_mfma_i32_16x16x64_i8 v[96:99], v[100:103], v[220:223], v[96:99]
	v_mfma_i32_16x16x64_i8 v[124:127], v[84:87], v[140:143], v[132:135]
	v_mfma_i32_16x16x64_i8 v[124:127], v[88:91], v[188:191], v[124:127]
	s_barrier
	s_add_i32 s8, s84, s12
	v_lshl_add_u64 v[200:201], s[82:83], 0, v[178:179]
	s_mov_b32 m0, s8
	ds_read_b128 v[128:131], v215 offset:16384
	ds_read_b128 v[132:135], v215 offset:17408
	ds_read_b128 v[140:143], v215 offset:18432
	ds_read_b128 v[188:191], v215 offset:19456
	ds_read_b128 v[192:195], v215 offset:20480
	ds_read_b128 v[196:199], v215 offset:21504
	ds_read_b128 v[216:219], v215 offset:22528
	ds_read_b128 v[220:223], v215 offset:23552
	global_load_lds_dwordx4 v[200:201], off
	s_add_i32 m0, s8, 0x2000
	s_add_u32 s8, s82, 0x40000
	v_lshl_add_u64 v[206:207], s[82:83], 0, v[182:183]
	s_addc_u32 s9, s83, 0
	s_add_i32 s10, s10, s12
	global_load_lds_dwordx4 v[206:207], off
	v_lshl_add_u64 v[2:3], s[8:9], 0, v[178:179]
	s_mov_b32 m0, s10
	v_lshl_add_u64 v[210:211], vcc, 0, v[176:177]
	global_load_lds_dwordx4 v[2:3], off
	v_lshl_add_u64 v[2:3], s[8:9], 0, v[182:183]
	s_add_i32 m0, s10, 0x2000
	v_lshl_add_u64 v[224:225], vcc, 0, v[180:181]
	global_load_lds_dwordx4 v[2:3], off
	s_mov_b32 m0, s13
	s_nop 0
	global_load_lds_dwordx4 v[210:211], off
	s_mov_b32 m0, s66
	s_nop 0
	global_load_lds_dwordx4 v[224:225], off
	s_waitcnt vmcnt(8)
	s_waitcnt lgkmcnt(0)
	s_barrier
; #define PG8_STAGE(bufoff, gbase, voff) do { _Pragma("unroll") for (int _i = 0; _i < 2; ++_i) \
;         __builtin_amdgcn_global_load_lds((const unsigned*)((const char*)(gbase) + (voff)[_i]), (PG8_LAS unsigned*)(lds + (bufoff) + ldsw + _i * 8192), 16, 0, 0); } while (0)
; #define PG8_LDA(dst, b, h) do { _Pragma("unroll") for (int m = 0; m < 4; ++m) _Pragma("unroll") for (int k = 0; k < 2; ++k) dst[m][k] = *(const PG8_LAS bf16x8*)(lds + PG8_SA(b, h) + aoff + m * 2048 + k * 1024); } while (0)
; #define PG8_LDB(dst, b, h) do { _Pragma("unroll") for (int n = 0; n < 2; ++n) _Pragma("unroll") for (int k = 0; k < 2; ++k) dst[n][k] = *(const PG8_LAS bf16x8*)(lds + PG8_SB(b, h) + boff + n * 2048 + k * 1024); } while (0)
; #define PG8_MMA(ai, bj, At, Bt) do { __builtin_amdgcn_s_setprio(1); _Pragma("unroll") for (int m = 0; m < 4; ++m) _Pragma("unroll") for (int n = 0; n < 2; ++n) _Pragma("unroll") for (int k = 0; k < 2; ++k) \
;         acc[ai][bj][m][n] = mma16<Epi::I8>(Bt[n][k], At[m][k], acc[ai][bj][m][n]); __builtin_amdgcn_s_setprio(0); } while (0)
; #define PG8_WAIT_V(n) asm volatile("s_waitcnt vmcnt(" #n ")" ::: "memory")
; #define PG8_WAIT_L(n) asm volatile("s_waitcnt lgkmcnt(" #n ")" ::: "memory")
; #define PG8_BAR __builtin_amdgcn_s_barrier()
; #define PG8_SCHED __builtin_amdgcn_sched_barrier(0)
; template <class Epi, class Sched, bool ALIGN_EPI = false, bool SP2 = false>
; __device__ __forceinline__ void gemm_phase(PG8_LAS unsigned char* lds, const Gemm g, const Sched& S, const Epi& E) {
;     ...
;             PG8_WAIT_V(8); PG8_WAIT_L(0); PG8_BAR; PG8_MMA(1, 0, At, B0); PG8_MMA(1, 1, At, B1); PG8_BAR; PG8_SCHED;
;             PG8_LDB(B0, 1, 0); PG8_LDB(B1, 1, 1); PG8_SCHED; PG8_LDA(At, 1, 0); PG8_STAGE(PG8_SA(0, 1), a2 + hstep, voffA);
;             PG8_WAIT_V(8); PG8_WAIT_L(0); PG8_BAR; PG8_MMA(0, 0, At, B0); PG8_MMA(0, 1, At, B1); PG8_BAR; PG8_SCHED;
	v_mfma_i32_16x16x64_i8 v[80:83], v[44:47], v[128:131], v[80:83]
	v_mfma_i32_16x16x64_i8 v[80:83], v[52:55], v[132:135], v[80:83]
	v_mfma_i32_16x16x64_i8 v[72:75], v[60:63], v[128:131], v[72:75]
	v_mfma_i32_16x16x64_i8 v[72:75], v[64:67], v[132:135], v[72:75]
	v_mfma_i32_16x16x64_i8 v[68:71], v[60:63], v[140:143], v[68:71]
	v_mfma_i32_16x16x64_i8 v[68:71], v[64:67], v[188:191], v[68:71]
	v_mfma_i32_16x16x64_i8 v[76:79], v[44:47], v[140:143], v[76:79]
	v_mfma_i32_16x16x64_i8 v[76:79], v[52:55], v[188:191], v[76:79]
	v_mfma_i32_16x16x64_i8 v[56:59], v[44:47], v[192:195], v[56:59]
	v_mfma_i32_16x16x64_i8 v[56:59], v[52:55], v[196:199], v[56:59]
	v_mfma_i32_16x16x64_i8 v[48:51], v[60:63], v[192:195], v[48:51]
	v_mfma_i32_16x16x64_i8 v[48:51], v[64:67], v[196:199], v[48:51]
	v_mfma_i32_16x16x64_i8 v[36:39], v[60:63], v[216:219], v[36:39]
	v_mfma_i32_16x16x64_i8 v[36:39], v[64:67], v[220:223], v[36:39]
	v_mfma_i32_16x16x64_i8 v[40:43], v[44:47], v[216:219], v[40:43]
	v_mfma_i32_16x16x64_i8 v[40:43], v[52:55], v[220:223], v[40:43]
	v_mfma_i32_16x16x64_i8 v[32:35], v[84:87], v[128:131], v[32:35]
	v_mfma_i32_16x16x64_i8 v[32:35], v[88:91], v[132:135], v[32:35]
	v_mfma_i32_16x16x64_i8 v[24:27], v[92:95], v[128:131], v[24:27]
	v_mfma_i32_16x16x64_i8 v[24:27], v[100:103], v[132:135], v[24:27]
	v_mfma_i32_16x16x64_i8 v[20:23], v[92:95], v[140:143], v[20:23]
	v_mfma_i32_16x16x64_i8 v[20:23], v[100:103], v[188:191], v[20:23]
	v_mfma_i32_16x16x64_i8 v[28:31], v[84:87], v[140:143], v[28:31]
	v_mfma_i32_16x16x64_i8 v[28:31], v[88:91], v[188:191], v[28:31]
	v_mfma_i32_16x16x64_i8 v[16:19], v[84:87], v[192:195], v[16:19]
	v_mfma_i32_16x16x64_i8 v[16:19], v[88:91], v[196:199], v[16:19]
	v_mfma_i32_16x16x64_i8 v[12:15], v[92:95], v[192:195], v[12:15]
	v_mfma_i32_16x16x64_i8 v[12:15], v[100:103], v[196:199], v[12:15]
	v_mfma_i32_16x16x64_i8 v[2:5], v[92:95], v[216:219], v[4:7]
	v_mfma_i32_16x16x64_i8 v[2:5], v[100:103], v[220:223], v[2:5]
	v_mfma_i32_16x16x64_i8 v[8:11], v[84:87], v[216:219], v[8:11]
	v_mfma_i32_16x16x64_i8 v[8:11], v[88:91], v[220:223], v[8:11]
	s_barrier
	s_add_i32 s10, 0, 0x18000
	v_add_u32_e32 v0, s10, v214
	s_add_i32 s11, 0, 0x1c000
	ds_read_b128 v[44:47], v0
	ds_read_b128 v[52:55], v0 offset:1024
	ds_read_b128 v[60:63], v0 offset:2048
	ds_read_b128 v[64:67], v0 offset:3072
	v_add_u32_e32 v0, s11, v214
	ds_read_b128 v[84:87], v0
	ds_read_b128 v[88:91], v0 offset:1024
	ds_read_b128 v[92:95], v0 offset:2048
	ds_read_b128 v[100:103], v0 offset:3072
	s_add_u32 s8, vcc_lo, 0x40000
	s_addc_u32 s9, vcc_hi, 0
	s_mov_b32 m0, s67
	v_lshl_add_u64 v[6:7], s[8:9], 0, v[176:177]
	ds_read_b128 v[128:131], v215 offset:32768
	ds_read_b128 v[132:135], v215 offset:33792
	ds_read_b128 v[140:143], v215 offset:34816
	ds_read_b128 v[188:191], v215 offset:35840
	ds_read_b128 v[192:195], v215 offset:36864
	ds_read_b128 v[196:199], v215 offset:37888
	ds_read_b128 v[216:219], v215 offset:38912
	ds_read_b128 v[220:223], v215 offset:39936
	global_load_lds_dwordx4 v[6:7], off
	v_lshl_add_u64 v[6:7], s[8:9], 0, v[180:181]
	s_mov_b32 m0, s80
	s_nop 0
	global_load_lds_dwordx4 v[6:7], off
	s_waitcnt vmcnt(8)
	s_waitcnt lgkmcnt(0)
	s_barrier
	v_mfma_i32_16x16x64_i8 v[172:175], v[44:47], v[128:131], v[172:175]
	v_mfma_i32_16x16x64_i8 v[172:175], v[52:55], v[132:135], v[172:175]
	v_mfma_i32_16x16x64_i8 v[164:167], v[60:63], v[128:131], v[164:167]
	v_mfma_i32_16x16x64_i8 v[164:167], v[64:67], v[132:135], v[164:167]
	v_mfma_i32_16x16x64_i8 v[160:163], v[60:63], v[140:143], v[160:163]
	v_mfma_i32_16x16x64_i8 v[160:163], v[64:67], v[188:191], v[160:163]
	v_mfma_i32_16x16x64_i8 v[168:171], v[44:47], v[140:143], v[168:171]
	v_mfma_i32_16x16x64_i8 v[168:171], v[52:55], v[188:191], v[168:171]
	v_mfma_i32_16x16x64_i8 v[156:159], v[44:47], v[192:195], v[156:159]
	v_mfma_i32_16x16x64_i8 v[156:159], v[52:55], v[196:199], v[156:159]
	v_mfma_i32_16x16x64_i8 v[152:155], v[60:63], v[192:195], v[152:155]
	v_mfma_i32_16x16x64_i8 v[152:155], v[64:67], v[196:199], v[152:155]
	v_mfma_i32_16x16x64_i8 v[144:147], v[60:63], v[216:219], v[144:147]
	v_mfma_i32_16x16x64_i8 v[144:147], v[64:67], v[220:223], v[144:147]
	v_mfma_i32_16x16x64_i8 v[148:151], v[44:47], v[216:219], v[148:151]
	v_mfma_i32_16x16x64_i8 v[148:151], v[52:55], v[220:223], v[148:151]
	v_mfma_i32_16x16x64_i8 v[136:139], v[84:87], v[128:131], v[136:139]
	v_mfma_i32_16x16x64_i8 v[136:139], v[88:91], v[132:135], v[136:139]
	v_mfma_i32_16x16x64_i8 v[120:123], v[92:95], v[128:131], v[120:123]
	v_mfma_i32_16x16x64_i8 v[120:123], v[100:103], v[132:135], v[120:123]
	v_mfma_i32_16x16x64_i8 v[116:119], v[92:95], v[140:143], v[116:119]
	v_mfma_i32_16x16x64_i8 v[116:119], v[100:103], v[188:191], v[116:119]
	v_mfma_i32_16x16x64_i8 v[124:127], v[84:87], v[140:143], v[124:127]
	v_mfma_i32_16x16x64_i8 v[132:135], v[88:91], v[188:191], v[124:127]
	v_mfma_i32_16x16x64_i8 v[112:115], v[84:87], v[192:195], v[112:115]
	v_mfma_i32_16x16x64_i8 v[112:115], v[88:91], v[196:199], v[112:115]
	v_mfma_i32_16x16x64_i8 v[108:111], v[92:95], v[192:195], v[108:111]
	v_mfma_i32_16x16x64_i8 v[108:111], v[100:103], v[196:199], v[108:111]
	v_mfma_i32_16x16x64_i8 v[96:99], v[92:95], v[216:219], v[96:99]
	v_mfma_i32_16x16x64_i8 v[96:99], v[100:103], v[220:223], v[96:99]
	v_mfma_i32_16x16x64_i8 v[104:107], v[84:87], v[216:219], v[104:107]
	v_mfma_i32_16x16x64_i8 v[104:107], v[88:91], v[220:223], v[104:107]
	s_barrier
; #define PG8_STAGE(bufoff, gbase, voff) do { _Pragma("unroll") for (int _i = 0; _i < 2; ++_i) \
;         __builtin_amdgcn_global_load_lds((const unsigned*)((const char*)(gbase) + (voff)[_i]), (PG8_LAS unsigned*)(lds + (bufoff) + ldsw + _i * 8192), 16, 0, 0); } while (0)
; #define PG8_LDA(dst, b, h) do { _Pragma("unroll") for (int m = 0; m < 4; ++m) _Pragma("unroll") for (int k = 0; k < 2; ++k) dst[m][k] = *(const PG8_LAS bf16x8*)(lds + PG8_SA(b, h) + aoff + m * 2048 + k * 1024); } while (0)
; #define PG8_MMA(ai, bj, At, Bt) do { __builtin_amdgcn_s_setprio(1); _Pragma("unroll") for (int m = 0; m < 4; ++m) _Pragma("unroll") for (int n = 0; n < 2; ++n) _Pragma("unroll") for (int k = 0; k < 2; ++k) \
;         acc[ai][bj][m][n] = mma16<Epi::I8>(Bt[n][k], At[m][k], acc[ai][bj][m][n]); __builtin_amdgcn_s_setprio(0); } while (0)
; #define PG8_WAIT_V(n) asm volatile("s_waitcnt vmcnt(" #n ")" ::: "memory")
; #define PG8_WAIT_L(n) asm volatile("s_waitcnt lgkmcnt(" #n ")" ::: "memory")
; #define PG8_BAR __builtin_amdgcn_s_barrier()
; #define PG8_SCHED __builtin_amdgcn_sched_barrier(0)
; template <class Epi, class Sched, bool ALIGN_EPI = false, bool SP2 = false>
; __device__ __forceinline__ void gemm_phase(PG8_LAS unsigned char* lds, const Gemm g, const Sched& S, const Epi& E) {
;     ...
;             PG8_LDA(At, 1, 1); PG8_STAGE(PG8_SB(1, 0), b3, voffB); PG8_STAGE(PG8_SB(1, 1), b3 + hstep, voffB); PG8_STAGE(PG8_SA(1, 0), a3, voffA);
;             PG8_WAIT_V(8); PG8_WAIT_L(0); PG8_BAR; PG8_MMA(1, 0, At, B0); PG8_MMA(1, 1, At, B1); PG8_BAR; PG8_SCHED;
	s_add_i32 s8, s10, s12
	v_lshl_add_u64 v[6:7], v[200:201], 0, s[92:93]
	s_mov_b32 m0, s8
	ds_read_b128 v[124:127], v215 offset:49152
	ds_read_b128 v[128:131], v215 offset:50176
	ds_read_b128 v[140:143], v215 offset:51200
	ds_read_b128 v[188:191], v215 offset:52224
	ds_read_b128 v[192:195], v215 offset:53248
	ds_read_b128 v[196:199], v215 offset:54272
	ds_read_b128 v[216:219], v215 offset:55296
	ds_read_b128 v[220:223], v215 offset:56320
	global_load_lds_dwordx4 v[6:7], off
	s_add_i32 m0, s8, 0x2000
	s_add_u32 s8, s82, 0x40080
	v_lshl_add_u64 v[6:7], v[206:207], 0, s[92:93]
	s_addc_u32 s9, s83, 0
	s_add_i32 s10, s11, s12
	global_load_lds_dwordx4 v[6:7], off
	v_lshl_add_u64 v[6:7], s[8:9], 0, v[178:179]
	s_mov_b32 m0, s10
	s_nop 0
	global_load_lds_dwordx4 v[6:7], off
	v_lshl_add_u64 v[6:7], s[8:9], 0, v[182:183]
	s_add_i32 m0, s10, 0x2000
	s_nop 0
	global_load_lds_dwordx4 v[6:7], off
	v_lshl_add_u64 v[6:7], v[210:211], 0, s[92:93]
	s_mov_b32 m0, s58
	s_nop 0
	global_load_lds_dwordx4 v[6:7], off
	v_lshl_add_u64 v[6:7], v[224:225], 0, s[92:93]
	s_mov_b32 m0, s4
	s_nop 0
	global_load_lds_dwordx4 v[6:7], off
	s_waitcnt vmcnt(8)
	s_waitcnt lgkmcnt(0)
	s_barrier
	v_mfma_i32_16x16x64_i8 v[80:83], v[44:47], v[124:127], v[80:83]
	v_mfma_i32_16x16x64_i8 v[80:83], v[52:55], v[128:131], v[80:83]
	v_mfma_i32_16x16x64_i8 v[72:75], v[60:63], v[124:127], v[72:75]
	v_mfma_i32_16x16x64_i8 v[72:75], v[64:67], v[128:131], v[72:75]
	v_mfma_i32_16x16x64_i8 v[68:71], v[60:63], v[140:143], v[68:71]
	v_mfma_i32_16x16x64_i8 v[68:71], v[64:67], v[188:191], v[68:71]
	v_mfma_i32_16x16x64_i8 v[76:79], v[44:47], v[140:143], v[76:79]
	v_mfma_i32_16x16x64_i8 v[76:79], v[52:55], v[188:191], v[76:79]
	v_mfma_i32_16x16x64_i8 v[56:59], v[44:47], v[192:195], v[56:59]
	v_mfma_i32_16x16x64_i8 v[56:59], v[52:55], v[196:199], v[56:59]
	v_mfma_i32_16x16x64_i8 v[48:51], v[60:63], v[192:195], v[48:51]
	v_mfma_i32_16x16x64_i8 v[48:51], v[64:67], v[196:199], v[48:51]
	v_mfma_i32_16x16x64_i8 v[36:39], v[60:63], v[216:219], v[36:39]
	v_mfma_i32_16x16x64_i8 v[36:39], v[64:67], v[220:223], v[36:39]
	v_mfma_i32_16x16x64_i8 v[40:43], v[44:47], v[216:219], v[40:43]
	v_mfma_i32_16x16x64_i8 v[40:43], v[52:55], v[220:223], v[40:43]
	v_mfma_i32_16x16x64_i8 v[32:35], v[84:87], v[124:127], v[32:35]
	v_mfma_i32_16x16x64_i8 v[32:35], v[88:91], v[128:131], v[32:35]
	v_mfma_i32_16x16x64_i8 v[24:27], v[92:95], v[124:127], v[24:27]
	v_mfma_i32_16x16x64_i8 v[24:27], v[100:103], v[128:131], v[24:27]
	v_mfma_i32_16x16x64_i8 v[20:23], v[92:95], v[140:143], v[20:23]
	v_mfma_i32_16x16x64_i8 v[20:23], v[100:103], v[188:191], v[20:23]
	v_mfma_i32_16x16x64_i8 v[28:31], v[84:87], v[140:143], v[28:31]
	v_mfma_i32_16x16x64_i8 v[28:31], v[88:91], v[188:191], v[28:31]
	v_mfma_i32_16x16x64_i8 v[16:19], v[84:87], v[192:195], v[16:19]
	v_mfma_i32_16x16x64_i8 v[16:19], v[88:91], v[196:199], v[16:19]
	v_mfma_i32_16x16x64_i8 v[12:15], v[92:95], v[192:195], v[12:15]
	v_mfma_i32_16x16x64_i8 v[12:15], v[100:103], v[196:199], v[12:15]
	v_mfma_i32_16x16x64_i8 v[2:5], v[92:95], v[216:219], v[2:5]
	v_mfma_i32_16x16x64_i8 v[6:9], v[84:87], v[216:219], v[8:11]
	v_mfma_i32_16x16x64_i8 v[8:11], v[88:91], v[220:223], v[6:9]
	v_mfma_i32_16x16x64_i8 v[4:7], v[100:103], v[220:223], v[2:5]
	s_barrier
	s_add_i32 s5, s5, 2
	s_add_u32 s85, s85, 0x100
	s_addc_u32 s68, s68, 0
	s_cmp_gt_u32 s5, 13
	s_mov_b64 s[8:9], s[70:71]
	s_cbranch_scc0 .LBB0_385
